# M-phase gemm<4,1> K-loops rewritten: 3-stage 48KB LDS ring with counted vmcnt, fragment prefetch; MLA attention K/V fragment prefetch
# speedup vs baseline: 1.0208x; 1.0208x over previous
; DI int get_tid() { int t = threadIdx.x; asm volatile("" : "+v"(t)); return t; }
; DI f32x16 mfma(bf16x8 a, bf16x8 b, f32x16 c) { return __builtin_amdgcn_mfma_f32_32x32x16_bf16(a, b, c, 0, 0, 0); }
;     ...
;   const int tid = get_tid(), lane = tid & 63, wave = tid >> 6, l32 = lane & 31, hh = lane >> 5;
;   const int wf = wave >> 2, wt = wave & 3;
;   const int crow = tid >> 3, q = tid & 7;
;   const int gc = q ^ ((crow >> 1) & 7);
;   const u16* wp = W + (size_t)crow * ldw + gc * 8;
;   const u16* xp = X + (size_t)crow * ldx + gc * 8;
;   char* lw = lds + tid * 16;
;   const int xr = (l32 >> 1) & 7;
;   const int abase = (wf * NFB * 32 + l32) * DROW;
;   const int bbase = 256 * DROW + (wt * NTB * 32 + l32) * DROW;
;     ...
;   __syncthreads();
;   DMA_ISSUE(0, 0)
;   asm volatile("s_waitcnt vmcnt(0)" ::: "memory");
;   __builtin_amdgcn_s_barrier();
;   for (int kt = 0; kt < nk; ++kt) {
;     const char* cur = lds + (kt & 1) * DBUF;
;     if (kt + 1 < nk) DMA_ISSUE((kt + 1) & 1, kt + 1)
; #pragma unroll(NTB == 1 ? 2 : 4)
;     for (int s = 0; s < 4; ++s) {
;       const int ro = ((2 * s + hh) ^ xr) * 16;
;       bf16x8 bfr[NTB];
; #pragma unroll
;       for (int tb = 0; tb < NTB; ++tb) bfr[tb] = *(const bf16x8*)(cur + bbase + tb * 32 * DROW + ro);
; #pragma unroll
;       for (int fb = 0; fb < NFB; ++fb) {
;         const bf16x8 afr = *(const bf16x8*)(cur + abase + fb * 32 * DROW + ro);
; #pragma unroll
;         for (int tb = 0; tb < NTB; ++tb) acc[tb * NFB + fb] = mfma(afr, bfr[tb], acc[tb * NFB + fb]);
;       }
;     }
;     asm volatile("s_waitcnt vmcnt(0) lgkmcnt(0)" ::: "memory");
;     __builtin_amdgcn_s_barrier();
;   }
; __global__ void __launch_bounds__(512) mega(Params p) {
;     ...
;         for (int n = 0; n < 3; ++n) {
;           f32x16 acc[4]; zero4(acc);
;           const size_t ooff = (n == 0) ? R_OA : (n == 1 ? R_OB : R_OC);
;           gemm_main<4, 1>((const u16*)(ws + OFF_WBR) + ((size_t)n * 1024 + ft * 256) * 512, 512, (const u16*)(ws + ooff) + (size_t)tt * 128 * 512, 512, 8, acc, lds);
.LBB0_25:
	s_cmp_eq_u32 s8, 1
	s_mov_b32 s0, 0x19db1000
	s_cselect_b32 s33, s0, 0x1bdb1000
	s_cmp_eq_u32 s8, 0
	s_cselect_b64 s[0:1], -1, 0
	s_and_b64 s[34:35], s[0:1], exec
	s_cselect_b32 s33, 0x6db1000, s33
	s_lshl_b32 s34, s8, 10
	s_add_u32 s34, s34, s54
	s_addc_u32 s35, 0, s55
	s_lshl_b64 s[66:67], s[34:35], 10
	v_mov_b32_e32 v8, v145
	s_add_u32 s66, s36, s66
	s_addc_u32 s67, s37, s67
	v_ashrrev_i32_e32 v2, 3, v8
	v_lshrrev_b32_e32 v0, 4, v8
	v_xor_b32_e32 v0, v0, v8
	v_ashrrev_i32_e32 v3, 31, v2
	s_add_u32 s68, s9, s33
	v_lshlrev_b64 v[4:5], 10, v[2:3]
	v_lshlrev_b32_e32 v0, 4, v0
	v_lshl_add_u32 v15, v8, 4, 0
	s_addc_u32 s69, s59, 0
	v_lshl_add_u64 v[2:3], s[66:67], 0, v[4:5]
	v_and_b32_e32 v0, 0x70, v0
	v_readfirstlane_b32 s33, v15
	v_add_u32_e32 v16, 0x2000, v15
	v_lshl_add_u64 v[2:3], v[2:3], 0, v[0:1]
	v_lshl_add_u64 v[4:5], s[68:69], 0, v[4:5]
	v_lshl_add_u64 v[4:5], v[4:5], 0, v[0:1]
	s_mov_b64 s[68:69], 0x10000
	v_lshl_add_u64 v[6:7], v[2:3], 0, s[68:69]
	v_lshl_add_u64 v[12:13], v[4:5], 0, s[68:69]
	v_lshl_add_u64 v[8:9], v[6:7], 0, s[68:69]
	v_lshl_add_u64 v[10:11], v[8:9], 0, s[68:69]
	s_waitcnt vmcnt(0) lgkmcnt(0)
	s_barrier
	s_add_u32 m0, s33, 0x0
	s_nop 0
	global_load_lds_dwordx4 v[2:3], off
	s_add_u32 m0, s33, 0x2000
	s_nop 0
	global_load_lds_dwordx4 v[6:7], off
	s_add_u32 m0, s33, 0x4000
	s_nop 0
	global_load_lds_dwordx4 v[8:9], off
	s_add_u32 m0, s33, 0x6000
	s_nop 0
	global_load_lds_dwordx4 v[10:11], off
	s_add_u32 m0, s33, 0x8000
	s_nop 0
	global_load_lds_dwordx4 v[4:5], off
	s_add_u32 m0, s33, 0xa000
	s_nop 0
	global_load_lds_dwordx4 v[12:13], off
	s_add_u32 m0, s33, 0xc000
	v_lshl_add_u64 v[2:3], v[2:3], 0, s[84:85]
	global_load_lds_dwordx4 v[2:3], off
	s_add_u32 m0, s33, 0xe000
	v_lshl_add_u64 v[6:7], v[6:7], 0, s[84:85]
	global_load_lds_dwordx4 v[6:7], off
	s_add_u32 m0, s33, 0x10000
	v_lshl_add_u64 v[8:9], v[8:9], 0, s[84:85]
	global_load_lds_dwordx4 v[8:9], off
	s_add_u32 m0, s33, 0x12000
	v_lshl_add_u64 v[10:11], v[10:11], 0, s[84:85]
	global_load_lds_dwordx4 v[10:11], off
	s_add_u32 m0, s33, 0x14000
	v_lshl_add_u64 v[4:5], v[4:5], 0, s[84:85]
	global_load_lds_dwordx4 v[4:5], off
	s_add_u32 m0, s33, 0x16000
	v_lshl_add_u64 v[12:13], v[12:13], 0, s[84:85]
	global_load_lds_dwordx4 v[12:13], off
	v_and_b32_e32 v238, 31, v145
	v_lshrrev_b32_e32 v239, 8, v145
	v_bfe_u32 v240, v145, 6, 2
	v_lshl_add_u32 v239, v239, 7, v238
	v_lshl_add_u32 v240, v240, 5, v238
	v_lshlrev_b32_e32 v239, 7, v239
	v_lshlrev_b32_e32 v240, 7, v240
	v_bfe_u32 v241, v145, 5, 1
	v_bfe_u32 v242, v145, 1, 3
	v_or_b32_e32 v243, 0, v241
	v_xor_b32_e32 v243, v243, v242
	v_lshlrev_b32_e32 v243, 4, v243
	v_add_u32_e32 v14, v239, v243
	v_add_u32_e32 v186, v240, v243
	v_or_b32_e32 v243, 2, v241
	v_xor_b32_e32 v243, v243, v242
	v_lshlrev_b32_e32 v243, 4, v243
	v_add_u32_e32 v15, v239, v243
	v_add_u32_e32 v189, v240, v243
	v_or_b32_e32 v243, 4, v241
	v_xor_b32_e32 v243, v243, v242
	v_lshlrev_b32_e32 v243, 4, v243
	v_add_u32_e32 v0, v239, v243
	v_add_u32_e32 v233, v240, v243
	v_or_b32_e32 v243, 6, v241
	v_xor_b32_e32 v243, v243, v242
	v_lshlrev_b32_e32 v243, 4, v243
	v_add_u32_e32 v184, v239, v243
	v_add_u32_e32 v234, v240, v243
	s_waitcnt vmcnt(6)
	s_barrier
	ds_read_b128 v[180:183], v186 offset:32768
	ds_read_b128 v[238:241], v14
	ds_read_b128 v[242:245], v14 offset:4096
	ds_read_b128 v[246:249], v14 offset:8192
	ds_read_b128 v[250:253], v14 offset:12288
	s_add_u32 m0, s33, 0x18000
	v_lshl_add_u64 v[2:3], v[2:3], 0, s[84:85]
	global_load_lds_dwordx4 v[2:3], off
	s_add_u32 m0, s33, 0x1a000
	v_lshl_add_u64 v[6:7], v[6:7], 0, s[84:85]
	global_load_lds_dwordx4 v[6:7], off
	s_add_u32 m0, s33, 0x1c000
	v_lshl_add_u64 v[8:9], v[8:9], 0, s[84:85]
	global_load_lds_dwordx4 v[8:9], off
	s_add_u32 m0, s33, 0x1e000
	v_lshl_add_u64 v[10:11], v[10:11], 0, s[84:85]
	global_load_lds_dwordx4 v[10:11], off
	s_add_u32 m0, s33, 0x20000
	v_lshl_add_u64 v[4:5], v[4:5], 0, s[84:85]
	global_load_lds_dwordx4 v[4:5], off
	s_add_u32 m0, s33, 0x22000
	v_lshl_add_u64 v[12:13], v[12:13], 0, s[84:85]
	global_load_lds_dwordx4 v[12:13], off
	ds_read_b128 v[190:193], v189 offset:32768
	s_waitcnt lgkmcnt(4)
	v_mfma_f32_32x32x16_bf16 v[112:127], v[238:241], v[180:183], 0
	ds_read_b128 v[238:241], v15
	s_waitcnt lgkmcnt(4)
	v_mfma_f32_32x32x16_bf16 v[96:111], v[242:245], v[180:183], 0
	ds_read_b128 v[242:245], v15 offset:4096
	s_waitcnt lgkmcnt(4)
	v_mfma_f32_32x32x16_bf16 v[80:95], v[246:249], v[180:183], 0
	ds_read_b128 v[246:249], v15 offset:8192
	s_waitcnt lgkmcnt(4)
	v_mfma_f32_32x32x16_bf16 v[64:79], v[250:253], v[180:183], 0
	ds_read_b128 v[250:253], v15 offset:12288
	ds_read_b128 v[180:183], v233 offset:32768
	s_waitcnt lgkmcnt(4)
	v_mfma_f32_32x32x16_bf16 v[112:127], v[238:241], v[190:193], v[112:127]
	ds_read_b128 v[238:241], v0
	s_waitcnt lgkmcnt(4)
	v_mfma_f32_32x32x16_bf16 v[96:111], v[242:245], v[190:193], v[96:111]
	ds_read_b128 v[242:245], v0 offset:4096
	s_waitcnt lgkmcnt(4)
	v_mfma_f32_32x32x16_bf16 v[80:95], v[246:249], v[190:193], v[80:95]
	ds_read_b128 v[246:249], v0 offset:8192
	s_waitcnt lgkmcnt(4)
	v_mfma_f32_32x32x16_bf16 v[64:79], v[250:253], v[190:193], v[64:79]
	ds_read_b128 v[250:253], v0 offset:12288
	ds_read_b128 v[190:193], v234 offset:32768
	s_waitcnt lgkmcnt(4)
	v_mfma_f32_32x32x16_bf16 v[112:127], v[238:241], v[180:183], v[112:127]
	ds_read_b128 v[238:241], v184
	s_waitcnt lgkmcnt(4)
	v_mfma_f32_32x32x16_bf16 v[96:111], v[242:245], v[180:183], v[96:111]
	ds_read_b128 v[242:245], v184 offset:4096
	s_waitcnt lgkmcnt(4)
	v_mfma_f32_32x32x16_bf16 v[80:95], v[246:249], v[180:183], v[80:95]
	ds_read_b128 v[246:249], v184 offset:8192
	s_waitcnt lgkmcnt(4)
	v_mfma_f32_32x32x16_bf16 v[64:79], v[250:253], v[180:183], v[64:79]
	ds_read_b128 v[250:253], v184 offset:12288
	s_waitcnt lgkmcnt(3)
	v_mfma_f32_32x32x16_bf16 v[112:127], v[238:241], v[190:193], v[112:127]
	s_waitcnt lgkmcnt(2)
	v_mfma_f32_32x32x16_bf16 v[96:111], v[242:245], v[190:193], v[96:111]
	s_waitcnt lgkmcnt(1)
	v_mfma_f32_32x32x16_bf16 v[80:95], v[246:249], v[190:193], v[80:95]
	s_waitcnt lgkmcnt(0)
	v_mfma_f32_32x32x16_bf16 v[64:79], v[250:253], v[190:193], v[64:79]
	s_waitcnt vmcnt(6)
	s_barrier
; DI f32x16 mfma(bf16x8 a, bf16x8 b, f32x16 c) { return __builtin_amdgcn_mfma_f32_32x32x16_bf16(a, b, c, 0, 0, 0); }
;     ...
;   __syncthreads();
;   DMA_ISSUE(0, 0)
;   asm volatile("s_waitcnt vmcnt(0)" ::: "memory");
;   __builtin_amdgcn_s_barrier();
;   for (int kt = 0; kt < nk; ++kt) {
;     const char* cur = lds + (kt & 1) * DBUF;
;     if (kt + 1 < nk) DMA_ISSUE((kt + 1) & 1, kt + 1)
; #pragma unroll(NTB == 1 ? 2 : 4)
;     for (int s = 0; s < 4; ++s) {
;       const int ro = ((2 * s + hh) ^ xr) * 16;
;       bf16x8 bfr[NTB];
; #pragma unroll
;       for (int tb = 0; tb < NTB; ++tb) bfr[tb] = *(const bf16x8*)(cur + bbase + tb * 32 * DROW + ro);
; #pragma unroll
;       for (int fb = 0; fb < NFB; ++fb) {
;         const bf16x8 afr = *(const bf16x8*)(cur + abase + fb * 32 * DROW + ro);
; #pragma unroll
;         for (int tb = 0; tb < NTB; ++tb) acc[tb * NFB + fb] = mfma(afr, bfr[tb], acc[tb * NFB + fb]);
;       }
;     }
;     asm volatile("s_waitcnt vmcnt(0) lgkmcnt(0)" ::: "memory");
;     __builtin_amdgcn_s_barrier();
	v_add_u32_e32 v195, 0xc000, v186
	ds_read_b128 v[180:183], v195 offset:32768
	v_add_u32_e32 v194, 0xc000, v14
	ds_read_b128 v[238:241], v194
	ds_read_b128 v[242:245], v194 offset:4096
	ds_read_b128 v[246:249], v194 offset:8192
	ds_read_b128 v[250:253], v194 offset:12288
	s_add_u32 m0, s33, 0x0
	v_lshl_add_u64 v[2:3], v[2:3], 0, s[84:85]
	global_load_lds_dwordx4 v[2:3], off
	s_add_u32 m0, s33, 0x2000
	v_lshl_add_u64 v[6:7], v[6:7], 0, s[84:85]
	global_load_lds_dwordx4 v[6:7], off
	s_add_u32 m0, s33, 0x4000
	v_lshl_add_u64 v[8:9], v[8:9], 0, s[84:85]
	global_load_lds_dwordx4 v[8:9], off
	s_add_u32 m0, s33, 0x6000
	v_lshl_add_u64 v[10:11], v[10:11], 0, s[84:85]
	global_load_lds_dwordx4 v[10:11], off
	s_add_u32 m0, s33, 0x8000
	v_lshl_add_u64 v[4:5], v[4:5], 0, s[84:85]
	global_load_lds_dwordx4 v[4:5], off
	s_add_u32 m0, s33, 0xa000
	v_lshl_add_u64 v[12:13], v[12:13], 0, s[84:85]
	global_load_lds_dwordx4 v[12:13], off
	v_add_u32_e32 v195, 0xc000, v189
	ds_read_b128 v[190:193], v195 offset:32768
	v_add_u32_e32 v194, 0xc000, v15
	s_waitcnt lgkmcnt(4)
	v_mfma_f32_32x32x16_bf16 v[112:127], v[238:241], v[180:183], v[112:127]
	ds_read_b128 v[238:241], v194
	s_waitcnt lgkmcnt(4)
	v_mfma_f32_32x32x16_bf16 v[96:111], v[242:245], v[180:183], v[96:111]
	ds_read_b128 v[242:245], v194 offset:4096
	s_waitcnt lgkmcnt(4)
	v_mfma_f32_32x32x16_bf16 v[80:95], v[246:249], v[180:183], v[80:95]
	ds_read_b128 v[246:249], v194 offset:8192
	s_waitcnt lgkmcnt(4)
	v_mfma_f32_32x32x16_bf16 v[64:79], v[250:253], v[180:183], v[64:79]
	ds_read_b128 v[250:253], v194 offset:12288
	v_add_u32_e32 v195, 0xc000, v233
	ds_read_b128 v[180:183], v195 offset:32768
	v_add_u32_e32 v194, 0xc000, v0
	s_waitcnt lgkmcnt(4)
	v_mfma_f32_32x32x16_bf16 v[112:127], v[238:241], v[190:193], v[112:127]
	ds_read_b128 v[238:241], v194
	s_waitcnt lgkmcnt(4)
	v_mfma_f32_32x32x16_bf16 v[96:111], v[242:245], v[190:193], v[96:111]
	ds_read_b128 v[242:245], v194 offset:4096
	s_waitcnt lgkmcnt(4)
	v_mfma_f32_32x32x16_bf16 v[80:95], v[246:249], v[190:193], v[80:95]
	ds_read_b128 v[246:249], v194 offset:8192
	s_waitcnt lgkmcnt(4)
	v_mfma_f32_32x32x16_bf16 v[64:79], v[250:253], v[190:193], v[64:79]
	ds_read_b128 v[250:253], v194 offset:12288
	v_add_u32_e32 v195, 0xc000, v234
	ds_read_b128 v[190:193], v195 offset:32768
	v_add_u32_e32 v194, 0xc000, v184
	s_waitcnt lgkmcnt(4)
	v_mfma_f32_32x32x16_bf16 v[112:127], v[238:241], v[180:183], v[112:127]
	ds_read_b128 v[238:241], v194
	s_waitcnt lgkmcnt(4)
	v_mfma_f32_32x32x16_bf16 v[96:111], v[242:245], v[180:183], v[96:111]
	ds_read_b128 v[242:245], v194 offset:4096
	s_waitcnt lgkmcnt(4)
	v_mfma_f32_32x32x16_bf16 v[80:95], v[246:249], v[180:183], v[80:95]
	ds_read_b128 v[246:249], v194 offset:8192
	s_waitcnt lgkmcnt(4)
	v_mfma_f32_32x32x16_bf16 v[64:79], v[250:253], v[180:183], v[64:79]
	ds_read_b128 v[250:253], v194 offset:12288
	s_waitcnt lgkmcnt(3)
	v_mfma_f32_32x32x16_bf16 v[112:127], v[238:241], v[190:193], v[112:127]
	s_waitcnt lgkmcnt(2)
	v_mfma_f32_32x32x16_bf16 v[96:111], v[242:245], v[190:193], v[96:111]
	s_waitcnt lgkmcnt(1)
	v_mfma_f32_32x32x16_bf16 v[80:95], v[246:249], v[190:193], v[80:95]
	s_waitcnt lgkmcnt(0)
	v_mfma_f32_32x32x16_bf16 v[64:79], v[250:253], v[190:193], v[64:79]
	s_waitcnt vmcnt(6)
	s_barrier
	v_add_u32_e32 v195, 0x18000, v186
	ds_read_b128 v[180:183], v195 offset:32768
	v_add_u32_e32 v194, 0x18000, v14
	ds_read_b128 v[238:241], v194
	ds_read_b128 v[242:245], v194 offset:4096
	ds_read_b128 v[246:249], v194 offset:8192
	ds_read_b128 v[250:253], v194 offset:12288
	s_add_u32 m0, s33, 0xc000
	v_lshl_add_u64 v[2:3], v[2:3], 0, s[84:85]
	global_load_lds_dwordx4 v[2:3], off
	s_add_u32 m0, s33, 0xe000
	v_lshl_add_u64 v[6:7], v[6:7], 0, s[84:85]
	global_load_lds_dwordx4 v[6:7], off
	s_add_u32 m0, s33, 0x10000
	v_lshl_add_u64 v[8:9], v[8:9], 0, s[84:85]
	global_load_lds_dwordx4 v[8:9], off
	s_add_u32 m0, s33, 0x12000
	v_lshl_add_u64 v[10:11], v[10:11], 0, s[84:85]
	global_load_lds_dwordx4 v[10:11], off
	s_add_u32 m0, s33, 0x14000
	v_lshl_add_u64 v[4:5], v[4:5], 0, s[84:85]
	global_load_lds_dwordx4 v[4:5], off
	s_add_u32 m0, s33, 0x16000
	v_lshl_add_u64 v[12:13], v[12:13], 0, s[84:85]
	global_load_lds_dwordx4 v[12:13], off
	v_add_u32_e32 v195, 0x18000, v189
	ds_read_b128 v[190:193], v195 offset:32768
	v_add_u32_e32 v194, 0x18000, v15
	s_waitcnt lgkmcnt(4)
	v_mfma_f32_32x32x16_bf16 v[112:127], v[238:241], v[180:183], v[112:127]
	ds_read_b128 v[238:241], v194
	s_waitcnt lgkmcnt(4)
	v_mfma_f32_32x32x16_bf16 v[96:111], v[242:245], v[180:183], v[96:111]
	ds_read_b128 v[242:245], v194 offset:4096
	s_waitcnt lgkmcnt(4)
	v_mfma_f32_32x32x16_bf16 v[80:95], v[246:249], v[180:183], v[80:95]
	ds_read_b128 v[246:249], v194 offset:8192
	s_waitcnt lgkmcnt(4)
	v_mfma_f32_32x32x16_bf16 v[64:79], v[250:253], v[180:183], v[64:79]
	ds_read_b128 v[250:253], v194 offset:12288
	v_add_u32_e32 v195, 0x18000, v233
	ds_read_b128 v[180:183], v195 offset:32768
	v_add_u32_e32 v194, 0x18000, v0
	s_waitcnt lgkmcnt(4)
	v_mfma_f32_32x32x16_bf16 v[112:127], v[238:241], v[190:193], v[112:127]
	ds_read_b128 v[238:241], v194
	s_waitcnt lgkmcnt(4)
	v_mfma_f32_32x32x16_bf16 v[96:111], v[242:245], v[190:193], v[96:111]
	ds_read_b128 v[242:245], v194 offset:4096
	s_waitcnt lgkmcnt(4)
	v_mfma_f32_32x32x16_bf16 v[80:95], v[246:249], v[190:193], v[80:95]
	ds_read_b128 v[246:249], v194 offset:8192
	s_waitcnt lgkmcnt(4)
	v_mfma_f32_32x32x16_bf16 v[64:79], v[250:253], v[190:193], v[64:79]
	ds_read_b128 v[250:253], v194 offset:12288
	v_add_u32_e32 v195, 0x18000, v234
	ds_read_b128 v[190:193], v195 offset:32768
	v_add_u32_e32 v194, 0x18000, v184
	s_waitcnt lgkmcnt(4)
	v_mfma_f32_32x32x16_bf16 v[112:127], v[238:241], v[180:183], v[112:127]
	ds_read_b128 v[238:241], v194
	s_waitcnt lgkmcnt(4)
	v_mfma_f32_32x32x16_bf16 v[96:111], v[242:245], v[180:183], v[96:111]
	ds_read_b128 v[242:245], v194 offset:4096
	s_waitcnt lgkmcnt(4)
	v_mfma_f32_32x32x16_bf16 v[80:95], v[246:249], v[180:183], v[80:95]
	ds_read_b128 v[246:249], v194 offset:8192
	s_waitcnt lgkmcnt(4)
	v_mfma_f32_32x32x16_bf16 v[64:79], v[250:253], v[180:183], v[64:79]
	ds_read_b128 v[250:253], v194 offset:12288
	s_waitcnt lgkmcnt(3)
	v_mfma_f32_32x32x16_bf16 v[112:127], v[238:241], v[190:193], v[112:127]
	s_waitcnt lgkmcnt(2)
	v_mfma_f32_32x32x16_bf16 v[96:111], v[242:245], v[190:193], v[96:111]
	s_waitcnt lgkmcnt(1)
	v_mfma_f32_32x32x16_bf16 v[80:95], v[246:249], v[190:193], v[80:95]
	s_waitcnt lgkmcnt(0)
	v_mfma_f32_32x32x16_bf16 v[64:79], v[250:253], v[190:193], v[64:79]
	s_waitcnt vmcnt(6)
	s_barrier
; DI f32x16 mfma(bf16x8 a, bf16x8 b, f32x16 c) { return __builtin_amdgcn_mfma_f32_32x32x16_bf16(a, b, c, 0, 0, 0); }
;     ...
;   __syncthreads();
;   DMA_ISSUE(0, 0)
;   asm volatile("s_waitcnt vmcnt(0)" ::: "memory");
;   __builtin_amdgcn_s_barrier();
;   for (int kt = 0; kt < nk; ++kt) {
;     const char* cur = lds + (kt & 1) * DBUF;
;     if (kt + 1 < nk) DMA_ISSUE((kt + 1) & 1, kt + 1)
; #pragma unroll(NTB == 1 ? 2 : 4)
;     for (int s = 0; s < 4; ++s) {
;       const int ro = ((2 * s + hh) ^ xr) * 16;
;       bf16x8 bfr[NTB];
; #pragma unroll
;       for (int tb = 0; tb < NTB; ++tb) bfr[tb] = *(const bf16x8*)(cur + bbase + tb * 32 * DROW + ro);
; #pragma unroll
;       for (int fb = 0; fb < NFB; ++fb) {
;         const bf16x8 afr = *(const bf16x8*)(cur + abase + fb * 32 * DROW + ro);
; #pragma unroll
;         for (int tb = 0; tb < NTB; ++tb) acc[tb * NFB + fb] = mfma(afr, bfr[tb], acc[tb * NFB + fb]);
;       }
;     }
;     asm volatile("s_waitcnt vmcnt(0) lgkmcnt(0)" ::: "memory");
;     __builtin_amdgcn_s_barrier();
	ds_read_b128 v[180:183], v186 offset:32768
	ds_read_b128 v[238:241], v14
	ds_read_b128 v[242:245], v14 offset:4096
	ds_read_b128 v[246:249], v14 offset:8192
	ds_read_b128 v[250:253], v14 offset:12288
	s_add_u32 m0, s33, 0x18000
	v_lshl_add_u64 v[2:3], v[2:3], 0, s[84:85]
	global_load_lds_dwordx4 v[2:3], off
	s_add_u32 m0, s33, 0x1a000
	v_lshl_add_u64 v[6:7], v[6:7], 0, s[84:85]
	global_load_lds_dwordx4 v[6:7], off
	s_add_u32 m0, s33, 0x1c000
	v_lshl_add_u64 v[8:9], v[8:9], 0, s[84:85]
	global_load_lds_dwordx4 v[8:9], off
	s_add_u32 m0, s33, 0x1e000
	v_lshl_add_u64 v[10:11], v[10:11], 0, s[84:85]
	global_load_lds_dwordx4 v[10:11], off
	s_add_u32 m0, s33, 0x20000
	v_lshl_add_u64 v[4:5], v[4:5], 0, s[84:85]
	global_load_lds_dwordx4 v[4:5], off
	s_add_u32 m0, s33, 0x22000
	v_lshl_add_u64 v[12:13], v[12:13], 0, s[84:85]
	global_load_lds_dwordx4 v[12:13], off
	ds_read_b128 v[190:193], v189 offset:32768
	s_waitcnt lgkmcnt(4)
	v_mfma_f32_32x32x16_bf16 v[112:127], v[238:241], v[180:183], v[112:127]
	ds_read_b128 v[238:241], v15
	s_waitcnt lgkmcnt(4)
	v_mfma_f32_32x32x16_bf16 v[96:111], v[242:245], v[180:183], v[96:111]
	ds_read_b128 v[242:245], v15 offset:4096
	s_waitcnt lgkmcnt(4)
	v_mfma_f32_32x32x16_bf16 v[80:95], v[246:249], v[180:183], v[80:95]
	ds_read_b128 v[246:249], v15 offset:8192
	s_waitcnt lgkmcnt(4)
	v_mfma_f32_32x32x16_bf16 v[64:79], v[250:253], v[180:183], v[64:79]
	ds_read_b128 v[250:253], v15 offset:12288
	ds_read_b128 v[180:183], v233 offset:32768
	s_waitcnt lgkmcnt(4)
	v_mfma_f32_32x32x16_bf16 v[112:127], v[238:241], v[190:193], v[112:127]
	ds_read_b128 v[238:241], v0
	s_waitcnt lgkmcnt(4)
	v_mfma_f32_32x32x16_bf16 v[96:111], v[242:245], v[190:193], v[96:111]
	ds_read_b128 v[242:245], v0 offset:4096
	s_waitcnt lgkmcnt(4)
	v_mfma_f32_32x32x16_bf16 v[80:95], v[246:249], v[190:193], v[80:95]
	ds_read_b128 v[246:249], v0 offset:8192
	s_waitcnt lgkmcnt(4)
	v_mfma_f32_32x32x16_bf16 v[64:79], v[250:253], v[190:193], v[64:79]
	ds_read_b128 v[250:253], v0 offset:12288
	ds_read_b128 v[190:193], v234 offset:32768
	s_waitcnt lgkmcnt(4)
	v_mfma_f32_32x32x16_bf16 v[112:127], v[238:241], v[180:183], v[112:127]
	ds_read_b128 v[238:241], v184
	s_waitcnt lgkmcnt(4)
	v_mfma_f32_32x32x16_bf16 v[96:111], v[242:245], v[180:183], v[96:111]
	ds_read_b128 v[242:245], v184 offset:4096
	s_waitcnt lgkmcnt(4)
	v_mfma_f32_32x32x16_bf16 v[80:95], v[246:249], v[180:183], v[80:95]
	ds_read_b128 v[246:249], v184 offset:8192
	s_waitcnt lgkmcnt(4)
	v_mfma_f32_32x32x16_bf16 v[64:79], v[250:253], v[180:183], v[64:79]
	ds_read_b128 v[250:253], v184 offset:12288
	s_waitcnt lgkmcnt(3)
	v_mfma_f32_32x32x16_bf16 v[112:127], v[238:241], v[190:193], v[112:127]
	s_waitcnt lgkmcnt(2)
	v_mfma_f32_32x32x16_bf16 v[96:111], v[242:245], v[190:193], v[96:111]
	s_waitcnt lgkmcnt(1)
	v_mfma_f32_32x32x16_bf16 v[80:95], v[246:249], v[190:193], v[80:95]
	s_waitcnt lgkmcnt(0)
	v_mfma_f32_32x32x16_bf16 v[64:79], v[250:253], v[190:193], v[64:79]
	s_waitcnt vmcnt(6)
	s_barrier
	v_add_u32_e32 v195, 0xc000, v186
	ds_read_b128 v[180:183], v195 offset:32768
	v_add_u32_e32 v194, 0xc000, v14
	ds_read_b128 v[238:241], v194
	ds_read_b128 v[242:245], v194 offset:4096
	ds_read_b128 v[246:249], v194 offset:8192
	ds_read_b128 v[250:253], v194 offset:12288
	s_add_u32 m0, s33, 0x0
	v_lshl_add_u64 v[2:3], v[2:3], 0, s[84:85]
	global_load_lds_dwordx4 v[2:3], off
	s_add_u32 m0, s33, 0x2000
	v_lshl_add_u64 v[6:7], v[6:7], 0, s[84:85]
	global_load_lds_dwordx4 v[6:7], off
	s_add_u32 m0, s33, 0x4000
	v_lshl_add_u64 v[8:9], v[8:9], 0, s[84:85]
	global_load_lds_dwordx4 v[8:9], off
	s_add_u32 m0, s33, 0x6000
	v_lshl_add_u64 v[10:11], v[10:11], 0, s[84:85]
	global_load_lds_dwordx4 v[10:11], off
	s_add_u32 m0, s33, 0x8000
	v_lshl_add_u64 v[4:5], v[4:5], 0, s[84:85]
	global_load_lds_dwordx4 v[4:5], off
	s_add_u32 m0, s33, 0xa000
	v_lshl_add_u64 v[12:13], v[12:13], 0, s[84:85]
	global_load_lds_dwordx4 v[12:13], off
	v_add_u32_e32 v195, 0xc000, v189
	ds_read_b128 v[190:193], v195 offset:32768
	v_add_u32_e32 v194, 0xc000, v15
	s_waitcnt lgkmcnt(4)
	v_mfma_f32_32x32x16_bf16 v[112:127], v[238:241], v[180:183], v[112:127]
	ds_read_b128 v[238:241], v194
	s_waitcnt lgkmcnt(4)
	v_mfma_f32_32x32x16_bf16 v[96:111], v[242:245], v[180:183], v[96:111]
	ds_read_b128 v[242:245], v194 offset:4096
	s_waitcnt lgkmcnt(4)
	v_mfma_f32_32x32x16_bf16 v[80:95], v[246:249], v[180:183], v[80:95]
	ds_read_b128 v[246:249], v194 offset:8192
	s_waitcnt lgkmcnt(4)
	v_mfma_f32_32x32x16_bf16 v[64:79], v[250:253], v[180:183], v[64:79]
	ds_read_b128 v[250:253], v194 offset:12288
	v_add_u32_e32 v195, 0xc000, v233
	ds_read_b128 v[180:183], v195 offset:32768
	v_add_u32_e32 v194, 0xc000, v0
	s_waitcnt lgkmcnt(4)
	v_mfma_f32_32x32x16_bf16 v[112:127], v[238:241], v[190:193], v[112:127]
	ds_read_b128 v[238:241], v194
	s_waitcnt lgkmcnt(4)
	v_mfma_f32_32x32x16_bf16 v[96:111], v[242:245], v[190:193], v[96:111]
	ds_read_b128 v[242:245], v194 offset:4096
	s_waitcnt lgkmcnt(4)
	v_mfma_f32_32x32x16_bf16 v[80:95], v[246:249], v[190:193], v[80:95]
	ds_read_b128 v[246:249], v194 offset:8192
	s_waitcnt lgkmcnt(4)
	v_mfma_f32_32x32x16_bf16 v[64:79], v[250:253], v[190:193], v[64:79]
	ds_read_b128 v[250:253], v194 offset:12288
	v_add_u32_e32 v195, 0xc000, v234
	ds_read_b128 v[190:193], v195 offset:32768
	v_add_u32_e32 v194, 0xc000, v184
	s_waitcnt lgkmcnt(4)
	v_mfma_f32_32x32x16_bf16 v[112:127], v[238:241], v[180:183], v[112:127]
	ds_read_b128 v[238:241], v194
	s_waitcnt lgkmcnt(4)
	v_mfma_f32_32x32x16_bf16 v[96:111], v[242:245], v[180:183], v[96:111]
	ds_read_b128 v[242:245], v194 offset:4096
	s_waitcnt lgkmcnt(4)
	v_mfma_f32_32x32x16_bf16 v[80:95], v[246:249], v[180:183], v[80:95]
	ds_read_b128 v[246:249], v194 offset:8192
	s_waitcnt lgkmcnt(4)
	v_mfma_f32_32x32x16_bf16 v[64:79], v[250:253], v[180:183], v[64:79]
	ds_read_b128 v[250:253], v194 offset:12288
	s_waitcnt lgkmcnt(3)
	v_mfma_f32_32x32x16_bf16 v[112:127], v[238:241], v[190:193], v[112:127]
	s_waitcnt lgkmcnt(2)
	v_mfma_f32_32x32x16_bf16 v[96:111], v[242:245], v[190:193], v[96:111]
	s_waitcnt lgkmcnt(1)
	v_mfma_f32_32x32x16_bf16 v[80:95], v[246:249], v[190:193], v[80:95]
	s_waitcnt lgkmcnt(0)
	v_mfma_f32_32x32x16_bf16 v[64:79], v[250:253], v[190:193], v[64:79]
	s_waitcnt vmcnt(6)
	s_barrier
; DI f32x16 mfma(bf16x8 a, bf16x8 b, f32x16 c) { return __builtin_amdgcn_mfma_f32_32x32x16_bf16(a, b, c, 0, 0, 0); }
;     ...
;   __syncthreads();
;   DMA_ISSUE(0, 0)
;   asm volatile("s_waitcnt vmcnt(0)" ::: "memory");
;   __builtin_amdgcn_s_barrier();
;   for (int kt = 0; kt < nk; ++kt) {
;     const char* cur = lds + (kt & 1) * DBUF;
;     if (kt + 1 < nk) DMA_ISSUE((kt + 1) & 1, kt + 1)
; #pragma unroll(NTB == 1 ? 2 : 4)
;     for (int s = 0; s < 4; ++s) {
;       const int ro = ((2 * s + hh) ^ xr) * 16;
;       bf16x8 bfr[NTB];
; #pragma unroll
;       for (int tb = 0; tb < NTB; ++tb) bfr[tb] = *(const bf16x8*)(cur + bbase + tb * 32 * DROW + ro);
; #pragma unroll
;       for (int fb = 0; fb < NFB; ++fb) {
;         const bf16x8 afr = *(const bf16x8*)(cur + abase + fb * 32 * DROW + ro);
; #pragma unroll
;         for (int tb = 0; tb < NTB; ++tb) acc[tb * NFB + fb] = mfma(afr, bfr[tb], acc[tb * NFB + fb]);
;       }
;     }
;     asm volatile("s_waitcnt vmcnt(0) lgkmcnt(0)" ::: "memory");
;     __builtin_amdgcn_s_barrier();
	v_add_u32_e32 v195, 0x18000, v186
	ds_read_b128 v[180:183], v195 offset:32768
	v_add_u32_e32 v194, 0x18000, v14
	ds_read_b128 v[238:241], v194
	ds_read_b128 v[242:245], v194 offset:4096
	ds_read_b128 v[246:249], v194 offset:8192
	ds_read_b128 v[250:253], v194 offset:12288
	s_add_u32 m0, s33, 0xc000
	v_lshl_add_u64 v[2:3], v[2:3], 0, s[84:85]
	global_load_lds_dwordx4 v[2:3], off
	s_add_u32 m0, s33, 0xe000
	v_lshl_add_u64 v[6:7], v[6:7], 0, s[84:85]
	global_load_lds_dwordx4 v[6:7], off
	s_add_u32 m0, s33, 0x10000
	v_lshl_add_u64 v[8:9], v[8:9], 0, s[84:85]
	global_load_lds_dwordx4 v[8:9], off
	s_add_u32 m0, s33, 0x12000
	v_lshl_add_u64 v[10:11], v[10:11], 0, s[84:85]
	global_load_lds_dwordx4 v[10:11], off
	s_add_u32 m0, s33, 0x14000
	v_lshl_add_u64 v[4:5], v[4:5], 0, s[84:85]
	global_load_lds_dwordx4 v[4:5], off
	s_add_u32 m0, s33, 0x16000
	v_lshl_add_u64 v[12:13], v[12:13], 0, s[84:85]
	global_load_lds_dwordx4 v[12:13], off
	v_add_u32_e32 v195, 0x18000, v189
	ds_read_b128 v[190:193], v195 offset:32768
	v_add_u32_e32 v194, 0x18000, v15
	s_waitcnt lgkmcnt(4)
	v_mfma_f32_32x32x16_bf16 v[112:127], v[238:241], v[180:183], v[112:127]
	ds_read_b128 v[238:241], v194
	s_waitcnt lgkmcnt(4)
	v_mfma_f32_32x32x16_bf16 v[96:111], v[242:245], v[180:183], v[96:111]
	ds_read_b128 v[242:245], v194 offset:4096
	s_waitcnt lgkmcnt(4)
	v_mfma_f32_32x32x16_bf16 v[80:95], v[246:249], v[180:183], v[80:95]
	ds_read_b128 v[246:249], v194 offset:8192
	s_waitcnt lgkmcnt(4)
	v_mfma_f32_32x32x16_bf16 v[64:79], v[250:253], v[180:183], v[64:79]
	ds_read_b128 v[250:253], v194 offset:12288
	v_add_u32_e32 v195, 0x18000, v233
	ds_read_b128 v[180:183], v195 offset:32768
	v_add_u32_e32 v194, 0x18000, v0
	s_waitcnt lgkmcnt(4)
	v_mfma_f32_32x32x16_bf16 v[112:127], v[238:241], v[190:193], v[112:127]
	ds_read_b128 v[238:241], v194
	s_waitcnt lgkmcnt(4)
	v_mfma_f32_32x32x16_bf16 v[96:111], v[242:245], v[190:193], v[96:111]
	ds_read_b128 v[242:245], v194 offset:4096
	s_waitcnt lgkmcnt(4)
	v_mfma_f32_32x32x16_bf16 v[80:95], v[246:249], v[190:193], v[80:95]
	ds_read_b128 v[246:249], v194 offset:8192
	s_waitcnt lgkmcnt(4)
	v_mfma_f32_32x32x16_bf16 v[64:79], v[250:253], v[190:193], v[64:79]
	ds_read_b128 v[250:253], v194 offset:12288
	v_add_u32_e32 v195, 0x18000, v234
	ds_read_b128 v[190:193], v195 offset:32768
	v_add_u32_e32 v194, 0x18000, v184
	s_waitcnt lgkmcnt(4)
	v_mfma_f32_32x32x16_bf16 v[112:127], v[238:241], v[180:183], v[112:127]
	ds_read_b128 v[238:241], v194
	s_waitcnt lgkmcnt(4)
	v_mfma_f32_32x32x16_bf16 v[96:111], v[242:245], v[180:183], v[96:111]
	ds_read_b128 v[242:245], v194 offset:4096
	s_waitcnt lgkmcnt(4)
	v_mfma_f32_32x32x16_bf16 v[80:95], v[246:249], v[180:183], v[80:95]
	ds_read_b128 v[246:249], v194 offset:8192
	s_waitcnt lgkmcnt(4)
	v_mfma_f32_32x32x16_bf16 v[64:79], v[250:253], v[180:183], v[64:79]
	ds_read_b128 v[250:253], v194 offset:12288
	s_waitcnt lgkmcnt(3)
	v_mfma_f32_32x32x16_bf16 v[112:127], v[238:241], v[190:193], v[112:127]
	s_waitcnt lgkmcnt(2)
	v_mfma_f32_32x32x16_bf16 v[96:111], v[242:245], v[190:193], v[96:111]
	s_waitcnt lgkmcnt(1)
	v_mfma_f32_32x32x16_bf16 v[80:95], v[246:249], v[190:193], v[80:95]
	s_waitcnt lgkmcnt(0)
	v_mfma_f32_32x32x16_bf16 v[64:79], v[250:253], v[190:193], v[64:79]
	s_waitcnt vmcnt(6)
	s_barrier
	ds_read_b128 v[180:183], v186 offset:32768
	ds_read_b128 v[238:241], v14
	ds_read_b128 v[242:245], v14 offset:4096
	ds_read_b128 v[246:249], v14 offset:8192
	ds_read_b128 v[250:253], v14 offset:12288
	ds_read_b128 v[190:193], v189 offset:32768
	s_waitcnt lgkmcnt(4)
	v_mfma_f32_32x32x16_bf16 v[112:127], v[238:241], v[180:183], v[112:127]
	ds_read_b128 v[238:241], v15
	s_waitcnt lgkmcnt(4)
	v_mfma_f32_32x32x16_bf16 v[96:111], v[242:245], v[180:183], v[96:111]
	ds_read_b128 v[242:245], v15 offset:4096
	s_waitcnt lgkmcnt(4)
	v_mfma_f32_32x32x16_bf16 v[80:95], v[246:249], v[180:183], v[80:95]
	ds_read_b128 v[246:249], v15 offset:8192
	s_waitcnt lgkmcnt(4)
	v_mfma_f32_32x32x16_bf16 v[64:79], v[250:253], v[180:183], v[64:79]
	ds_read_b128 v[250:253], v15 offset:12288
	ds_read_b128 v[180:183], v233 offset:32768
	s_waitcnt lgkmcnt(4)
	v_mfma_f32_32x32x16_bf16 v[112:127], v[238:241], v[190:193], v[112:127]
	ds_read_b128 v[238:241], v0
	s_waitcnt lgkmcnt(4)
	v_mfma_f32_32x32x16_bf16 v[96:111], v[242:245], v[190:193], v[96:111]
	ds_read_b128 v[242:245], v0 offset:4096
	s_waitcnt lgkmcnt(4)
	v_mfma_f32_32x32x16_bf16 v[80:95], v[246:249], v[190:193], v[80:95]
	ds_read_b128 v[246:249], v0 offset:8192
	s_waitcnt lgkmcnt(4)
	v_mfma_f32_32x32x16_bf16 v[64:79], v[250:253], v[190:193], v[64:79]
	ds_read_b128 v[250:253], v0 offset:12288
	ds_read_b128 v[190:193], v234 offset:32768
	s_waitcnt lgkmcnt(4)
	v_mfma_f32_32x32x16_bf16 v[112:127], v[238:241], v[180:183], v[112:127]
	ds_read_b128 v[238:241], v184
	s_waitcnt lgkmcnt(4)
	v_mfma_f32_32x32x16_bf16 v[96:111], v[242:245], v[180:183], v[96:111]
	ds_read_b128 v[242:245], v184 offset:4096
	s_waitcnt lgkmcnt(4)
	v_mfma_f32_32x32x16_bf16 v[80:95], v[246:249], v[180:183], v[80:95]
	ds_read_b128 v[246:249], v184 offset:8192
	s_waitcnt lgkmcnt(4)
	v_mfma_f32_32x32x16_bf16 v[64:79], v[250:253], v[180:183], v[64:79]
	ds_read_b128 v[250:253], v184 offset:12288
	s_waitcnt lgkmcnt(3)
	v_mfma_f32_32x32x16_bf16 v[112:127], v[238:241], v[190:193], v[112:127]
	s_waitcnt lgkmcnt(2)
	v_mfma_f32_32x32x16_bf16 v[96:111], v[242:245], v[190:193], v[96:111]
	s_waitcnt lgkmcnt(1)
	v_mfma_f32_32x32x16_bf16 v[80:95], v[246:249], v[190:193], v[80:95]
	s_waitcnt lgkmcnt(0)
	v_mfma_f32_32x32x16_bf16 v[64:79], v[250:253], v[190:193], v[64:79]
	s_waitcnt vmcnt(0)
	s_barrier
; DI int get_tid() { int t = threadIdx.x; asm volatile("" : "+v"(t)); return t; }
;     ...
;   const int tid = get_tid(), lane = tid & 63, wave = tid >> 6, l32 = lane & 31, hh = lane >> 5;
;   const int wf = wave >> 2, wt = wave & 3;
;   const int crow = tid >> 3, q = tid & 7;
;   const int gc = q ^ ((crow >> 1) & 7);
;   const u16* wp = W + (size_t)crow * ldw + gc * 8;
;   const u16* xp = X + (size_t)crow * ldx + gc * 8;
;   char* lw = lds + tid * 16;
;   const int xr = (l32 >> 1) & 7;
;   const int abase = (wf * NFB * 32 + l32) * DROW;
;   const int bbase = 256 * DROW + (wt * NTB * 32 + l32) * DROW;
;     ...
;   __syncthreads();
;   DMA_ISSUE(0, 0)
;   asm volatile("s_waitcnt vmcnt(0)" ::: "memory");
;   __builtin_amdgcn_s_barrier();
;   for (int kt = 0; kt < nk; ++kt) {
;     const char* cur = lds + (kt & 1) * DBUF;
;     if (kt + 1 < nk) DMA_ISSUE((kt + 1) & 1, kt + 1)
; __global__ void __launch_bounds__(512) mega(Params p) {
;     ...
;           gemm_main<4, 1>((const u16*)(ws + OFF_WG) + ((size_t)n * 1024 + ft * 256) * 1024, 1024, (const u16*)(ws + OFF_H) + (size_t)tt * 128 * 1024, 1024, 16, acc, lds);
	v_add_u32_e32 v195, 0xc000, v186
	ds_read_b128 v[180:183], v195 offset:32768
	v_add_u32_e32 v194, 0xc000, v14
	ds_read_b128 v[238:241], v194
	ds_read_b128 v[242:245], v194 offset:4096
	ds_read_b128 v[246:249], v194 offset:8192
	ds_read_b128 v[250:253], v194 offset:12288
	v_add_u32_e32 v195, 0xc000, v189
	ds_read_b128 v[190:193], v195 offset:32768
	v_add_u32_e32 v194, 0xc000, v15
	s_waitcnt lgkmcnt(4)
	v_mfma_f32_32x32x16_bf16 v[112:127], v[238:241], v[180:183], v[112:127]
	ds_read_b128 v[238:241], v194
	s_waitcnt lgkmcnt(4)
	v_mfma_f32_32x32x16_bf16 v[96:111], v[242:245], v[180:183], v[96:111]
	ds_read_b128 v[242:245], v194 offset:4096
	s_waitcnt lgkmcnt(4)
	v_mfma_f32_32x32x16_bf16 v[80:95], v[246:249], v[180:183], v[80:95]
	ds_read_b128 v[246:249], v194 offset:8192
	s_waitcnt lgkmcnt(4)
	v_mfma_f32_32x32x16_bf16 v[64:79], v[250:253], v[180:183], v[64:79]
	ds_read_b128 v[250:253], v194 offset:12288
	v_add_u32_e32 v195, 0xc000, v233
	ds_read_b128 v[180:183], v195 offset:32768
	v_add_u32_e32 v194, 0xc000, v0
	s_waitcnt lgkmcnt(4)
	v_mfma_f32_32x32x16_bf16 v[112:127], v[238:241], v[190:193], v[112:127]
	ds_read_b128 v[238:241], v194
	s_waitcnt lgkmcnt(4)
	v_mfma_f32_32x32x16_bf16 v[96:111], v[242:245], v[190:193], v[96:111]
	ds_read_b128 v[242:245], v194 offset:4096
	s_waitcnt lgkmcnt(4)
	v_mfma_f32_32x32x16_bf16 v[80:95], v[246:249], v[190:193], v[80:95]
	ds_read_b128 v[246:249], v194 offset:8192
	s_waitcnt lgkmcnt(4)
	v_mfma_f32_32x32x16_bf16 v[64:79], v[250:253], v[190:193], v[64:79]
	ds_read_b128 v[250:253], v194 offset:12288
	v_add_u32_e32 v195, 0xc000, v234
	ds_read_b128 v[190:193], v195 offset:32768
	v_add_u32_e32 v194, 0xc000, v184
	s_waitcnt lgkmcnt(4)
	v_mfma_f32_32x32x16_bf16 v[112:127], v[238:241], v[180:183], v[112:127]
	ds_read_b128 v[238:241], v194
	s_waitcnt lgkmcnt(4)
	v_mfma_f32_32x32x16_bf16 v[96:111], v[242:245], v[180:183], v[96:111]
	ds_read_b128 v[242:245], v194 offset:4096
	s_waitcnt lgkmcnt(4)
	v_mfma_f32_32x32x16_bf16 v[80:95], v[246:249], v[180:183], v[80:95]
	ds_read_b128 v[246:249], v194 offset:8192
	s_waitcnt lgkmcnt(4)
	v_mfma_f32_32x32x16_bf16 v[64:79], v[250:253], v[180:183], v[64:79]
	ds_read_b128 v[250:253], v194 offset:12288
	s_waitcnt lgkmcnt(3)
	v_mfma_f32_32x32x16_bf16 v[112:127], v[238:241], v[190:193], v[112:127]
	s_waitcnt lgkmcnt(2)
	v_mfma_f32_32x32x16_bf16 v[96:111], v[242:245], v[190:193], v[96:111]
	s_waitcnt lgkmcnt(1)
	v_mfma_f32_32x32x16_bf16 v[80:95], v[246:249], v[190:193], v[80:95]
	s_waitcnt lgkmcnt(0)
	v_mfma_f32_32x32x16_bf16 v[64:79], v[250:253], v[190:193], v[64:79]
	s_nop 7
	s_nop 7
	s_waitcnt vmcnt(0) lgkmcnt(0)
	s_barrier
	s_lshl_b64 s[34:35], s[34:35], 11
	s_add_u32 s34, s38, s34
	s_addc_u32 s35, s39, s35
	v_ashrrev_i32_e32 v12, 3, v145
	v_lshrrev_b32_e32 v0, 4, v145
	v_xor_b32_e32 v0, v0, v145
	v_ashrrev_i32_e32 v13, 31, v12
	v_lshlrev_b64 v[12:13], 11, v[12:13]
	v_lshlrev_b32_e32 v0, 4, v0
	v_and_b32_e32 v0, 0x70, v0
	v_lshl_add_u64 v[2:3], s[34:35], 0, v[12:13]
	v_lshl_add_u64 v[4:5], s[64:65], 0, v[12:13]
	v_lshl_add_u64 v[2:3], v[2:3], 0, v[0:1]
	v_lshl_add_u64 v[4:5], v[4:5], 0, v[0:1]
	s_mov_b64 s[68:69], 0x20000
	v_lshl_add_u64 v[6:7], v[2:3], 0, s[68:69]
	v_lshl_add_u64 v[12:13], v[4:5], 0, s[68:69]
	v_lshl_add_u64 v[8:9], v[6:7], 0, s[68:69]
	v_lshl_add_u64 v[10:11], v[8:9], 0, s[68:69]
	s_waitcnt vmcnt(0) lgkmcnt(0)
	s_barrier
	s_add_u32 m0, s33, 0x0
	s_nop 0
	global_load_lds_dwordx4 v[2:3], off
	s_add_u32 m0, s33, 0x2000
	s_nop 0
	global_load_lds_dwordx4 v[6:7], off
	s_add_u32 m0, s33, 0x4000
	s_nop 0
	global_load_lds_dwordx4 v[8:9], off
	s_add_u32 m0, s33, 0x6000
	s_nop 0
	global_load_lds_dwordx4 v[10:11], off
	s_add_u32 m0, s33, 0x8000
	s_nop 0
	global_load_lds_dwordx4 v[4:5], off
	s_add_u32 m0, s33, 0xa000
	s_nop 0
	global_load_lds_dwordx4 v[12:13], off
	s_add_u32 m0, s33, 0xc000
	v_lshl_add_u64 v[2:3], v[2:3], 0, s[84:85]
	global_load_lds_dwordx4 v[2:3], off
	s_add_u32 m0, s33, 0xe000
	v_lshl_add_u64 v[6:7], v[6:7], 0, s[84:85]
	global_load_lds_dwordx4 v[6:7], off
	s_add_u32 m0, s33, 0x10000
	v_lshl_add_u64 v[8:9], v[8:9], 0, s[84:85]
	global_load_lds_dwordx4 v[8:9], off
	s_add_u32 m0, s33, 0x12000
	v_lshl_add_u64 v[10:11], v[10:11], 0, s[84:85]
	global_load_lds_dwordx4 v[10:11], off
	s_add_u32 m0, s33, 0x14000
	v_lshl_add_u64 v[4:5], v[4:5], 0, s[84:85]
	global_load_lds_dwordx4 v[4:5], off
	s_add_u32 m0, s33, 0x16000
	v_lshl_add_u64 v[12:13], v[12:13], 0, s[84:85]
	global_load_lds_dwordx4 v[12:13], off
	v_and_b32_e32 v238, 31, v145
	v_lshrrev_b32_e32 v239, 8, v145
	v_bfe_u32 v240, v145, 6, 2
	v_lshl_add_u32 v239, v239, 7, v238
	v_lshl_add_u32 v240, v240, 5, v238
	v_lshlrev_b32_e32 v239, 7, v239
	v_lshlrev_b32_e32 v240, 7, v240
	v_bfe_u32 v241, v145, 5, 1
	v_bfe_u32 v242, v145, 1, 3
	v_or_b32_e32 v243, 0, v241
	v_xor_b32_e32 v243, v243, v242
	v_lshlrev_b32_e32 v243, 4, v243
	v_add_u32_e32 v14, v239, v243
	v_add_u32_e32 v186, v240, v243
	v_or_b32_e32 v243, 2, v241
	v_xor_b32_e32 v243, v243, v242
	v_lshlrev_b32_e32 v243, 4, v243
	v_add_u32_e32 v15, v239, v243
	v_add_u32_e32 v189, v240, v243
	v_or_b32_e32 v243, 4, v241
	v_xor_b32_e32 v243, v243, v242
	v_lshlrev_b32_e32 v243, 4, v243
	v_add_u32_e32 v0, v239, v243
	v_add_u32_e32 v233, v240, v243
	v_or_b32_e32 v243, 6, v241
	v_xor_b32_e32 v243, v243, v242
	v_lshlrev_b32_e32 v243, 4, v243
	v_add_u32_e32 v184, v239, v243
	v_add_u32_e32 v234, v240, v243
	s_waitcnt vmcnt(6)
	s_barrier
; DI f32x16 mfma(bf16x8 a, bf16x8 b, f32x16 c) { return __builtin_amdgcn_mfma_f32_32x32x16_bf16(a, b, c, 0, 0, 0); }
;     ...
;   for (int kt = 0; kt < nk; ++kt) {
;     const char* cur = lds + (kt & 1) * DBUF;
;     if (kt + 1 < nk) DMA_ISSUE((kt + 1) & 1, kt + 1)
; #pragma unroll(NTB == 1 ? 2 : 4)
;     for (int s = 0; s < 4; ++s) {
;       const int ro = ((2 * s + hh) ^ xr) * 16;
;       bf16x8 bfr[NTB];
; #pragma unroll
;       for (int tb = 0; tb < NTB; ++tb) bfr[tb] = *(const bf16x8*)(cur + bbase + tb * 32 * DROW + ro);
; #pragma unroll
;       for (int fb = 0; fb < NFB; ++fb) {
;         const bf16x8 afr = *(const bf16x8*)(cur + abase + fb * 32 * DROW + ro);
; #pragma unroll
;         for (int tb = 0; tb < NTB; ++tb) acc[tb * NFB + fb] = mfma(afr, bfr[tb], acc[tb * NFB + fb]);
;       }
;     }
;     asm volatile("s_waitcnt vmcnt(0) lgkmcnt(0)" ::: "memory");
;     __builtin_amdgcn_s_barrier();
	ds_read_b128 v[180:183], v186 offset:32768
	ds_read_b128 v[238:241], v14
	ds_read_b128 v[242:245], v14 offset:4096
	ds_read_b128 v[246:249], v14 offset:8192
	ds_read_b128 v[250:253], v14 offset:12288
	s_add_u32 m0, s33, 0x18000
	v_lshl_add_u64 v[2:3], v[2:3], 0, s[84:85]
	global_load_lds_dwordx4 v[2:3], off
	s_add_u32 m0, s33, 0x1a000
	v_lshl_add_u64 v[6:7], v[6:7], 0, s[84:85]
	global_load_lds_dwordx4 v[6:7], off
	s_add_u32 m0, s33, 0x1c000
	v_lshl_add_u64 v[8:9], v[8:9], 0, s[84:85]
	global_load_lds_dwordx4 v[8:9], off
	s_add_u32 m0, s33, 0x1e000
	v_lshl_add_u64 v[10:11], v[10:11], 0, s[84:85]
	global_load_lds_dwordx4 v[10:11], off
	s_add_u32 m0, s33, 0x20000
	v_lshl_add_u64 v[4:5], v[4:5], 0, s[84:85]
	global_load_lds_dwordx4 v[4:5], off
	s_add_u32 m0, s33, 0x22000
	v_lshl_add_u64 v[12:13], v[12:13], 0, s[84:85]
	global_load_lds_dwordx4 v[12:13], off
	ds_read_b128 v[190:193], v189 offset:32768
	s_waitcnt lgkmcnt(4)
	v_mfma_f32_32x32x16_bf16 v[128:143], v[238:241], v[180:183], 0
	ds_read_b128 v[238:241], v15
	s_waitcnt lgkmcnt(4)
	v_mfma_f32_32x32x16_bf16 v[48:63], v[242:245], v[180:183], 0
	ds_read_b128 v[242:245], v15 offset:4096
	s_waitcnt lgkmcnt(4)
	v_mfma_f32_32x32x16_bf16 v[32:47], v[246:249], v[180:183], 0
	ds_read_b128 v[246:249], v15 offset:8192
	s_waitcnt lgkmcnt(4)
	v_mfma_f32_32x32x16_bf16 v[16:31], v[250:253], v[180:183], 0
	ds_read_b128 v[250:253], v15 offset:12288
	ds_read_b128 v[180:183], v233 offset:32768
	s_waitcnt lgkmcnt(4)
	v_mfma_f32_32x32x16_bf16 v[128:143], v[238:241], v[190:193], v[128:143]
	ds_read_b128 v[238:241], v0
	s_waitcnt lgkmcnt(4)
	v_mfma_f32_32x32x16_bf16 v[48:63], v[242:245], v[190:193], v[48:63]
	ds_read_b128 v[242:245], v0 offset:4096
	s_waitcnt lgkmcnt(4)
	v_mfma_f32_32x32x16_bf16 v[32:47], v[246:249], v[190:193], v[32:47]
	ds_read_b128 v[246:249], v0 offset:8192
	s_waitcnt lgkmcnt(4)
	v_mfma_f32_32x32x16_bf16 v[16:31], v[250:253], v[190:193], v[16:31]
	ds_read_b128 v[250:253], v0 offset:12288
	ds_read_b128 v[190:193], v234 offset:32768
	s_waitcnt lgkmcnt(4)
	v_mfma_f32_32x32x16_bf16 v[128:143], v[238:241], v[180:183], v[128:143]
	ds_read_b128 v[238:241], v184
	s_waitcnt lgkmcnt(4)
	v_mfma_f32_32x32x16_bf16 v[48:63], v[242:245], v[180:183], v[48:63]
	ds_read_b128 v[242:245], v184 offset:4096
	s_waitcnt lgkmcnt(4)
	v_mfma_f32_32x32x16_bf16 v[32:47], v[246:249], v[180:183], v[32:47]
	ds_read_b128 v[246:249], v184 offset:8192
	s_waitcnt lgkmcnt(4)
	v_mfma_f32_32x32x16_bf16 v[16:31], v[250:253], v[180:183], v[16:31]
	ds_read_b128 v[250:253], v184 offset:12288
	s_waitcnt lgkmcnt(3)
	v_mfma_f32_32x32x16_bf16 v[128:143], v[238:241], v[190:193], v[128:143]
	s_waitcnt lgkmcnt(2)
	v_mfma_f32_32x32x16_bf16 v[48:63], v[242:245], v[190:193], v[48:63]
	s_waitcnt lgkmcnt(1)
	v_mfma_f32_32x32x16_bf16 v[32:47], v[246:249], v[190:193], v[32:47]
	s_waitcnt lgkmcnt(0)
	v_mfma_f32_32x32x16_bf16 v[16:31], v[250:253], v[190:193], v[16:31]
	s_waitcnt vmcnt(6)
	s_barrier
	v_add_u32_e32 v195, 0xc000, v186
	ds_read_b128 v[180:183], v195 offset:32768
	v_add_u32_e32 v194, 0xc000, v14
	ds_read_b128 v[238:241], v194
	ds_read_b128 v[242:245], v194 offset:4096
	ds_read_b128 v[246:249], v194 offset:8192
	ds_read_b128 v[250:253], v194 offset:12288
	s_add_u32 m0, s33, 0x0
	v_lshl_add_u64 v[2:3], v[2:3], 0, s[84:85]
	global_load_lds_dwordx4 v[2:3], off
	s_add_u32 m0, s33, 0x2000
	v_lshl_add_u64 v[6:7], v[6:7], 0, s[84:85]
	global_load_lds_dwordx4 v[6:7], off
	s_add_u32 m0, s33, 0x4000
	v_lshl_add_u64 v[8:9], v[8:9], 0, s[84:85]
	global_load_lds_dwordx4 v[8:9], off
	s_add_u32 m0, s33, 0x6000
	v_lshl_add_u64 v[10:11], v[10:11], 0, s[84:85]
	global_load_lds_dwordx4 v[10:11], off
	s_add_u32 m0, s33, 0x8000
	v_lshl_add_u64 v[4:5], v[4:5], 0, s[84:85]
	global_load_lds_dwordx4 v[4:5], off
	s_add_u32 m0, s33, 0xa000
	v_lshl_add_u64 v[12:13], v[12:13], 0, s[84:85]
	global_load_lds_dwordx4 v[12:13], off
	v_add_u32_e32 v195, 0xc000, v189
	ds_read_b128 v[190:193], v195 offset:32768
	v_add_u32_e32 v194, 0xc000, v15
	s_waitcnt lgkmcnt(4)
	v_mfma_f32_32x32x16_bf16 v[128:143], v[238:241], v[180:183], v[128:143]
	ds_read_b128 v[238:241], v194
	s_waitcnt lgkmcnt(4)
	v_mfma_f32_32x32x16_bf16 v[48:63], v[242:245], v[180:183], v[48:63]
	ds_read_b128 v[242:245], v194 offset:4096
	s_waitcnt lgkmcnt(4)
	v_mfma_f32_32x32x16_bf16 v[32:47], v[246:249], v[180:183], v[32:47]
	ds_read_b128 v[246:249], v194 offset:8192
	s_waitcnt lgkmcnt(4)
	v_mfma_f32_32x32x16_bf16 v[16:31], v[250:253], v[180:183], v[16:31]
	ds_read_b128 v[250:253], v194 offset:12288
	v_add_u32_e32 v195, 0xc000, v233
	ds_read_b128 v[180:183], v195 offset:32768
	v_add_u32_e32 v194, 0xc000, v0
	s_waitcnt lgkmcnt(4)
	v_mfma_f32_32x32x16_bf16 v[128:143], v[238:241], v[190:193], v[128:143]
	ds_read_b128 v[238:241], v194
	s_waitcnt lgkmcnt(4)
	v_mfma_f32_32x32x16_bf16 v[48:63], v[242:245], v[190:193], v[48:63]
	ds_read_b128 v[242:245], v194 offset:4096
	s_waitcnt lgkmcnt(4)
	v_mfma_f32_32x32x16_bf16 v[32:47], v[246:249], v[190:193], v[32:47]
	ds_read_b128 v[246:249], v194 offset:8192
	s_waitcnt lgkmcnt(4)
	v_mfma_f32_32x32x16_bf16 v[16:31], v[250:253], v[190:193], v[16:31]
	ds_read_b128 v[250:253], v194 offset:12288
	v_add_u32_e32 v195, 0xc000, v234
	ds_read_b128 v[190:193], v195 offset:32768
	v_add_u32_e32 v194, 0xc000, v184
	s_waitcnt lgkmcnt(4)
	v_mfma_f32_32x32x16_bf16 v[128:143], v[238:241], v[180:183], v[128:143]
	ds_read_b128 v[238:241], v194
	s_waitcnt lgkmcnt(4)
	v_mfma_f32_32x32x16_bf16 v[48:63], v[242:245], v[180:183], v[48:63]
	ds_read_b128 v[242:245], v194 offset:4096
	s_waitcnt lgkmcnt(4)
	v_mfma_f32_32x32x16_bf16 v[32:47], v[246:249], v[180:183], v[32:47]
	ds_read_b128 v[246:249], v194 offset:8192
	s_waitcnt lgkmcnt(4)
	v_mfma_f32_32x32x16_bf16 v[16:31], v[250:253], v[180:183], v[16:31]
	ds_read_b128 v[250:253], v194 offset:12288
	s_waitcnt lgkmcnt(3)
	v_mfma_f32_32x32x16_bf16 v[128:143], v[238:241], v[190:193], v[128:143]
	s_waitcnt lgkmcnt(2)
	v_mfma_f32_32x32x16_bf16 v[48:63], v[242:245], v[190:193], v[48:63]
	s_waitcnt lgkmcnt(1)
	v_mfma_f32_32x32x16_bf16 v[32:47], v[246:249], v[190:193], v[32:47]
	s_waitcnt lgkmcnt(0)
	v_mfma_f32_32x32x16_bf16 v[16:31], v[250:253], v[190:193], v[16:31]
	s_waitcnt vmcnt(6)
	s_barrier
; DI f32x16 mfma(bf16x8 a, bf16x8 b, f32x16 c) { return __builtin_amdgcn_mfma_f32_32x32x16_bf16(a, b, c, 0, 0, 0); }
;     ...
;   for (int kt = 0; kt < nk; ++kt) {
;     const char* cur = lds + (kt & 1) * DBUF;
;     if (kt + 1 < nk) DMA_ISSUE((kt + 1) & 1, kt + 1)
; #pragma unroll(NTB == 1 ? 2 : 4)
;     for (int s = 0; s < 4; ++s) {
;       const int ro = ((2 * s + hh) ^ xr) * 16;
;       bf16x8 bfr[NTB];
; #pragma unroll
;       for (int tb = 0; tb < NTB; ++tb) bfr[tb] = *(const bf16x8*)(cur + bbase + tb * 32 * DROW + ro);
; #pragma unroll
;       for (int fb = 0; fb < NFB; ++fb) {
;         const bf16x8 afr = *(const bf16x8*)(cur + abase + fb * 32 * DROW + ro);
; #pragma unroll
;         for (int tb = 0; tb < NTB; ++tb) acc[tb * NFB + fb] = mfma(afr, bfr[tb], acc[tb * NFB + fb]);
;       }
;     }
;     asm volatile("s_waitcnt vmcnt(0) lgkmcnt(0)" ::: "memory");
;     __builtin_amdgcn_s_barrier();
	v_add_u32_e32 v195, 0x18000, v186
	ds_read_b128 v[180:183], v195 offset:32768
	v_add_u32_e32 v194, 0x18000, v14
	ds_read_b128 v[238:241], v194
	ds_read_b128 v[242:245], v194 offset:4096
	ds_read_b128 v[246:249], v194 offset:8192
	ds_read_b128 v[250:253], v194 offset:12288
	s_add_u32 m0, s33, 0xc000
	v_lshl_add_u64 v[2:3], v[2:3], 0, s[84:85]
	global_load_lds_dwordx4 v[2:3], off
	s_add_u32 m0, s33, 0xe000
	v_lshl_add_u64 v[6:7], v[6:7], 0, s[84:85]
	global_load_lds_dwordx4 v[6:7], off
	s_add_u32 m0, s33, 0x10000
	v_lshl_add_u64 v[8:9], v[8:9], 0, s[84:85]
	global_load_lds_dwordx4 v[8:9], off
	s_add_u32 m0, s33, 0x12000
	v_lshl_add_u64 v[10:11], v[10:11], 0, s[84:85]
	global_load_lds_dwordx4 v[10:11], off
	s_add_u32 m0, s33, 0x14000
	v_lshl_add_u64 v[4:5], v[4:5], 0, s[84:85]
	global_load_lds_dwordx4 v[4:5], off
	s_add_u32 m0, s33, 0x16000
	v_lshl_add_u64 v[12:13], v[12:13], 0, s[84:85]
	global_load_lds_dwordx4 v[12:13], off
	v_add_u32_e32 v195, 0x18000, v189
	ds_read_b128 v[190:193], v195 offset:32768
	v_add_u32_e32 v194, 0x18000, v15
	s_waitcnt lgkmcnt(4)
	v_mfma_f32_32x32x16_bf16 v[128:143], v[238:241], v[180:183], v[128:143]
	ds_read_b128 v[238:241], v194
	s_waitcnt lgkmcnt(4)
	v_mfma_f32_32x32x16_bf16 v[48:63], v[242:245], v[180:183], v[48:63]
	ds_read_b128 v[242:245], v194 offset:4096
	s_waitcnt lgkmcnt(4)
	v_mfma_f32_32x32x16_bf16 v[32:47], v[246:249], v[180:183], v[32:47]
	ds_read_b128 v[246:249], v194 offset:8192
	s_waitcnt lgkmcnt(4)
	v_mfma_f32_32x32x16_bf16 v[16:31], v[250:253], v[180:183], v[16:31]
	ds_read_b128 v[250:253], v194 offset:12288
	v_add_u32_e32 v195, 0x18000, v233
	ds_read_b128 v[180:183], v195 offset:32768
	v_add_u32_e32 v194, 0x18000, v0
	s_waitcnt lgkmcnt(4)
	v_mfma_f32_32x32x16_bf16 v[128:143], v[238:241], v[190:193], v[128:143]
	ds_read_b128 v[238:241], v194
	s_waitcnt lgkmcnt(4)
	v_mfma_f32_32x32x16_bf16 v[48:63], v[242:245], v[190:193], v[48:63]
	ds_read_b128 v[242:245], v194 offset:4096
	s_waitcnt lgkmcnt(4)
	v_mfma_f32_32x32x16_bf16 v[32:47], v[246:249], v[190:193], v[32:47]
	ds_read_b128 v[246:249], v194 offset:8192
	s_waitcnt lgkmcnt(4)
	v_mfma_f32_32x32x16_bf16 v[16:31], v[250:253], v[190:193], v[16:31]
	ds_read_b128 v[250:253], v194 offset:12288
	v_add_u32_e32 v195, 0x18000, v234
	ds_read_b128 v[190:193], v195 offset:32768
	v_add_u32_e32 v194, 0x18000, v184
	s_waitcnt lgkmcnt(4)
	v_mfma_f32_32x32x16_bf16 v[128:143], v[238:241], v[180:183], v[128:143]
	ds_read_b128 v[238:241], v194
	s_waitcnt lgkmcnt(4)
	v_mfma_f32_32x32x16_bf16 v[48:63], v[242:245], v[180:183], v[48:63]
	ds_read_b128 v[242:245], v194 offset:4096
	s_waitcnt lgkmcnt(4)
	v_mfma_f32_32x32x16_bf16 v[32:47], v[246:249], v[180:183], v[32:47]
	ds_read_b128 v[246:249], v194 offset:8192
	s_waitcnt lgkmcnt(4)
	v_mfma_f32_32x32x16_bf16 v[16:31], v[250:253], v[180:183], v[16:31]
	ds_read_b128 v[250:253], v194 offset:12288
	s_waitcnt lgkmcnt(3)
	v_mfma_f32_32x32x16_bf16 v[128:143], v[238:241], v[190:193], v[128:143]
	s_waitcnt lgkmcnt(2)
	v_mfma_f32_32x32x16_bf16 v[48:63], v[242:245], v[190:193], v[48:63]
	s_waitcnt lgkmcnt(1)
	v_mfma_f32_32x32x16_bf16 v[32:47], v[246:249], v[190:193], v[32:47]
	s_waitcnt lgkmcnt(0)
	v_mfma_f32_32x32x16_bf16 v[16:31], v[250:253], v[190:193], v[16:31]
	s_waitcnt vmcnt(6)
	s_barrier
	ds_read_b128 v[180:183], v186 offset:32768
	ds_read_b128 v[238:241], v14
	ds_read_b128 v[242:245], v14 offset:4096
	ds_read_b128 v[246:249], v14 offset:8192
	ds_read_b128 v[250:253], v14 offset:12288
	s_add_u32 m0, s33, 0x18000
	v_lshl_add_u64 v[2:3], v[2:3], 0, s[84:85]
	global_load_lds_dwordx4 v[2:3], off
	s_add_u32 m0, s33, 0x1a000
	v_lshl_add_u64 v[6:7], v[6:7], 0, s[84:85]
	global_load_lds_dwordx4 v[6:7], off
	s_add_u32 m0, s33, 0x1c000
	v_lshl_add_u64 v[8:9], v[8:9], 0, s[84:85]
	global_load_lds_dwordx4 v[8:9], off
	s_add_u32 m0, s33, 0x1e000
	v_lshl_add_u64 v[10:11], v[10:11], 0, s[84:85]
	global_load_lds_dwordx4 v[10:11], off
	s_add_u32 m0, s33, 0x20000
	v_lshl_add_u64 v[4:5], v[4:5], 0, s[84:85]
	global_load_lds_dwordx4 v[4:5], off
	s_add_u32 m0, s33, 0x22000
	v_lshl_add_u64 v[12:13], v[12:13], 0, s[84:85]
	global_load_lds_dwordx4 v[12:13], off
	ds_read_b128 v[190:193], v189 offset:32768
	s_waitcnt lgkmcnt(4)
	v_mfma_f32_32x32x16_bf16 v[128:143], v[238:241], v[180:183], v[128:143]
	ds_read_b128 v[238:241], v15
	s_waitcnt lgkmcnt(4)
	v_mfma_f32_32x32x16_bf16 v[48:63], v[242:245], v[180:183], v[48:63]
	ds_read_b128 v[242:245], v15 offset:4096
	s_waitcnt lgkmcnt(4)
	v_mfma_f32_32x32x16_bf16 v[32:47], v[246:249], v[180:183], v[32:47]
	ds_read_b128 v[246:249], v15 offset:8192
	s_waitcnt lgkmcnt(4)
	v_mfma_f32_32x32x16_bf16 v[16:31], v[250:253], v[180:183], v[16:31]
	ds_read_b128 v[250:253], v15 offset:12288
	ds_read_b128 v[180:183], v233 offset:32768
	s_waitcnt lgkmcnt(4)
	v_mfma_f32_32x32x16_bf16 v[128:143], v[238:241], v[190:193], v[128:143]
	ds_read_b128 v[238:241], v0
	s_waitcnt lgkmcnt(4)
	v_mfma_f32_32x32x16_bf16 v[48:63], v[242:245], v[190:193], v[48:63]
	ds_read_b128 v[242:245], v0 offset:4096
	s_waitcnt lgkmcnt(4)
	v_mfma_f32_32x32x16_bf16 v[32:47], v[246:249], v[190:193], v[32:47]
	ds_read_b128 v[246:249], v0 offset:8192
	s_waitcnt lgkmcnt(4)
	v_mfma_f32_32x32x16_bf16 v[16:31], v[250:253], v[190:193], v[16:31]
	ds_read_b128 v[250:253], v0 offset:12288
	ds_read_b128 v[190:193], v234 offset:32768
	s_waitcnt lgkmcnt(4)
	v_mfma_f32_32x32x16_bf16 v[128:143], v[238:241], v[180:183], v[128:143]
	ds_read_b128 v[238:241], v184
	s_waitcnt lgkmcnt(4)
	v_mfma_f32_32x32x16_bf16 v[48:63], v[242:245], v[180:183], v[48:63]
	ds_read_b128 v[242:245], v184 offset:4096
	s_waitcnt lgkmcnt(4)
	v_mfma_f32_32x32x16_bf16 v[32:47], v[246:249], v[180:183], v[32:47]
	ds_read_b128 v[246:249], v184 offset:8192
	s_waitcnt lgkmcnt(4)
	v_mfma_f32_32x32x16_bf16 v[16:31], v[250:253], v[180:183], v[16:31]
	ds_read_b128 v[250:253], v184 offset:12288
	s_waitcnt lgkmcnt(3)
	v_mfma_f32_32x32x16_bf16 v[128:143], v[238:241], v[190:193], v[128:143]
	s_waitcnt lgkmcnt(2)
	v_mfma_f32_32x32x16_bf16 v[48:63], v[242:245], v[190:193], v[48:63]
	s_waitcnt lgkmcnt(1)
	v_mfma_f32_32x32x16_bf16 v[32:47], v[246:249], v[190:193], v[32:47]
	s_waitcnt lgkmcnt(0)
	v_mfma_f32_32x32x16_bf16 v[16:31], v[250:253], v[190:193], v[16:31]
	s_waitcnt vmcnt(6)
	s_barrier
; DI f32x16 mfma(bf16x8 a, bf16x8 b, f32x16 c) { return __builtin_amdgcn_mfma_f32_32x32x16_bf16(a, b, c, 0, 0, 0); }
;     ...
;   for (int kt = 0; kt < nk; ++kt) {
;     const char* cur = lds + (kt & 1) * DBUF;
;     if (kt + 1 < nk) DMA_ISSUE((kt + 1) & 1, kt + 1)
; #pragma unroll(NTB == 1 ? 2 : 4)
;     for (int s = 0; s < 4; ++s) {
;       const int ro = ((2 * s + hh) ^ xr) * 16;
;       bf16x8 bfr[NTB];
; #pragma unroll
;       for (int tb = 0; tb < NTB; ++tb) bfr[tb] = *(const bf16x8*)(cur + bbase + tb * 32 * DROW + ro);
; #pragma unroll
;       for (int fb = 0; fb < NFB; ++fb) {
;         const bf16x8 afr = *(const bf16x8*)(cur + abase + fb * 32 * DROW + ro);
; #pragma unroll
;         for (int tb = 0; tb < NTB; ++tb) acc[tb * NFB + fb] = mfma(afr, bfr[tb], acc[tb * NFB + fb]);
;       }
;     }
;     asm volatile("s_waitcnt vmcnt(0) lgkmcnt(0)" ::: "memory");
;     __builtin_amdgcn_s_barrier();
	v_add_u32_e32 v195, 0xc000, v186
	ds_read_b128 v[180:183], v195 offset:32768
	v_add_u32_e32 v194, 0xc000, v14
	ds_read_b128 v[238:241], v194
	ds_read_b128 v[242:245], v194 offset:4096
	ds_read_b128 v[246:249], v194 offset:8192
	ds_read_b128 v[250:253], v194 offset:12288
	s_add_u32 m0, s33, 0x0
	v_lshl_add_u64 v[2:3], v[2:3], 0, s[84:85]
	global_load_lds_dwordx4 v[2:3], off
	s_add_u32 m0, s33, 0x2000
	v_lshl_add_u64 v[6:7], v[6:7], 0, s[84:85]
	global_load_lds_dwordx4 v[6:7], off
	s_add_u32 m0, s33, 0x4000
	v_lshl_add_u64 v[8:9], v[8:9], 0, s[84:85]
	global_load_lds_dwordx4 v[8:9], off
	s_add_u32 m0, s33, 0x6000
	v_lshl_add_u64 v[10:11], v[10:11], 0, s[84:85]
	global_load_lds_dwordx4 v[10:11], off
	s_add_u32 m0, s33, 0x8000
	v_lshl_add_u64 v[4:5], v[4:5], 0, s[84:85]
	global_load_lds_dwordx4 v[4:5], off
	s_add_u32 m0, s33, 0xa000
	v_lshl_add_u64 v[12:13], v[12:13], 0, s[84:85]
	global_load_lds_dwordx4 v[12:13], off
	v_add_u32_e32 v195, 0xc000, v189
	ds_read_b128 v[190:193], v195 offset:32768
	v_add_u32_e32 v194, 0xc000, v15
	s_waitcnt lgkmcnt(4)
	v_mfma_f32_32x32x16_bf16 v[128:143], v[238:241], v[180:183], v[128:143]
	ds_read_b128 v[238:241], v194
	s_waitcnt lgkmcnt(4)
	v_mfma_f32_32x32x16_bf16 v[48:63], v[242:245], v[180:183], v[48:63]
	ds_read_b128 v[242:245], v194 offset:4096
	s_waitcnt lgkmcnt(4)
	v_mfma_f32_32x32x16_bf16 v[32:47], v[246:249], v[180:183], v[32:47]
	ds_read_b128 v[246:249], v194 offset:8192
	s_waitcnt lgkmcnt(4)
	v_mfma_f32_32x32x16_bf16 v[16:31], v[250:253], v[180:183], v[16:31]
	ds_read_b128 v[250:253], v194 offset:12288
	v_add_u32_e32 v195, 0xc000, v233
	ds_read_b128 v[180:183], v195 offset:32768
	v_add_u32_e32 v194, 0xc000, v0
	s_waitcnt lgkmcnt(4)
	v_mfma_f32_32x32x16_bf16 v[128:143], v[238:241], v[190:193], v[128:143]
	ds_read_b128 v[238:241], v194
	s_waitcnt lgkmcnt(4)
	v_mfma_f32_32x32x16_bf16 v[48:63], v[242:245], v[190:193], v[48:63]
	ds_read_b128 v[242:245], v194 offset:4096
	s_waitcnt lgkmcnt(4)
	v_mfma_f32_32x32x16_bf16 v[32:47], v[246:249], v[190:193], v[32:47]
	ds_read_b128 v[246:249], v194 offset:8192
	s_waitcnt lgkmcnt(4)
	v_mfma_f32_32x32x16_bf16 v[16:31], v[250:253], v[190:193], v[16:31]
	ds_read_b128 v[250:253], v194 offset:12288
	v_add_u32_e32 v195, 0xc000, v234
	ds_read_b128 v[190:193], v195 offset:32768
	v_add_u32_e32 v194, 0xc000, v184
	s_waitcnt lgkmcnt(4)
	v_mfma_f32_32x32x16_bf16 v[128:143], v[238:241], v[180:183], v[128:143]
	ds_read_b128 v[238:241], v194
	s_waitcnt lgkmcnt(4)
	v_mfma_f32_32x32x16_bf16 v[48:63], v[242:245], v[180:183], v[48:63]
	ds_read_b128 v[242:245], v194 offset:4096
	s_waitcnt lgkmcnt(4)
	v_mfma_f32_32x32x16_bf16 v[32:47], v[246:249], v[180:183], v[32:47]
	ds_read_b128 v[246:249], v194 offset:8192
	s_waitcnt lgkmcnt(4)
	v_mfma_f32_32x32x16_bf16 v[16:31], v[250:253], v[180:183], v[16:31]
	ds_read_b128 v[250:253], v194 offset:12288
	s_waitcnt lgkmcnt(3)
	v_mfma_f32_32x32x16_bf16 v[128:143], v[238:241], v[190:193], v[128:143]
	s_waitcnt lgkmcnt(2)
	v_mfma_f32_32x32x16_bf16 v[48:63], v[242:245], v[190:193], v[48:63]
	s_waitcnt lgkmcnt(1)
	v_mfma_f32_32x32x16_bf16 v[32:47], v[246:249], v[190:193], v[32:47]
	s_waitcnt lgkmcnt(0)
	v_mfma_f32_32x32x16_bf16 v[16:31], v[250:253], v[190:193], v[16:31]
	s_waitcnt vmcnt(6)
	s_barrier
	v_add_u32_e32 v195, 0x18000, v186
	ds_read_b128 v[180:183], v195 offset:32768
	v_add_u32_e32 v194, 0x18000, v14
	ds_read_b128 v[238:241], v194
	ds_read_b128 v[242:245], v194 offset:4096
	ds_read_b128 v[246:249], v194 offset:8192
	ds_read_b128 v[250:253], v194 offset:12288
	s_add_u32 m0, s33, 0xc000
	v_lshl_add_u64 v[2:3], v[2:3], 0, s[84:85]
	global_load_lds_dwordx4 v[2:3], off
	s_add_u32 m0, s33, 0xe000
	v_lshl_add_u64 v[6:7], v[6:7], 0, s[84:85]
	global_load_lds_dwordx4 v[6:7], off
	s_add_u32 m0, s33, 0x10000
	v_lshl_add_u64 v[8:9], v[8:9], 0, s[84:85]
	global_load_lds_dwordx4 v[8:9], off
	s_add_u32 m0, s33, 0x12000
	v_lshl_add_u64 v[10:11], v[10:11], 0, s[84:85]
	global_load_lds_dwordx4 v[10:11], off
	s_add_u32 m0, s33, 0x14000
	v_lshl_add_u64 v[4:5], v[4:5], 0, s[84:85]
	global_load_lds_dwordx4 v[4:5], off
	s_add_u32 m0, s33, 0x16000
	v_lshl_add_u64 v[12:13], v[12:13], 0, s[84:85]
	global_load_lds_dwordx4 v[12:13], off
	v_add_u32_e32 v195, 0x18000, v189
	ds_read_b128 v[190:193], v195 offset:32768
	v_add_u32_e32 v194, 0x18000, v15
	s_waitcnt lgkmcnt(4)
	v_mfma_f32_32x32x16_bf16 v[128:143], v[238:241], v[180:183], v[128:143]
	ds_read_b128 v[238:241], v194
	s_waitcnt lgkmcnt(4)
	v_mfma_f32_32x32x16_bf16 v[48:63], v[242:245], v[180:183], v[48:63]
	ds_read_b128 v[242:245], v194 offset:4096
	s_waitcnt lgkmcnt(4)
	v_mfma_f32_32x32x16_bf16 v[32:47], v[246:249], v[180:183], v[32:47]
	ds_read_b128 v[246:249], v194 offset:8192
	s_waitcnt lgkmcnt(4)
	v_mfma_f32_32x32x16_bf16 v[16:31], v[250:253], v[180:183], v[16:31]
	ds_read_b128 v[250:253], v194 offset:12288
	v_add_u32_e32 v195, 0x18000, v233
	ds_read_b128 v[180:183], v195 offset:32768
	v_add_u32_e32 v194, 0x18000, v0
	s_waitcnt lgkmcnt(4)
	v_mfma_f32_32x32x16_bf16 v[128:143], v[238:241], v[190:193], v[128:143]
	ds_read_b128 v[238:241], v194
	s_waitcnt lgkmcnt(4)
	v_mfma_f32_32x32x16_bf16 v[48:63], v[242:245], v[190:193], v[48:63]
	ds_read_b128 v[242:245], v194 offset:4096
	s_waitcnt lgkmcnt(4)
	v_mfma_f32_32x32x16_bf16 v[32:47], v[246:249], v[190:193], v[32:47]
	ds_read_b128 v[246:249], v194 offset:8192
	s_waitcnt lgkmcnt(4)
	v_mfma_f32_32x32x16_bf16 v[16:31], v[250:253], v[190:193], v[16:31]
	ds_read_b128 v[250:253], v194 offset:12288
	v_add_u32_e32 v195, 0x18000, v234
	ds_read_b128 v[190:193], v195 offset:32768
	v_add_u32_e32 v194, 0x18000, v184
	s_waitcnt lgkmcnt(4)
	v_mfma_f32_32x32x16_bf16 v[128:143], v[238:241], v[180:183], v[128:143]
	ds_read_b128 v[238:241], v194
	s_waitcnt lgkmcnt(4)
	v_mfma_f32_32x32x16_bf16 v[48:63], v[242:245], v[180:183], v[48:63]
	ds_read_b128 v[242:245], v194 offset:4096
	s_waitcnt lgkmcnt(4)
	v_mfma_f32_32x32x16_bf16 v[32:47], v[246:249], v[180:183], v[32:47]
	ds_read_b128 v[246:249], v194 offset:8192
	s_waitcnt lgkmcnt(4)
	v_mfma_f32_32x32x16_bf16 v[16:31], v[250:253], v[180:183], v[16:31]
	ds_read_b128 v[250:253], v194 offset:12288
	s_waitcnt lgkmcnt(3)
	v_mfma_f32_32x32x16_bf16 v[128:143], v[238:241], v[190:193], v[128:143]
	s_waitcnt lgkmcnt(2)
	v_mfma_f32_32x32x16_bf16 v[48:63], v[242:245], v[190:193], v[48:63]
	s_waitcnt lgkmcnt(1)
	v_mfma_f32_32x32x16_bf16 v[32:47], v[246:249], v[190:193], v[32:47]
	s_waitcnt lgkmcnt(0)
	v_mfma_f32_32x32x16_bf16 v[16:31], v[250:253], v[190:193], v[16:31]
	s_waitcnt vmcnt(6)
	s_barrier
; DI f32x16 mfma(bf16x8 a, bf16x8 b, f32x16 c) { return __builtin_amdgcn_mfma_f32_32x32x16_bf16(a, b, c, 0, 0, 0); }
;     ...
;   for (int kt = 0; kt < nk; ++kt) {
;     const char* cur = lds + (kt & 1) * DBUF;
;     if (kt + 1 < nk) DMA_ISSUE((kt + 1) & 1, kt + 1)
; #pragma unroll(NTB == 1 ? 2 : 4)
;     for (int s = 0; s < 4; ++s) {
;       const int ro = ((2 * s + hh) ^ xr) * 16;
;       bf16x8 bfr[NTB];
; #pragma unroll
;       for (int tb = 0; tb < NTB; ++tb) bfr[tb] = *(const bf16x8*)(cur + bbase + tb * 32 * DROW + ro);
; #pragma unroll
;       for (int fb = 0; fb < NFB; ++fb) {
;         const bf16x8 afr = *(const bf16x8*)(cur + abase + fb * 32 * DROW + ro);
; #pragma unroll
;         for (int tb = 0; tb < NTB; ++tb) acc[tb * NFB + fb] = mfma(afr, bfr[tb], acc[tb * NFB + fb]);
;       }
;     }
;     asm volatile("s_waitcnt vmcnt(0) lgkmcnt(0)" ::: "memory");
;     __builtin_amdgcn_s_barrier();
	ds_read_b128 v[180:183], v186 offset:32768
	ds_read_b128 v[238:241], v14
	ds_read_b128 v[242:245], v14 offset:4096
	ds_read_b128 v[246:249], v14 offset:8192
	ds_read_b128 v[250:253], v14 offset:12288
	s_add_u32 m0, s33, 0x18000
	v_lshl_add_u64 v[2:3], v[2:3], 0, s[84:85]
	global_load_lds_dwordx4 v[2:3], off
	s_add_u32 m0, s33, 0x1a000
	v_lshl_add_u64 v[6:7], v[6:7], 0, s[84:85]
	global_load_lds_dwordx4 v[6:7], off
	s_add_u32 m0, s33, 0x1c000
	v_lshl_add_u64 v[8:9], v[8:9], 0, s[84:85]
	global_load_lds_dwordx4 v[8:9], off
	s_add_u32 m0, s33, 0x1e000
	v_lshl_add_u64 v[10:11], v[10:11], 0, s[84:85]
	global_load_lds_dwordx4 v[10:11], off
	s_add_u32 m0, s33, 0x20000
	v_lshl_add_u64 v[4:5], v[4:5], 0, s[84:85]
	global_load_lds_dwordx4 v[4:5], off
	s_add_u32 m0, s33, 0x22000
	v_lshl_add_u64 v[12:13], v[12:13], 0, s[84:85]
	global_load_lds_dwordx4 v[12:13], off
	ds_read_b128 v[190:193], v189 offset:32768
	s_waitcnt lgkmcnt(4)
	v_mfma_f32_32x32x16_bf16 v[128:143], v[238:241], v[180:183], v[128:143]
	ds_read_b128 v[238:241], v15
	s_waitcnt lgkmcnt(4)
	v_mfma_f32_32x32x16_bf16 v[48:63], v[242:245], v[180:183], v[48:63]
	ds_read_b128 v[242:245], v15 offset:4096
	s_waitcnt lgkmcnt(4)
	v_mfma_f32_32x32x16_bf16 v[32:47], v[246:249], v[180:183], v[32:47]
	ds_read_b128 v[246:249], v15 offset:8192
	s_waitcnt lgkmcnt(4)
	v_mfma_f32_32x32x16_bf16 v[16:31], v[250:253], v[180:183], v[16:31]
	ds_read_b128 v[250:253], v15 offset:12288
	ds_read_b128 v[180:183], v233 offset:32768
	s_waitcnt lgkmcnt(4)
	v_mfma_f32_32x32x16_bf16 v[128:143], v[238:241], v[190:193], v[128:143]
	ds_read_b128 v[238:241], v0
	s_waitcnt lgkmcnt(4)
	v_mfma_f32_32x32x16_bf16 v[48:63], v[242:245], v[190:193], v[48:63]
	ds_read_b128 v[242:245], v0 offset:4096
	s_waitcnt lgkmcnt(4)
	v_mfma_f32_32x32x16_bf16 v[32:47], v[246:249], v[190:193], v[32:47]
	ds_read_b128 v[246:249], v0 offset:8192
	s_waitcnt lgkmcnt(4)
	v_mfma_f32_32x32x16_bf16 v[16:31], v[250:253], v[190:193], v[16:31]
	ds_read_b128 v[250:253], v0 offset:12288
	ds_read_b128 v[190:193], v234 offset:32768
	s_waitcnt lgkmcnt(4)
	v_mfma_f32_32x32x16_bf16 v[128:143], v[238:241], v[180:183], v[128:143]
	ds_read_b128 v[238:241], v184
	s_waitcnt lgkmcnt(4)
	v_mfma_f32_32x32x16_bf16 v[48:63], v[242:245], v[180:183], v[48:63]
	ds_read_b128 v[242:245], v184 offset:4096
	s_waitcnt lgkmcnt(4)
	v_mfma_f32_32x32x16_bf16 v[32:47], v[246:249], v[180:183], v[32:47]
	ds_read_b128 v[246:249], v184 offset:8192
	s_waitcnt lgkmcnt(4)
	v_mfma_f32_32x32x16_bf16 v[16:31], v[250:253], v[180:183], v[16:31]
	ds_read_b128 v[250:253], v184 offset:12288
	s_waitcnt lgkmcnt(3)
	v_mfma_f32_32x32x16_bf16 v[128:143], v[238:241], v[190:193], v[128:143]
	s_waitcnt lgkmcnt(2)
	v_mfma_f32_32x32x16_bf16 v[48:63], v[242:245], v[190:193], v[48:63]
	s_waitcnt lgkmcnt(1)
	v_mfma_f32_32x32x16_bf16 v[32:47], v[246:249], v[190:193], v[32:47]
	s_waitcnt lgkmcnt(0)
	v_mfma_f32_32x32x16_bf16 v[16:31], v[250:253], v[190:193], v[16:31]
	s_waitcnt vmcnt(6)
	s_barrier
	v_add_u32_e32 v195, 0xc000, v186
	ds_read_b128 v[180:183], v195 offset:32768
	v_add_u32_e32 v194, 0xc000, v14
	ds_read_b128 v[238:241], v194
	ds_read_b128 v[242:245], v194 offset:4096
	ds_read_b128 v[246:249], v194 offset:8192
	ds_read_b128 v[250:253], v194 offset:12288
	s_add_u32 m0, s33, 0x0
	v_lshl_add_u64 v[2:3], v[2:3], 0, s[84:85]
	global_load_lds_dwordx4 v[2:3], off
	s_add_u32 m0, s33, 0x2000
	v_lshl_add_u64 v[6:7], v[6:7], 0, s[84:85]
	global_load_lds_dwordx4 v[6:7], off
	s_add_u32 m0, s33, 0x4000
	v_lshl_add_u64 v[8:9], v[8:9], 0, s[84:85]
	global_load_lds_dwordx4 v[8:9], off
	s_add_u32 m0, s33, 0x6000
	v_lshl_add_u64 v[10:11], v[10:11], 0, s[84:85]
	global_load_lds_dwordx4 v[10:11], off
	s_add_u32 m0, s33, 0x8000
	v_lshl_add_u64 v[4:5], v[4:5], 0, s[84:85]
	global_load_lds_dwordx4 v[4:5], off
	s_add_u32 m0, s33, 0xa000
	v_lshl_add_u64 v[12:13], v[12:13], 0, s[84:85]
	global_load_lds_dwordx4 v[12:13], off
	v_add_u32_e32 v195, 0xc000, v189
	ds_read_b128 v[190:193], v195 offset:32768
	v_add_u32_e32 v194, 0xc000, v15
	s_waitcnt lgkmcnt(4)
	v_mfma_f32_32x32x16_bf16 v[128:143], v[238:241], v[180:183], v[128:143]
	ds_read_b128 v[238:241], v194
	s_waitcnt lgkmcnt(4)
	v_mfma_f32_32x32x16_bf16 v[48:63], v[242:245], v[180:183], v[48:63]
	ds_read_b128 v[242:245], v194 offset:4096
	s_waitcnt lgkmcnt(4)
	v_mfma_f32_32x32x16_bf16 v[32:47], v[246:249], v[180:183], v[32:47]
	ds_read_b128 v[246:249], v194 offset:8192
	s_waitcnt lgkmcnt(4)
	v_mfma_f32_32x32x16_bf16 v[16:31], v[250:253], v[180:183], v[16:31]
	ds_read_b128 v[250:253], v194 offset:12288
	v_add_u32_e32 v195, 0xc000, v233
	ds_read_b128 v[180:183], v195 offset:32768
	v_add_u32_e32 v194, 0xc000, v0
	s_waitcnt lgkmcnt(4)
	v_mfma_f32_32x32x16_bf16 v[128:143], v[238:241], v[190:193], v[128:143]
	ds_read_b128 v[238:241], v194
	s_waitcnt lgkmcnt(4)
	v_mfma_f32_32x32x16_bf16 v[48:63], v[242:245], v[190:193], v[48:63]
	ds_read_b128 v[242:245], v194 offset:4096
	s_waitcnt lgkmcnt(4)
	v_mfma_f32_32x32x16_bf16 v[32:47], v[246:249], v[190:193], v[32:47]
	ds_read_b128 v[246:249], v194 offset:8192
	s_waitcnt lgkmcnt(4)
	v_mfma_f32_32x32x16_bf16 v[16:31], v[250:253], v[190:193], v[16:31]
	ds_read_b128 v[250:253], v194 offset:12288
	v_add_u32_e32 v195, 0xc000, v234
	ds_read_b128 v[190:193], v195 offset:32768
	v_add_u32_e32 v194, 0xc000, v184
	s_waitcnt lgkmcnt(4)
	v_mfma_f32_32x32x16_bf16 v[128:143], v[238:241], v[180:183], v[128:143]
	ds_read_b128 v[238:241], v194
	s_waitcnt lgkmcnt(4)
	v_mfma_f32_32x32x16_bf16 v[48:63], v[242:245], v[180:183], v[48:63]
	ds_read_b128 v[242:245], v194 offset:4096
	s_waitcnt lgkmcnt(4)
	v_mfma_f32_32x32x16_bf16 v[32:47], v[246:249], v[180:183], v[32:47]
	ds_read_b128 v[246:249], v194 offset:8192
	s_waitcnt lgkmcnt(4)
	v_mfma_f32_32x32x16_bf16 v[16:31], v[250:253], v[180:183], v[16:31]
	ds_read_b128 v[250:253], v194 offset:12288
	s_waitcnt lgkmcnt(3)
	v_mfma_f32_32x32x16_bf16 v[128:143], v[238:241], v[190:193], v[128:143]
	s_waitcnt lgkmcnt(2)
	v_mfma_f32_32x32x16_bf16 v[48:63], v[242:245], v[190:193], v[48:63]
	s_waitcnt lgkmcnt(1)
	v_mfma_f32_32x32x16_bf16 v[32:47], v[246:249], v[190:193], v[32:47]
	s_waitcnt lgkmcnt(0)
	v_mfma_f32_32x32x16_bf16 v[16:31], v[250:253], v[190:193], v[16:31]
	s_waitcnt vmcnt(6)
	s_barrier
; DI f32x16 mfma(bf16x8 a, bf16x8 b, f32x16 c) { return __builtin_amdgcn_mfma_f32_32x32x16_bf16(a, b, c, 0, 0, 0); }
;     ...
;   for (int kt = 0; kt < nk; ++kt) {
;     const char* cur = lds + (kt & 1) * DBUF;
;     if (kt + 1 < nk) DMA_ISSUE((kt + 1) & 1, kt + 1)
; #pragma unroll(NTB == 1 ? 2 : 4)
;     for (int s = 0; s < 4; ++s) {
;       const int ro = ((2 * s + hh) ^ xr) * 16;
;       bf16x8 bfr[NTB];
; #pragma unroll
;       for (int tb = 0; tb < NTB; ++tb) bfr[tb] = *(const bf16x8*)(cur + bbase + tb * 32 * DROW + ro);
; #pragma unroll
;       for (int fb = 0; fb < NFB; ++fb) {
;         const bf16x8 afr = *(const bf16x8*)(cur + abase + fb * 32 * DROW + ro);
; #pragma unroll
;         for (int tb = 0; tb < NTB; ++tb) acc[tb * NFB + fb] = mfma(afr, bfr[tb], acc[tb * NFB + fb]);
;       }
;     }
;     asm volatile("s_waitcnt vmcnt(0) lgkmcnt(0)" ::: "memory");
;     __builtin_amdgcn_s_barrier();
	v_add_u32_e32 v195, 0x18000, v186
	ds_read_b128 v[180:183], v195 offset:32768
	v_add_u32_e32 v194, 0x18000, v14
	ds_read_b128 v[238:241], v194
	ds_read_b128 v[242:245], v194 offset:4096
	ds_read_b128 v[246:249], v194 offset:8192
	ds_read_b128 v[250:253], v194 offset:12288
	s_add_u32 m0, s33, 0xc000
	v_lshl_add_u64 v[2:3], v[2:3], 0, s[84:85]
	global_load_lds_dwordx4 v[2:3], off
	s_add_u32 m0, s33, 0xe000
	v_lshl_add_u64 v[6:7], v[6:7], 0, s[84:85]
	global_load_lds_dwordx4 v[6:7], off
	s_add_u32 m0, s33, 0x10000
	v_lshl_add_u64 v[8:9], v[8:9], 0, s[84:85]
	global_load_lds_dwordx4 v[8:9], off
	s_add_u32 m0, s33, 0x12000
	v_lshl_add_u64 v[10:11], v[10:11], 0, s[84:85]
	global_load_lds_dwordx4 v[10:11], off
	s_add_u32 m0, s33, 0x14000
	v_lshl_add_u64 v[4:5], v[4:5], 0, s[84:85]
	global_load_lds_dwordx4 v[4:5], off
	s_add_u32 m0, s33, 0x16000
	v_lshl_add_u64 v[12:13], v[12:13], 0, s[84:85]
	global_load_lds_dwordx4 v[12:13], off
	v_add_u32_e32 v195, 0x18000, v189
	ds_read_b128 v[190:193], v195 offset:32768
	v_add_u32_e32 v194, 0x18000, v15
	s_waitcnt lgkmcnt(4)
	v_mfma_f32_32x32x16_bf16 v[128:143], v[238:241], v[180:183], v[128:143]
	ds_read_b128 v[238:241], v194
	s_waitcnt lgkmcnt(4)
	v_mfma_f32_32x32x16_bf16 v[48:63], v[242:245], v[180:183], v[48:63]
	ds_read_b128 v[242:245], v194 offset:4096
	s_waitcnt lgkmcnt(4)
	v_mfma_f32_32x32x16_bf16 v[32:47], v[246:249], v[180:183], v[32:47]
	ds_read_b128 v[246:249], v194 offset:8192
	s_waitcnt lgkmcnt(4)
	v_mfma_f32_32x32x16_bf16 v[16:31], v[250:253], v[180:183], v[16:31]
	ds_read_b128 v[250:253], v194 offset:12288
	v_add_u32_e32 v195, 0x18000, v233
	ds_read_b128 v[180:183], v195 offset:32768
	v_add_u32_e32 v194, 0x18000, v0
	s_waitcnt lgkmcnt(4)
	v_mfma_f32_32x32x16_bf16 v[128:143], v[238:241], v[190:193], v[128:143]
	ds_read_b128 v[238:241], v194
	s_waitcnt lgkmcnt(4)
	v_mfma_f32_32x32x16_bf16 v[48:63], v[242:245], v[190:193], v[48:63]
	ds_read_b128 v[242:245], v194 offset:4096
	s_waitcnt lgkmcnt(4)
	v_mfma_f32_32x32x16_bf16 v[32:47], v[246:249], v[190:193], v[32:47]
	ds_read_b128 v[246:249], v194 offset:8192
	s_waitcnt lgkmcnt(4)
	v_mfma_f32_32x32x16_bf16 v[16:31], v[250:253], v[190:193], v[16:31]
	ds_read_b128 v[250:253], v194 offset:12288
	v_add_u32_e32 v195, 0x18000, v234
	ds_read_b128 v[190:193], v195 offset:32768
	v_add_u32_e32 v194, 0x18000, v184
	s_waitcnt lgkmcnt(4)
	v_mfma_f32_32x32x16_bf16 v[128:143], v[238:241], v[180:183], v[128:143]
	ds_read_b128 v[238:241], v194
	s_waitcnt lgkmcnt(4)
	v_mfma_f32_32x32x16_bf16 v[48:63], v[242:245], v[180:183], v[48:63]
	ds_read_b128 v[242:245], v194 offset:4096
	s_waitcnt lgkmcnt(4)
	v_mfma_f32_32x32x16_bf16 v[32:47], v[246:249], v[180:183], v[32:47]
	ds_read_b128 v[246:249], v194 offset:8192
	s_waitcnt lgkmcnt(4)
	v_mfma_f32_32x32x16_bf16 v[16:31], v[250:253], v[180:183], v[16:31]
	ds_read_b128 v[250:253], v194 offset:12288
	s_waitcnt lgkmcnt(3)
	v_mfma_f32_32x32x16_bf16 v[128:143], v[238:241], v[190:193], v[128:143]
	s_waitcnt lgkmcnt(2)
	v_mfma_f32_32x32x16_bf16 v[48:63], v[242:245], v[190:193], v[48:63]
	s_waitcnt lgkmcnt(1)
	v_mfma_f32_32x32x16_bf16 v[32:47], v[246:249], v[190:193], v[32:47]
	s_waitcnt lgkmcnt(0)
	v_mfma_f32_32x32x16_bf16 v[16:31], v[250:253], v[190:193], v[16:31]
	s_waitcnt vmcnt(6)
	s_barrier
	ds_read_b128 v[180:183], v186 offset:32768
	ds_read_b128 v[238:241], v14
	ds_read_b128 v[242:245], v14 offset:4096
	ds_read_b128 v[246:249], v14 offset:8192
	ds_read_b128 v[250:253], v14 offset:12288
	s_add_u32 m0, s33, 0x18000
	v_lshl_add_u64 v[2:3], v[2:3], 0, s[84:85]
	global_load_lds_dwordx4 v[2:3], off
	s_add_u32 m0, s33, 0x1a000
	v_lshl_add_u64 v[6:7], v[6:7], 0, s[84:85]
	global_load_lds_dwordx4 v[6:7], off
	s_add_u32 m0, s33, 0x1c000
	v_lshl_add_u64 v[8:9], v[8:9], 0, s[84:85]
	global_load_lds_dwordx4 v[8:9], off
	s_add_u32 m0, s33, 0x1e000
	v_lshl_add_u64 v[10:11], v[10:11], 0, s[84:85]
	global_load_lds_dwordx4 v[10:11], off
	s_add_u32 m0, s33, 0x20000
	v_lshl_add_u64 v[4:5], v[4:5], 0, s[84:85]
	global_load_lds_dwordx4 v[4:5], off
	s_add_u32 m0, s33, 0x22000
	v_lshl_add_u64 v[12:13], v[12:13], 0, s[84:85]
	global_load_lds_dwordx4 v[12:13], off
	ds_read_b128 v[190:193], v189 offset:32768
	s_waitcnt lgkmcnt(4)
	v_mfma_f32_32x32x16_bf16 v[128:143], v[238:241], v[180:183], v[128:143]
	ds_read_b128 v[238:241], v15
	s_waitcnt lgkmcnt(4)
	v_mfma_f32_32x32x16_bf16 v[48:63], v[242:245], v[180:183], v[48:63]
	ds_read_b128 v[242:245], v15 offset:4096
	s_waitcnt lgkmcnt(4)
	v_mfma_f32_32x32x16_bf16 v[32:47], v[246:249], v[180:183], v[32:47]
	ds_read_b128 v[246:249], v15 offset:8192
	s_waitcnt lgkmcnt(4)
	v_mfma_f32_32x32x16_bf16 v[16:31], v[250:253], v[180:183], v[16:31]
	ds_read_b128 v[250:253], v15 offset:12288
	ds_read_b128 v[180:183], v233 offset:32768
	s_waitcnt lgkmcnt(4)
	v_mfma_f32_32x32x16_bf16 v[128:143], v[238:241], v[190:193], v[128:143]
	ds_read_b128 v[238:241], v0
	s_waitcnt lgkmcnt(4)
	v_mfma_f32_32x32x16_bf16 v[48:63], v[242:245], v[190:193], v[48:63]
	ds_read_b128 v[242:245], v0 offset:4096
	s_waitcnt lgkmcnt(4)
	v_mfma_f32_32x32x16_bf16 v[32:47], v[246:249], v[190:193], v[32:47]
	ds_read_b128 v[246:249], v0 offset:8192
	s_waitcnt lgkmcnt(4)
	v_mfma_f32_32x32x16_bf16 v[16:31], v[250:253], v[190:193], v[16:31]
	ds_read_b128 v[250:253], v0 offset:12288
	ds_read_b128 v[190:193], v234 offset:32768
	s_waitcnt lgkmcnt(4)
	v_mfma_f32_32x32x16_bf16 v[128:143], v[238:241], v[180:183], v[128:143]
	ds_read_b128 v[238:241], v184
	s_waitcnt lgkmcnt(4)
	v_mfma_f32_32x32x16_bf16 v[48:63], v[242:245], v[180:183], v[48:63]
	ds_read_b128 v[242:245], v184 offset:4096
	s_waitcnt lgkmcnt(4)
	v_mfma_f32_32x32x16_bf16 v[32:47], v[246:249], v[180:183], v[32:47]
	ds_read_b128 v[246:249], v184 offset:8192
	s_waitcnt lgkmcnt(4)
	v_mfma_f32_32x32x16_bf16 v[16:31], v[250:253], v[180:183], v[16:31]
	ds_read_b128 v[250:253], v184 offset:12288
	s_waitcnt lgkmcnt(3)
	v_mfma_f32_32x32x16_bf16 v[128:143], v[238:241], v[190:193], v[128:143]
	s_waitcnt lgkmcnt(2)
	v_mfma_f32_32x32x16_bf16 v[48:63], v[242:245], v[190:193], v[48:63]
	s_waitcnt lgkmcnt(1)
	v_mfma_f32_32x32x16_bf16 v[32:47], v[246:249], v[190:193], v[32:47]
	s_waitcnt lgkmcnt(0)
	v_mfma_f32_32x32x16_bf16 v[16:31], v[250:253], v[190:193], v[16:31]
	s_waitcnt vmcnt(6)
	s_barrier
; DI f32x16 mfma(bf16x8 a, bf16x8 b, f32x16 c) { return __builtin_amdgcn_mfma_f32_32x32x16_bf16(a, b, c, 0, 0, 0); }
;     ...
;   for (int kt = 0; kt < nk; ++kt) {
;     const char* cur = lds + (kt & 1) * DBUF;
;     if (kt + 1 < nk) DMA_ISSUE((kt + 1) & 1, kt + 1)
; #pragma unroll(NTB == 1 ? 2 : 4)
;     for (int s = 0; s < 4; ++s) {
;       const int ro = ((2 * s + hh) ^ xr) * 16;
;       bf16x8 bfr[NTB];
; #pragma unroll
;       for (int tb = 0; tb < NTB; ++tb) bfr[tb] = *(const bf16x8*)(cur + bbase + tb * 32 * DROW + ro);
; #pragma unroll
;       for (int fb = 0; fb < NFB; ++fb) {
;         const bf16x8 afr = *(const bf16x8*)(cur + abase + fb * 32 * DROW + ro);
; #pragma unroll
;         for (int tb = 0; tb < NTB; ++tb) acc[tb * NFB + fb] = mfma(afr, bfr[tb], acc[tb * NFB + fb]);
;       }
;     }
;     asm volatile("s_waitcnt vmcnt(0) lgkmcnt(0)" ::: "memory");
;     __builtin_amdgcn_s_barrier();
	v_add_u32_e32 v195, 0xc000, v186
	ds_read_b128 v[180:183], v195 offset:32768
	v_add_u32_e32 v194, 0xc000, v14
	ds_read_b128 v[238:241], v194
	ds_read_b128 v[242:245], v194 offset:4096
	ds_read_b128 v[246:249], v194 offset:8192
	ds_read_b128 v[250:253], v194 offset:12288
	s_add_u32 m0, s33, 0x0
	v_lshl_add_u64 v[2:3], v[2:3], 0, s[84:85]
	global_load_lds_dwordx4 v[2:3], off
	s_add_u32 m0, s33, 0x2000
	v_lshl_add_u64 v[6:7], v[6:7], 0, s[84:85]
	global_load_lds_dwordx4 v[6:7], off
	s_add_u32 m0, s33, 0x4000
	v_lshl_add_u64 v[8:9], v[8:9], 0, s[84:85]
	global_load_lds_dwordx4 v[8:9], off
	s_add_u32 m0, s33, 0x6000
	v_lshl_add_u64 v[10:11], v[10:11], 0, s[84:85]
	global_load_lds_dwordx4 v[10:11], off
	s_add_u32 m0, s33, 0x8000
	v_lshl_add_u64 v[4:5], v[4:5], 0, s[84:85]
	global_load_lds_dwordx4 v[4:5], off
	s_add_u32 m0, s33, 0xa000
	v_lshl_add_u64 v[12:13], v[12:13], 0, s[84:85]
	global_load_lds_dwordx4 v[12:13], off
	v_add_u32_e32 v195, 0xc000, v189
	ds_read_b128 v[190:193], v195 offset:32768
	v_add_u32_e32 v194, 0xc000, v15
	s_waitcnt lgkmcnt(4)
	v_mfma_f32_32x32x16_bf16 v[128:143], v[238:241], v[180:183], v[128:143]
	ds_read_b128 v[238:241], v194
	s_waitcnt lgkmcnt(4)
	v_mfma_f32_32x32x16_bf16 v[48:63], v[242:245], v[180:183], v[48:63]
	ds_read_b128 v[242:245], v194 offset:4096
	s_waitcnt lgkmcnt(4)
	v_mfma_f32_32x32x16_bf16 v[32:47], v[246:249], v[180:183], v[32:47]
	ds_read_b128 v[246:249], v194 offset:8192
	s_waitcnt lgkmcnt(4)
	v_mfma_f32_32x32x16_bf16 v[16:31], v[250:253], v[180:183], v[16:31]
	ds_read_b128 v[250:253], v194 offset:12288
	v_add_u32_e32 v195, 0xc000, v233
	ds_read_b128 v[180:183], v195 offset:32768
	v_add_u32_e32 v194, 0xc000, v0
	s_waitcnt lgkmcnt(4)
	v_mfma_f32_32x32x16_bf16 v[128:143], v[238:241], v[190:193], v[128:143]
	ds_read_b128 v[238:241], v194
	s_waitcnt lgkmcnt(4)
	v_mfma_f32_32x32x16_bf16 v[48:63], v[242:245], v[190:193], v[48:63]
	ds_read_b128 v[242:245], v194 offset:4096
	s_waitcnt lgkmcnt(4)
	v_mfma_f32_32x32x16_bf16 v[32:47], v[246:249], v[190:193], v[32:47]
	ds_read_b128 v[246:249], v194 offset:8192
	s_waitcnt lgkmcnt(4)
	v_mfma_f32_32x32x16_bf16 v[16:31], v[250:253], v[190:193], v[16:31]
	ds_read_b128 v[250:253], v194 offset:12288
	v_add_u32_e32 v195, 0xc000, v234
	ds_read_b128 v[190:193], v195 offset:32768
	v_add_u32_e32 v194, 0xc000, v184
	s_waitcnt lgkmcnt(4)
	v_mfma_f32_32x32x16_bf16 v[128:143], v[238:241], v[180:183], v[128:143]
	ds_read_b128 v[238:241], v194
	s_waitcnt lgkmcnt(4)
	v_mfma_f32_32x32x16_bf16 v[48:63], v[242:245], v[180:183], v[48:63]
	ds_read_b128 v[242:245], v194 offset:4096
	s_waitcnt lgkmcnt(4)
	v_mfma_f32_32x32x16_bf16 v[32:47], v[246:249], v[180:183], v[32:47]
	ds_read_b128 v[246:249], v194 offset:8192
	s_waitcnt lgkmcnt(4)
	v_mfma_f32_32x32x16_bf16 v[16:31], v[250:253], v[180:183], v[16:31]
	ds_read_b128 v[250:253], v194 offset:12288
	s_waitcnt lgkmcnt(3)
	v_mfma_f32_32x32x16_bf16 v[128:143], v[238:241], v[190:193], v[128:143]
	s_waitcnt lgkmcnt(2)
	v_mfma_f32_32x32x16_bf16 v[48:63], v[242:245], v[190:193], v[48:63]
	s_waitcnt lgkmcnt(1)
	v_mfma_f32_32x32x16_bf16 v[32:47], v[246:249], v[190:193], v[32:47]
	s_waitcnt lgkmcnt(0)
	v_mfma_f32_32x32x16_bf16 v[16:31], v[250:253], v[190:193], v[16:31]
	s_waitcnt vmcnt(6)
	s_barrier
	v_add_u32_e32 v195, 0x18000, v186
	ds_read_b128 v[180:183], v195 offset:32768
	v_add_u32_e32 v194, 0x18000, v14
	ds_read_b128 v[238:241], v194
	ds_read_b128 v[242:245], v194 offset:4096
	ds_read_b128 v[246:249], v194 offset:8192
	ds_read_b128 v[250:253], v194 offset:12288
	s_add_u32 m0, s33, 0xc000
	v_lshl_add_u64 v[2:3], v[2:3], 0, s[84:85]
	global_load_lds_dwordx4 v[2:3], off
	s_add_u32 m0, s33, 0xe000
	v_lshl_add_u64 v[6:7], v[6:7], 0, s[84:85]
	global_load_lds_dwordx4 v[6:7], off
	s_add_u32 m0, s33, 0x10000
	v_lshl_add_u64 v[8:9], v[8:9], 0, s[84:85]
	global_load_lds_dwordx4 v[8:9], off
	s_add_u32 m0, s33, 0x12000
	v_lshl_add_u64 v[10:11], v[10:11], 0, s[84:85]
	global_load_lds_dwordx4 v[10:11], off
	s_add_u32 m0, s33, 0x14000
	v_lshl_add_u64 v[4:5], v[4:5], 0, s[84:85]
	global_load_lds_dwordx4 v[4:5], off
	s_add_u32 m0, s33, 0x16000
	v_lshl_add_u64 v[12:13], v[12:13], 0, s[84:85]
	global_load_lds_dwordx4 v[12:13], off
	v_add_u32_e32 v195, 0x18000, v189
	ds_read_b128 v[190:193], v195 offset:32768
	v_add_u32_e32 v194, 0x18000, v15
	s_waitcnt lgkmcnt(4)
	v_mfma_f32_32x32x16_bf16 v[128:143], v[238:241], v[180:183], v[128:143]
	ds_read_b128 v[238:241], v194
	s_waitcnt lgkmcnt(4)
	v_mfma_f32_32x32x16_bf16 v[48:63], v[242:245], v[180:183], v[48:63]
	ds_read_b128 v[242:245], v194 offset:4096
	s_waitcnt lgkmcnt(4)
	v_mfma_f32_32x32x16_bf16 v[32:47], v[246:249], v[180:183], v[32:47]
	ds_read_b128 v[246:249], v194 offset:8192
	s_waitcnt lgkmcnt(4)
	v_mfma_f32_32x32x16_bf16 v[16:31], v[250:253], v[180:183], v[16:31]
	ds_read_b128 v[250:253], v194 offset:12288
	v_add_u32_e32 v195, 0x18000, v233
	ds_read_b128 v[180:183], v195 offset:32768
	v_add_u32_e32 v194, 0x18000, v0
	s_waitcnt lgkmcnt(4)
	v_mfma_f32_32x32x16_bf16 v[128:143], v[238:241], v[190:193], v[128:143]
	ds_read_b128 v[238:241], v194
	s_waitcnt lgkmcnt(4)
	v_mfma_f32_32x32x16_bf16 v[48:63], v[242:245], v[190:193], v[48:63]
	ds_read_b128 v[242:245], v194 offset:4096
	s_waitcnt lgkmcnt(4)
	v_mfma_f32_32x32x16_bf16 v[32:47], v[246:249], v[190:193], v[32:47]
	ds_read_b128 v[246:249], v194 offset:8192
	s_waitcnt lgkmcnt(4)
	v_mfma_f32_32x32x16_bf16 v[16:31], v[250:253], v[190:193], v[16:31]
	ds_read_b128 v[250:253], v194 offset:12288
	v_add_u32_e32 v195, 0x18000, v234
	ds_read_b128 v[190:193], v195 offset:32768
	v_add_u32_e32 v194, 0x18000, v184
	s_waitcnt lgkmcnt(4)
	v_mfma_f32_32x32x16_bf16 v[128:143], v[238:241], v[180:183], v[128:143]
	ds_read_b128 v[238:241], v194
	s_waitcnt lgkmcnt(4)
	v_mfma_f32_32x32x16_bf16 v[48:63], v[242:245], v[180:183], v[48:63]
	ds_read_b128 v[242:245], v194 offset:4096
	s_waitcnt lgkmcnt(4)
	v_mfma_f32_32x32x16_bf16 v[32:47], v[246:249], v[180:183], v[32:47]
	ds_read_b128 v[246:249], v194 offset:8192
	s_waitcnt lgkmcnt(4)
	v_mfma_f32_32x32x16_bf16 v[16:31], v[250:253], v[180:183], v[16:31]
	ds_read_b128 v[250:253], v194 offset:12288
	s_waitcnt lgkmcnt(3)
	v_mfma_f32_32x32x16_bf16 v[128:143], v[238:241], v[190:193], v[128:143]
	s_waitcnt lgkmcnt(2)
	v_mfma_f32_32x32x16_bf16 v[48:63], v[242:245], v[190:193], v[48:63]
	s_waitcnt lgkmcnt(1)
	v_mfma_f32_32x32x16_bf16 v[32:47], v[246:249], v[190:193], v[32:47]
	s_waitcnt lgkmcnt(0)
	v_mfma_f32_32x32x16_bf16 v[16:31], v[250:253], v[190:193], v[16:31]
	s_waitcnt vmcnt(6)
	s_barrier
; DI f32x16 mfma(bf16x8 a, bf16x8 b, f32x16 c) { return __builtin_amdgcn_mfma_f32_32x32x16_bf16(a, b, c, 0, 0, 0); }
;     ...
;   for (int kt = 0; kt < nk; ++kt) {
;     const char* cur = lds + (kt & 1) * DBUF;
;     if (kt + 1 < nk) DMA_ISSUE((kt + 1) & 1, kt + 1)
; #pragma unroll(NTB == 1 ? 2 : 4)
;     for (int s = 0; s < 4; ++s) {
;       const int ro = ((2 * s + hh) ^ xr) * 16;
;       bf16x8 bfr[NTB];
; #pragma unroll
;       for (int tb = 0; tb < NTB; ++tb) bfr[tb] = *(const bf16x8*)(cur + bbase + tb * 32 * DROW + ro);
; #pragma unroll
;       for (int fb = 0; fb < NFB; ++fb) {
;         const bf16x8 afr = *(const bf16x8*)(cur + abase + fb * 32 * DROW + ro);
; #pragma unroll
;         for (int tb = 0; tb < NTB; ++tb) acc[tb * NFB + fb] = mfma(afr, bfr[tb], acc[tb * NFB + fb]);
;       }
;     }
;     asm volatile("s_waitcnt vmcnt(0) lgkmcnt(0)" ::: "memory");
;     __builtin_amdgcn_s_barrier();
	ds_read_b128 v[180:183], v186 offset:32768
	ds_read_b128 v[238:241], v14
	ds_read_b128 v[242:245], v14 offset:4096
	ds_read_b128 v[246:249], v14 offset:8192
	ds_read_b128 v[250:253], v14 offset:12288
	s_add_u32 m0, s33, 0x18000
	v_lshl_add_u64 v[2:3], v[2:3], 0, s[84:85]
	global_load_lds_dwordx4 v[2:3], off
	s_add_u32 m0, s33, 0x1a000
	v_lshl_add_u64 v[6:7], v[6:7], 0, s[84:85]
	global_load_lds_dwordx4 v[6:7], off
	s_add_u32 m0, s33, 0x1c000
	v_lshl_add_u64 v[8:9], v[8:9], 0, s[84:85]
	global_load_lds_dwordx4 v[8:9], off
	s_add_u32 m0, s33, 0x1e000
	v_lshl_add_u64 v[10:11], v[10:11], 0, s[84:85]
	global_load_lds_dwordx4 v[10:11], off
	s_add_u32 m0, s33, 0x20000
	v_lshl_add_u64 v[4:5], v[4:5], 0, s[84:85]
	global_load_lds_dwordx4 v[4:5], off
	s_add_u32 m0, s33, 0x22000
	v_lshl_add_u64 v[12:13], v[12:13], 0, s[84:85]
	global_load_lds_dwordx4 v[12:13], off
	ds_read_b128 v[190:193], v189 offset:32768
	s_waitcnt lgkmcnt(4)
	v_mfma_f32_32x32x16_bf16 v[128:143], v[238:241], v[180:183], v[128:143]
	ds_read_b128 v[238:241], v15
	s_waitcnt lgkmcnt(4)
	v_mfma_f32_32x32x16_bf16 v[48:63], v[242:245], v[180:183], v[48:63]
	ds_read_b128 v[242:245], v15 offset:4096
	s_waitcnt lgkmcnt(4)
	v_mfma_f32_32x32x16_bf16 v[32:47], v[246:249], v[180:183], v[32:47]
	ds_read_b128 v[246:249], v15 offset:8192
	s_waitcnt lgkmcnt(4)
	v_mfma_f32_32x32x16_bf16 v[16:31], v[250:253], v[180:183], v[16:31]
	ds_read_b128 v[250:253], v15 offset:12288
	ds_read_b128 v[180:183], v233 offset:32768
	s_waitcnt lgkmcnt(4)
	v_mfma_f32_32x32x16_bf16 v[128:143], v[238:241], v[190:193], v[128:143]
	ds_read_b128 v[238:241], v0
	s_waitcnt lgkmcnt(4)
	v_mfma_f32_32x32x16_bf16 v[48:63], v[242:245], v[190:193], v[48:63]
	ds_read_b128 v[242:245], v0 offset:4096
	s_waitcnt lgkmcnt(4)
	v_mfma_f32_32x32x16_bf16 v[32:47], v[246:249], v[190:193], v[32:47]
	ds_read_b128 v[246:249], v0 offset:8192
	s_waitcnt lgkmcnt(4)
	v_mfma_f32_32x32x16_bf16 v[16:31], v[250:253], v[190:193], v[16:31]
	ds_read_b128 v[250:253], v0 offset:12288
	ds_read_b128 v[190:193], v234 offset:32768
	s_waitcnt lgkmcnt(4)
	v_mfma_f32_32x32x16_bf16 v[128:143], v[238:241], v[180:183], v[128:143]
	ds_read_b128 v[238:241], v184
	s_waitcnt lgkmcnt(4)
	v_mfma_f32_32x32x16_bf16 v[48:63], v[242:245], v[180:183], v[48:63]
	ds_read_b128 v[242:245], v184 offset:4096
	s_waitcnt lgkmcnt(4)
	v_mfma_f32_32x32x16_bf16 v[32:47], v[246:249], v[180:183], v[32:47]
	ds_read_b128 v[246:249], v184 offset:8192
	s_waitcnt lgkmcnt(4)
	v_mfma_f32_32x32x16_bf16 v[16:31], v[250:253], v[180:183], v[16:31]
	ds_read_b128 v[250:253], v184 offset:12288
	s_waitcnt lgkmcnt(3)
	v_mfma_f32_32x32x16_bf16 v[128:143], v[238:241], v[190:193], v[128:143]
	s_waitcnt lgkmcnt(2)
	v_mfma_f32_32x32x16_bf16 v[48:63], v[242:245], v[190:193], v[48:63]
	s_waitcnt lgkmcnt(1)
	v_mfma_f32_32x32x16_bf16 v[32:47], v[246:249], v[190:193], v[32:47]
	s_waitcnt lgkmcnt(0)
	v_mfma_f32_32x32x16_bf16 v[16:31], v[250:253], v[190:193], v[16:31]
	s_waitcnt vmcnt(6)
	s_barrier
	v_add_u32_e32 v195, 0xc000, v186
	ds_read_b128 v[180:183], v195 offset:32768
	v_add_u32_e32 v194, 0xc000, v14
	ds_read_b128 v[238:241], v194
	ds_read_b128 v[242:245], v194 offset:4096
	ds_read_b128 v[246:249], v194 offset:8192
	ds_read_b128 v[250:253], v194 offset:12288
	s_add_u32 m0, s33, 0x0
	v_lshl_add_u64 v[2:3], v[2:3], 0, s[84:85]
	global_load_lds_dwordx4 v[2:3], off
	s_add_u32 m0, s33, 0x2000
	v_lshl_add_u64 v[6:7], v[6:7], 0, s[84:85]
	global_load_lds_dwordx4 v[6:7], off
	s_add_u32 m0, s33, 0x4000
	v_lshl_add_u64 v[8:9], v[8:9], 0, s[84:85]
	global_load_lds_dwordx4 v[8:9], off
	s_add_u32 m0, s33, 0x6000
	v_lshl_add_u64 v[10:11], v[10:11], 0, s[84:85]
	global_load_lds_dwordx4 v[10:11], off
	s_add_u32 m0, s33, 0x8000
	v_lshl_add_u64 v[4:5], v[4:5], 0, s[84:85]
	global_load_lds_dwordx4 v[4:5], off
	s_add_u32 m0, s33, 0xa000
	v_lshl_add_u64 v[12:13], v[12:13], 0, s[84:85]
	global_load_lds_dwordx4 v[12:13], off
	v_add_u32_e32 v195, 0xc000, v189
	ds_read_b128 v[190:193], v195 offset:32768
	v_add_u32_e32 v194, 0xc000, v15
	s_waitcnt lgkmcnt(4)
	v_mfma_f32_32x32x16_bf16 v[128:143], v[238:241], v[180:183], v[128:143]
	ds_read_b128 v[238:241], v194
	s_waitcnt lgkmcnt(4)
	v_mfma_f32_32x32x16_bf16 v[48:63], v[242:245], v[180:183], v[48:63]
	ds_read_b128 v[242:245], v194 offset:4096
	s_waitcnt lgkmcnt(4)
	v_mfma_f32_32x32x16_bf16 v[32:47], v[246:249], v[180:183], v[32:47]
	ds_read_b128 v[246:249], v194 offset:8192
	s_waitcnt lgkmcnt(4)
	v_mfma_f32_32x32x16_bf16 v[16:31], v[250:253], v[180:183], v[16:31]
	ds_read_b128 v[250:253], v194 offset:12288
	v_add_u32_e32 v195, 0xc000, v233
	ds_read_b128 v[180:183], v195 offset:32768
	v_add_u32_e32 v194, 0xc000, v0
	s_waitcnt lgkmcnt(4)
	v_mfma_f32_32x32x16_bf16 v[128:143], v[238:241], v[190:193], v[128:143]
	ds_read_b128 v[238:241], v194
	s_waitcnt lgkmcnt(4)
	v_mfma_f32_32x32x16_bf16 v[48:63], v[242:245], v[190:193], v[48:63]
	ds_read_b128 v[242:245], v194 offset:4096
	s_waitcnt lgkmcnt(4)
	v_mfma_f32_32x32x16_bf16 v[32:47], v[246:249], v[190:193], v[32:47]
	ds_read_b128 v[246:249], v194 offset:8192
	s_waitcnt lgkmcnt(4)
	v_mfma_f32_32x32x16_bf16 v[16:31], v[250:253], v[190:193], v[16:31]
	ds_read_b128 v[250:253], v194 offset:12288
	v_add_u32_e32 v195, 0xc000, v234
	ds_read_b128 v[190:193], v195 offset:32768
	v_add_u32_e32 v194, 0xc000, v184
	s_waitcnt lgkmcnt(4)
	v_mfma_f32_32x32x16_bf16 v[128:143], v[238:241], v[180:183], v[128:143]
	ds_read_b128 v[238:241], v194
	s_waitcnt lgkmcnt(4)
	v_mfma_f32_32x32x16_bf16 v[48:63], v[242:245], v[180:183], v[48:63]
	ds_read_b128 v[242:245], v194 offset:4096
	s_waitcnt lgkmcnt(4)
	v_mfma_f32_32x32x16_bf16 v[32:47], v[246:249], v[180:183], v[32:47]
	ds_read_b128 v[246:249], v194 offset:8192
	s_waitcnt lgkmcnt(4)
	v_mfma_f32_32x32x16_bf16 v[16:31], v[250:253], v[180:183], v[16:31]
	ds_read_b128 v[250:253], v194 offset:12288
	s_waitcnt lgkmcnt(3)
	v_mfma_f32_32x32x16_bf16 v[128:143], v[238:241], v[190:193], v[128:143]
	s_waitcnt lgkmcnt(2)
	v_mfma_f32_32x32x16_bf16 v[48:63], v[242:245], v[190:193], v[48:63]
	s_waitcnt lgkmcnt(1)
	v_mfma_f32_32x32x16_bf16 v[32:47], v[246:249], v[190:193], v[32:47]
	s_waitcnt lgkmcnt(0)
	v_mfma_f32_32x32x16_bf16 v[16:31], v[250:253], v[190:193], v[16:31]
	s_waitcnt vmcnt(6)
	s_barrier
; DI f32x16 mfma(bf16x8 a, bf16x8 b, f32x16 c) { return __builtin_amdgcn_mfma_f32_32x32x16_bf16(a, b, c, 0, 0, 0); }
;     ...
;   for (int kt = 0; kt < nk; ++kt) {
;     const char* cur = lds + (kt & 1) * DBUF;
;     if (kt + 1 < nk) DMA_ISSUE((kt + 1) & 1, kt + 1)
; #pragma unroll(NTB == 1 ? 2 : 4)
;     for (int s = 0; s < 4; ++s) {
;       const int ro = ((2 * s + hh) ^ xr) * 16;
;       bf16x8 bfr[NTB];
; #pragma unroll
;       for (int tb = 0; tb < NTB; ++tb) bfr[tb] = *(const bf16x8*)(cur + bbase + tb * 32 * DROW + ro);
; #pragma unroll
;       for (int fb = 0; fb < NFB; ++fb) {
;         const bf16x8 afr = *(const bf16x8*)(cur + abase + fb * 32 * DROW + ro);
; #pragma unroll
;         for (int tb = 0; tb < NTB; ++tb) acc[tb * NFB + fb] = mfma(afr, bfr[tb], acc[tb * NFB + fb]);
;       }
;     }
;     asm volatile("s_waitcnt vmcnt(0) lgkmcnt(0)" ::: "memory");
;     __builtin_amdgcn_s_barrier();
;   }
	v_add_u32_e32 v195, 0x18000, v186
	ds_read_b128 v[180:183], v195 offset:32768
	v_add_u32_e32 v194, 0x18000, v14
	ds_read_b128 v[238:241], v194
	ds_read_b128 v[242:245], v194 offset:4096
	ds_read_b128 v[246:249], v194 offset:8192
	ds_read_b128 v[250:253], v194 offset:12288
	v_add_u32_e32 v195, 0x18000, v189
	ds_read_b128 v[190:193], v195 offset:32768
	v_add_u32_e32 v194, 0x18000, v15
	s_waitcnt lgkmcnt(4)
	v_mfma_f32_32x32x16_bf16 v[128:143], v[238:241], v[180:183], v[128:143]
	ds_read_b128 v[238:241], v194
	s_waitcnt lgkmcnt(4)
	v_mfma_f32_32x32x16_bf16 v[48:63], v[242:245], v[180:183], v[48:63]
	ds_read_b128 v[242:245], v194 offset:4096
	s_waitcnt lgkmcnt(4)
	v_mfma_f32_32x32x16_bf16 v[32:47], v[246:249], v[180:183], v[32:47]
	ds_read_b128 v[246:249], v194 offset:8192
	s_waitcnt lgkmcnt(4)
	v_mfma_f32_32x32x16_bf16 v[16:31], v[250:253], v[180:183], v[16:31]
	ds_read_b128 v[250:253], v194 offset:12288
	v_add_u32_e32 v195, 0x18000, v233
	ds_read_b128 v[180:183], v195 offset:32768
	v_add_u32_e32 v194, 0x18000, v0
	s_waitcnt lgkmcnt(4)
	v_mfma_f32_32x32x16_bf16 v[128:143], v[238:241], v[190:193], v[128:143]
	ds_read_b128 v[238:241], v194
	s_waitcnt lgkmcnt(4)
	v_mfma_f32_32x32x16_bf16 v[48:63], v[242:245], v[190:193], v[48:63]
	ds_read_b128 v[242:245], v194 offset:4096
	s_waitcnt lgkmcnt(4)
	v_mfma_f32_32x32x16_bf16 v[32:47], v[246:249], v[190:193], v[32:47]
	ds_read_b128 v[246:249], v194 offset:8192
	s_waitcnt lgkmcnt(4)
	v_mfma_f32_32x32x16_bf16 v[16:31], v[250:253], v[190:193], v[16:31]
	ds_read_b128 v[250:253], v194 offset:12288
	v_add_u32_e32 v195, 0x18000, v234
	ds_read_b128 v[190:193], v195 offset:32768
	v_add_u32_e32 v194, 0x18000, v184
	s_waitcnt lgkmcnt(4)
	v_mfma_f32_32x32x16_bf16 v[128:143], v[238:241], v[180:183], v[128:143]
	ds_read_b128 v[238:241], v194
	s_waitcnt lgkmcnt(4)
	v_mfma_f32_32x32x16_bf16 v[48:63], v[242:245], v[180:183], v[48:63]
	ds_read_b128 v[242:245], v194 offset:4096
	s_waitcnt lgkmcnt(4)
	v_mfma_f32_32x32x16_bf16 v[32:47], v[246:249], v[180:183], v[32:47]
	ds_read_b128 v[246:249], v194 offset:8192
	s_waitcnt lgkmcnt(4)
	v_mfma_f32_32x32x16_bf16 v[16:31], v[250:253], v[180:183], v[16:31]
	ds_read_b128 v[250:253], v194 offset:12288
	s_waitcnt lgkmcnt(3)
	v_mfma_f32_32x32x16_bf16 v[128:143], v[238:241], v[190:193], v[128:143]
	s_waitcnt lgkmcnt(2)
	v_mfma_f32_32x32x16_bf16 v[48:63], v[242:245], v[190:193], v[48:63]
	s_waitcnt lgkmcnt(1)
	v_mfma_f32_32x32x16_bf16 v[32:47], v[246:249], v[190:193], v[32:47]
	s_waitcnt lgkmcnt(0)
	v_mfma_f32_32x32x16_bf16 v[16:31], v[250:253], v[190:193], v[16:31]
	s_waitcnt vmcnt(0)
	s_barrier
	ds_read_b128 v[180:183], v186 offset:32768
	ds_read_b128 v[238:241], v14
	ds_read_b128 v[242:245], v14 offset:4096
	ds_read_b128 v[246:249], v14 offset:8192
	ds_read_b128 v[250:253], v14 offset:12288
	ds_read_b128 v[190:193], v189 offset:32768
	s_waitcnt lgkmcnt(4)
	v_mfma_f32_32x32x16_bf16 v[128:143], v[238:241], v[180:183], v[128:143]
	ds_read_b128 v[238:241], v15
	s_waitcnt lgkmcnt(4)
	v_mfma_f32_32x32x16_bf16 v[48:63], v[242:245], v[180:183], v[48:63]
	ds_read_b128 v[242:245], v15 offset:4096
	s_waitcnt lgkmcnt(4)
	v_mfma_f32_32x32x16_bf16 v[32:47], v[246:249], v[180:183], v[32:47]
	ds_read_b128 v[246:249], v15 offset:8192
	s_waitcnt lgkmcnt(4)
	v_mfma_f32_32x32x16_bf16 v[16:31], v[250:253], v[180:183], v[16:31]
	ds_read_b128 v[250:253], v15 offset:12288
	ds_read_b128 v[180:183], v233 offset:32768
	s_waitcnt lgkmcnt(4)
	v_mfma_f32_32x32x16_bf16 v[128:143], v[238:241], v[190:193], v[128:143]
	ds_read_b128 v[238:241], v0
	s_waitcnt lgkmcnt(4)
	v_mfma_f32_32x32x16_bf16 v[48:63], v[242:245], v[190:193], v[48:63]
	ds_read_b128 v[242:245], v0 offset:4096
	s_waitcnt lgkmcnt(4)
	v_mfma_f32_32x32x16_bf16 v[32:47], v[246:249], v[190:193], v[32:47]
	ds_read_b128 v[246:249], v0 offset:8192
	s_waitcnt lgkmcnt(4)
	v_mfma_f32_32x32x16_bf16 v[16:31], v[250:253], v[190:193], v[16:31]
	ds_read_b128 v[250:253], v0 offset:12288
	ds_read_b128 v[190:193], v234 offset:32768
	s_waitcnt lgkmcnt(4)
	v_mfma_f32_32x32x16_bf16 v[128:143], v[238:241], v[180:183], v[128:143]
	ds_read_b128 v[238:241], v184
	s_waitcnt lgkmcnt(4)
	v_mfma_f32_32x32x16_bf16 v[48:63], v[242:245], v[180:183], v[48:63]
	ds_read_b128 v[242:245], v184 offset:4096
	s_waitcnt lgkmcnt(4)
	v_mfma_f32_32x32x16_bf16 v[32:47], v[246:249], v[180:183], v[32:47]
	ds_read_b128 v[246:249], v184 offset:8192
	s_waitcnt lgkmcnt(4)
	v_mfma_f32_32x32x16_bf16 v[16:31], v[250:253], v[180:183], v[16:31]
	ds_read_b128 v[250:253], v184 offset:12288
	s_waitcnt lgkmcnt(3)
	v_mfma_f32_32x32x16_bf16 v[128:143], v[238:241], v[190:193], v[128:143]
	s_waitcnt lgkmcnt(2)
	v_mfma_f32_32x32x16_bf16 v[48:63], v[242:245], v[190:193], v[48:63]
	s_waitcnt lgkmcnt(1)
	v_mfma_f32_32x32x16_bf16 v[32:47], v[246:249], v[190:193], v[32:47]
	s_waitcnt lgkmcnt(0)
	v_mfma_f32_32x32x16_bf16 v[16:31], v[250:253], v[190:193], v[16:31]
	s_nop 7
	s_nop 7
	s_waitcnt vmcnt(0) lgkmcnt(0)
	s_barrier
; DI unsigned pack2(float a, float b) { f2_t v = {a, b}; bf2_t r = __builtin_convertvector(v, bf2_t); return __builtin_bit_cast(unsigned, r); }
; __global__ void __launch_bounds__(512) mega(Params p) {
;     ...
;           unsigned bp[4][8];
; #pragma unroll
;           for (int fb = 0; fb < 4; ++fb)
; #pragma unroll
;             for (int i = 0; i < 8; ++i) bp[fb][i] = pack2(acc[fb][2 * i], acc[fb][2 * i + 1]);
;           zero4(acc);
;           gemm_main<4, 1>((const u16*)(ws + OFF_WG) + ((size_t)n * 1024 + ft * 256) * 1024, 1024, (const u16*)(ws + OFF_H) + (size_t)tt * 128 * 1024, 1024, 16, acc, lds);
; #pragma unroll
;           for (int fb = 0; fb < 4; ++fb)
; #pragma unroll
;             for (int i = 0; i < 8; ++i) {
;               const float b0 = __uint_as_float(bp[fb][i] << 16), b1 = __uint_as_float(bp[fb][i] & 0xffff0000u);
;               const float g0 = 1.f / (1.f + __builtin_amdgcn_exp2f(nr1 * acc[fb][2 * i]));
;               const float g1 = 1.f / (1.f + __builtin_amdgcn_exp2f(nr1 * acc[fb][2 * i + 1]));
;               float y0 = g0 * b0, y1 = g1 * b1;
;               if (n > 0) { y0 += __uint_as_float(yp[fb][i] << 16); y1 += __uint_as_float(yp[fb][i] & 0xffff0000u); }
;               yp[fb][i] = pack2(y0, y1);
	v_cvt_pk_bf16_f32 v7, v66, v67
	v_mul_f32_e32 v66, v236, v128
	v_mul_f32_e32 v67, v236, v129
	v_exp_f32_e32 v66, v66
	v_exp_f32_e32 v67, v67
	v_cvt_pk_bf16_f32 v6, v68, v69
	v_cvt_pk_bf16_f32 v5, v70, v71
	v_cvt_pk_bf16_f32 v4, v72, v73
	v_pk_add_f32 v[66:67], v[66:67], 1.0 op_sel_hi:[1,0]
	v_cvt_pk_bf16_f32 v180, v112, v113
	v_div_scale_f32 v68, s[34:35], v67, v67, 1.0
	v_rcp_f32_e32 v69, v68
	v_cvt_pk_bf16_f32 v8, v64, v65
	v_lshlrev_b32_e32 v64, 16, v180
	v_and_b32_e32 v65, 0xffff0000, v180
	v_fma_f32 v70, -v68, v69, 1.0
	v_fmac_f32_e32 v69, v70, v69
	v_div_scale_f32 v70, vcc, 1.0, v67, 1.0
	v_mul_f32_e32 v71, v70, v69
	v_fma_f32 v72, -v68, v71, v70
	v_fmac_f32_e32 v71, v72, v69
	v_fma_f32 v68, -v68, v71, v70
	v_div_fmas_f32 v68, v68, v69, v71
	v_div_fixup_f32 v67, v68, v67, 1.0
	v_div_scale_f32 v68, s[34:35], v66, v66, 1.0
	v_rcp_f32_e32 v69, v68
	v_cvt_pk_bf16_f32 v181, v114, v115
	v_cvt_pk_bf16_f32 v182, v116, v117
	v_cvt_pk_bf16_f32 v118, v118, v119
	v_fma_f32 v70, -v68, v69, 1.0
	v_fmac_f32_e32 v69, v70, v69
	v_div_scale_f32 v70, vcc, 1.0, v66, 1.0
	v_mul_f32_e32 v71, v70, v69
	v_fma_f32 v72, -v68, v71, v70
	v_fmac_f32_e32 v71, v72, v69
	v_fma_f32 v68, -v68, v71, v70
	v_div_fmas_f32 v68, v68, v69, v71
	v_div_fixup_f32 v66, v68, v66, 1.0
	v_lshlrev_b32_e32 v70, 16, v166
	v_and_b32_e32 v71, 0xffff0000, v166
	v_pk_mul_f32 v[68:69], v[66:67], v[64:65]
	v_pk_fma_f32 v[64:65], v[66:67], v[64:65], v[70:71]
	v_mul_f32_e32 v66, v236, v130
	v_mul_f32_e32 v67, v236, v131
	v_exp_f32_e32 v66, v66
	v_exp_f32_e32 v67, v67
	v_cndmask_b32_e64 v64, v64, v68, s[0:1]
	v_cndmask_b32_e64 v65, v65, v69, s[0:1]
	v_cvt_pk_bf16_f32 v166, v64, v65
	v_pk_add_f32 v[66:67], v[66:67], 1.0 op_sel_hi:[1,0]
	v_lshlrev_b32_e32 v64, 16, v181
	v_div_scale_f32 v68, s[34:35], v67, v67, 1.0
	v_rcp_f32_e32 v69, v68
	v_and_b32_e32 v65, 0xffff0000, v181
	v_cvt_pk_bf16_f32 v117, v120, v121
	v_cvt_pk_bf16_f32 v116, v122, v123
	v_fma_f32 v70, -v68, v69, 1.0
	v_fmac_f32_e32 v69, v70, v69
	v_div_scale_f32 v70, vcc, 1.0, v67, 1.0
	v_mul_f32_e32 v71, v70, v69
	v_fma_f32 v72, -v68, v71, v70
	v_fmac_f32_e32 v71, v72, v69
	v_fma_f32 v68, -v68, v71, v70
	v_div_fmas_f32 v68, v68, v69, v71
	v_div_fixup_f32 v67, v68, v67, 1.0
	v_div_scale_f32 v68, s[34:35], v66, v66, 1.0
	v_rcp_f32_e32 v69, v68
	v_cvt_pk_bf16_f32 v115, v124, v125
	v_mul_f32_e32 v48, v236, v48
	v_mul_f32_e32 v49, v236, v49
	v_fma_f32 v70, -v68, v69, 1.0
	v_fmac_f32_e32 v69, v70, v69
	v_div_scale_f32 v70, vcc, 1.0, v66, 1.0
	v_mul_f32_e32 v71, v70, v69
	v_fma_f32 v72, -v68, v71, v70
	v_fmac_f32_e32 v71, v72, v69
	v_fma_f32 v68, -v68, v71, v70
	v_div_fmas_f32 v68, v68, v69, v71
	v_div_fixup_f32 v66, v68, v66, 1.0
	v_lshlrev_b32_e32 v70, 16, v167
	v_and_b32_e32 v71, 0xffff0000, v167
	v_pk_mul_f32 v[68:69], v[66:67], v[64:65]
	v_pk_fma_f32 v[64:65], v[66:67], v[64:65], v[70:71]
	v_mul_f32_e32 v66, v236, v132
	v_mul_f32_e32 v67, v236, v133
	v_exp_f32_e32 v66, v66
	v_exp_f32_e32 v67, v67
	v_cndmask_b32_e64 v64, v64, v68, s[0:1]
	v_cndmask_b32_e64 v65, v65, v69, s[0:1]
	v_cvt_pk_bf16_f32 v167, v64, v65
	v_pk_add_f32 v[66:67], v[66:67], 1.0 op_sel_hi:[1,0]
	v_lshlrev_b32_e32 v64, 16, v182
	v_div_scale_f32 v68, s[34:35], v67, v67, 1.0
	v_rcp_f32_e32 v69, v68
	v_and_b32_e32 v65, 0xffff0000, v182
	v_exp_f32_e32 v48, v48
	v_exp_f32_e32 v49, v49
	v_fma_f32 v70, -v68, v69, 1.0
	v_fmac_f32_e32 v69, v70, v69
	v_div_scale_f32 v70, vcc, 1.0, v67, 1.0
	v_mul_f32_e32 v71, v70, v69
	v_fma_f32 v72, -v68, v71, v70
	v_fmac_f32_e32 v71, v72, v69
	v_fma_f32 v68, -v68, v71, v70
	v_div_fmas_f32 v68, v68, v69, v71
	v_div_fixup_f32 v67, v68, v67, 1.0
	v_div_scale_f32 v68, s[34:35], v66, v66, 1.0
	v_rcp_f32_e32 v69, v68
	v_cvt_pk_bf16_f32 v114, v126, v127
	v_pk_add_f32 v[48:49], v[48:49], 1.0 op_sel_hi:[1,0]
	v_mul_f32_e32 v50, v236, v50
	v_fma_f32 v70, -v68, v69, 1.0
	v_fmac_f32_e32 v69, v70, v69
	v_div_scale_f32 v70, vcc, 1.0, v66, 1.0
	v_mul_f32_e32 v71, v70, v69
	v_fma_f32 v72, -v68, v71, v70
	v_fmac_f32_e32 v71, v72, v69
	v_fma_f32 v68, -v68, v71, v70
	v_div_fmas_f32 v68, v68, v69, v71
	v_div_fixup_f32 v66, v68, v66, 1.0
	v_lshlrev_b32_e32 v70, 16, v168
	v_and_b32_e32 v71, 0xffff0000, v168
	v_pk_mul_f32 v[68:69], v[66:67], v[64:65]
	v_pk_fma_f32 v[64:65], v[66:67], v[64:65], v[70:71]
	v_mul_f32_e32 v66, v236, v134
	v_mul_f32_e32 v67, v236, v135
	v_exp_f32_e32 v66, v66
	v_exp_f32_e32 v67, v67
	v_cndmask_b32_e64 v64, v64, v68, s[0:1]
	v_cndmask_b32_e64 v65, v65, v69, s[0:1]
	v_cvt_pk_bf16_f32 v168, v64, v65
	v_pk_add_f32 v[66:67], v[66:67], 1.0 op_sel_hi:[1,0]
	v_lshlrev_b32_e32 v64, 16, v118
	v_div_scale_f32 v68, s[34:35], v67, v67, 1.0
	v_rcp_f32_e32 v69, v68
	v_and_b32_e32 v65, 0xffff0000, v118
	v_mul_f32_e32 v51, v236, v51
	v_exp_f32_e32 v50, v50
	v_fma_f32 v70, -v68, v69, 1.0
	v_fmac_f32_e32 v69, v70, v69
	v_div_scale_f32 v70, vcc, 1.0, v67, 1.0
	v_mul_f32_e32 v71, v70, v69
	v_fma_f32 v72, -v68, v71, v70
	v_fmac_f32_e32 v71, v72, v69
	v_fma_f32 v68, -v68, v71, v70
	v_div_fmas_f32 v68, v68, v69, v71
	v_div_fixup_f32 v67, v68, v67, 1.0
	v_div_scale_f32 v68, s[34:35], v66, v66, 1.0
	v_rcp_f32_e32 v69, v68
	v_exp_f32_e32 v51, v51
	v_cvt_pk_bf16_f32 v113, v96, v97
	v_cvt_pk_bf16_f32 v112, v98, v99
	v_fma_f32 v70, -v68, v69, 1.0
	v_fmac_f32_e32 v69, v70, v69
	v_div_scale_f32 v70, vcc, 1.0, v66, 1.0
	v_mul_f32_e32 v71, v70, v69
	v_fma_f32 v72, -v68, v71, v70
	v_fmac_f32_e32 v71, v72, v69
	v_fma_f32 v68, -v68, v71, v70
	v_div_fmas_f32 v68, v68, v69, v71
	v_div_fixup_f32 v66, v68, v66, 1.0
	v_lshlrev_b32_e32 v70, 16, v169
	v_and_b32_e32 v71, 0xffff0000, v169
	v_pk_mul_f32 v[68:69], v[66:67], v[64:65]
	v_pk_fma_f32 v[64:65], v[66:67], v[64:65], v[70:71]
; DI unsigned pack2(float a, float b) { f2_t v = {a, b}; bf2_t r = __builtin_convertvector(v, bf2_t); return __builtin_bit_cast(unsigned, r); }
; __global__ void __launch_bounds__(512) mega(Params p) {
;     ...
; #pragma unroll
;           for (int fb = 0; fb < 4; ++fb)
; #pragma unroll
;             for (int i = 0; i < 8; ++i) {
;               const float b0 = __uint_as_float(bp[fb][i] << 16), b1 = __uint_as_float(bp[fb][i] & 0xffff0000u);
;               const float g0 = 1.f / (1.f + __builtin_amdgcn_exp2f(nr1 * acc[fb][2 * i]));
;               const float g1 = 1.f / (1.f + __builtin_amdgcn_exp2f(nr1 * acc[fb][2 * i + 1]));
;               float y0 = g0 * b0, y1 = g1 * b1;
;               if (n > 0) { y0 += __uint_as_float(yp[fb][i] << 16); y1 += __uint_as_float(yp[fb][i] & 0xffff0000u); }
;               yp[fb][i] = pack2(y0, y1);
	v_mul_f32_e32 v66, v236, v136
	v_mul_f32_e32 v67, v236, v137
	v_exp_f32_e32 v66, v66
	v_exp_f32_e32 v67, v67
	v_cndmask_b32_e64 v64, v64, v68, s[0:1]
	v_cndmask_b32_e64 v65, v65, v69, s[0:1]
	v_cvt_pk_bf16_f32 v169, v64, v65
	v_pk_add_f32 v[66:67], v[66:67], 1.0 op_sel_hi:[1,0]
	v_lshlrev_b32_e32 v64, 16, v117
	v_div_scale_f32 v68, s[34:35], v67, v67, 1.0
	v_rcp_f32_e32 v69, v68
	v_and_b32_e32 v65, 0xffff0000, v117
	v_pk_add_f32 v[50:51], v[50:51], 1.0 op_sel_hi:[1,0]
	v_cvt_pk_bf16_f32 v101, v100, v101
	v_fma_f32 v70, -v68, v69, 1.0
	v_fmac_f32_e32 v69, v70, v69
	v_div_scale_f32 v70, vcc, 1.0, v67, 1.0
	v_mul_f32_e32 v71, v70, v69
	v_fma_f32 v72, -v68, v71, v70
	v_fmac_f32_e32 v71, v72, v69
	v_fma_f32 v68, -v68, v71, v70
	v_div_fmas_f32 v68, v68, v69, v71
	v_div_fixup_f32 v67, v68, v67, 1.0
	v_div_scale_f32 v68, s[34:35], v66, v66, 1.0
	v_rcp_f32_e32 v69, v68
	v_cvt_pk_bf16_f32 v100, v102, v103
	v_cvt_pk_bf16_f32 v99, v104, v105
	v_cvt_pk_bf16_f32 v98, v106, v107
	v_fma_f32 v70, -v68, v69, 1.0
	v_fmac_f32_e32 v69, v70, v69
	v_div_scale_f32 v70, vcc, 1.0, v66, 1.0
	v_mul_f32_e32 v71, v70, v69
	v_fma_f32 v72, -v68, v71, v70
	v_fmac_f32_e32 v71, v72, v69
	v_fma_f32 v68, -v68, v71, v70
	v_div_fmas_f32 v68, v68, v69, v71
	v_div_fixup_f32 v66, v68, v66, 1.0
	v_lshlrev_b32_e32 v70, 16, v170
	v_and_b32_e32 v71, 0xffff0000, v170
	v_pk_mul_f32 v[68:69], v[66:67], v[64:65]
	v_pk_fma_f32 v[64:65], v[66:67], v[64:65], v[70:71]
	v_mul_f32_e32 v66, v236, v138
	v_mul_f32_e32 v67, v236, v139
	v_exp_f32_e32 v66, v66
	v_exp_f32_e32 v67, v67
	v_cndmask_b32_e64 v64, v64, v68, s[0:1]
	v_cndmask_b32_e64 v65, v65, v69, s[0:1]
	v_cvt_pk_bf16_f32 v170, v64, v65
	v_pk_add_f32 v[66:67], v[66:67], 1.0 op_sel_hi:[1,0]
	v_lshlrev_b32_e32 v64, 16, v116
	v_div_scale_f32 v68, s[34:35], v67, v67, 1.0
	v_rcp_f32_e32 v69, v68
	v_and_b32_e32 v65, 0xffff0000, v116
	v_cvt_pk_bf16_f32 v97, v108, v109
	v_mul_f32_e32 v32, v236, v32
	v_fma_f32 v70, -v68, v69, 1.0
	v_fmac_f32_e32 v69, v70, v69
	v_div_scale_f32 v70, vcc, 1.0, v67, 1.0
	v_mul_f32_e32 v71, v70, v69
	v_fma_f32 v72, -v68, v71, v70
	v_fmac_f32_e32 v71, v72, v69
	v_fma_f32 v68, -v68, v71, v70
	v_div_fmas_f32 v68, v68, v69, v71
	v_div_fixup_f32 v67, v68, v67, 1.0
	v_div_scale_f32 v68, s[34:35], v66, v66, 1.0
	v_rcp_f32_e32 v69, v68
	v_mul_f32_e32 v33, v236, v33
	v_exp_f32_e32 v32, v32
	v_exp_f32_e32 v33, v33
	v_fma_f32 v70, -v68, v69, 1.0
	v_fmac_f32_e32 v69, v70, v69
	v_div_scale_f32 v70, vcc, 1.0, v66, 1.0
	v_mul_f32_e32 v71, v70, v69
	v_fma_f32 v72, -v68, v71, v70
	v_fmac_f32_e32 v71, v72, v69
	v_fma_f32 v68, -v68, v71, v70
	v_div_fmas_f32 v68, v68, v69, v71
	v_div_fixup_f32 v66, v68, v66, 1.0
	v_lshlrev_b32_e32 v70, 16, v171
	v_and_b32_e32 v71, 0xffff0000, v171
	v_pk_mul_f32 v[68:69], v[66:67], v[64:65]
	v_pk_fma_f32 v[64:65], v[66:67], v[64:65], v[70:71]
	v_mul_f32_e32 v66, v236, v140
	v_mul_f32_e32 v67, v236, v141
	v_exp_f32_e32 v66, v66
	v_exp_f32_e32 v67, v67
	v_cndmask_b32_e64 v64, v64, v68, s[0:1]
	v_cndmask_b32_e64 v65, v65, v69, s[0:1]
	v_cvt_pk_bf16_f32 v171, v64, v65
	v_pk_add_f32 v[66:67], v[66:67], 1.0 op_sel_hi:[1,0]
	v_lshlrev_b32_e32 v64, 16, v115
	v_div_scale_f32 v68, s[34:35], v67, v67, 1.0
	v_rcp_f32_e32 v69, v68
	v_and_b32_e32 v65, 0xffff0000, v115
	v_cvt_pk_bf16_f32 v96, v110, v111
	v_pk_add_f32 v[32:33], v[32:33], 1.0 op_sel_hi:[1,0]
	v_fma_f32 v70, -v68, v69, 1.0
	v_fmac_f32_e32 v69, v70, v69
	v_div_scale_f32 v70, vcc, 1.0, v67, 1.0
	v_mul_f32_e32 v71, v70, v69
	v_fma_f32 v72, -v68, v71, v70
	v_fmac_f32_e32 v71, v72, v69
	v_fma_f32 v68, -v68, v71, v70
	v_div_fmas_f32 v68, v68, v69, v71
	v_div_fixup_f32 v67, v68, v67, 1.0
	v_div_scale_f32 v68, s[34:35], v66, v66, 1.0
	v_rcp_f32_e32 v69, v68
	v_cvt_pk_bf16_f32 v80, v80, v81
	v_cvt_pk_bf16_f32 v15, v82, v83
	v_cvt_pk_bf16_f32 v14, v84, v85
	v_fma_f32 v70, -v68, v69, 1.0
	v_fmac_f32_e32 v69, v70, v69
	v_div_scale_f32 v70, vcc, 1.0, v66, 1.0
	v_mul_f32_e32 v71, v70, v69
	v_fma_f32 v72, -v68, v71, v70
	v_fmac_f32_e32 v71, v72, v69
	v_fma_f32 v68, -v68, v71, v70
	v_div_fmas_f32 v68, v68, v69, v71
	v_div_fixup_f32 v66, v68, v66, 1.0
	v_lshlrev_b32_e32 v70, 16, v172
	v_and_b32_e32 v71, 0xffff0000, v172
	v_pk_mul_f32 v[68:69], v[66:67], v[64:65]
	v_pk_fma_f32 v[64:65], v[66:67], v[64:65], v[70:71]
	v_mul_f32_e32 v66, v236, v142
	v_mul_f32_e32 v67, v236, v143
	v_exp_f32_e32 v66, v66
	v_exp_f32_e32 v67, v67
	v_cndmask_b32_e64 v64, v64, v68, s[0:1]
	v_cndmask_b32_e64 v65, v65, v69, s[0:1]
	v_cvt_pk_bf16_f32 v172, v64, v65
	v_pk_add_f32 v[66:67], v[66:67], 1.0 op_sel_hi:[1,0]
	v_lshlrev_b32_e32 v64, 16, v114
	v_div_scale_f32 v68, s[34:35], v67, v67, 1.0
	v_rcp_f32_e32 v69, v68
	v_and_b32_e32 v65, 0xffff0000, v114
	v_cvt_pk_bf16_f32 v13, v86, v87
	v_cvt_pk_bf16_f32 v12, v88, v89
	v_fma_f32 v70, -v68, v69, 1.0
	v_fmac_f32_e32 v69, v70, v69
	v_div_scale_f32 v70, vcc, 1.0, v67, 1.0
	v_mul_f32_e32 v71, v70, v69
	v_fma_f32 v72, -v68, v71, v70
	v_fmac_f32_e32 v71, v72, v69
	v_fma_f32 v68, -v68, v71, v70
	v_div_fmas_f32 v68, v68, v69, v71
	v_div_fixup_f32 v67, v68, v67, 1.0
	v_div_scale_f32 v68, s[34:35], v66, v66, 1.0
	v_rcp_f32_e32 v69, v68
	v_cvt_pk_bf16_f32 v11, v90, v91
	v_cvt_pk_bf16_f32 v10, v92, v93
	v_cvt_pk_bf16_f32 v9, v94, v95
	v_fma_f32 v70, -v68, v69, 1.0
	v_fmac_f32_e32 v69, v70, v69
	v_div_scale_f32 v70, vcc, 1.0, v66, 1.0
	v_mul_f32_e32 v71, v70, v69
	v_fma_f32 v72, -v68, v71, v70
	v_fmac_f32_e32 v71, v72, v69
	v_fma_f32 v68, -v68, v71, v70
	v_div_fmas_f32 v68, v68, v69, v71
	v_div_fixup_f32 v66, v68, v66, 1.0
	v_lshlrev_b32_e32 v70, 16, v173
	v_and_b32_e32 v71, 0xffff0000, v173
	v_pk_mul_f32 v[68:69], v[66:67], v[64:65]
; DI unsigned pack2(float a, float b) { f2_t v = {a, b}; bf2_t r = __builtin_convertvector(v, bf2_t); return __builtin_bit_cast(unsigned, r); }
; __global__ void __launch_bounds__(512) mega(Params p) {
;     ...
; #pragma unroll
;           for (int fb = 0; fb < 4; ++fb)
; #pragma unroll
;             for (int i = 0; i < 8; ++i) {
;               const float b0 = __uint_as_float(bp[fb][i] << 16), b1 = __uint_as_float(bp[fb][i] & 0xffff0000u);
;               const float g0 = 1.f / (1.f + __builtin_amdgcn_exp2f(nr1 * acc[fb][2 * i]));
;               const float g1 = 1.f / (1.f + __builtin_amdgcn_exp2f(nr1 * acc[fb][2 * i + 1]));
;               float y0 = g0 * b0, y1 = g1 * b1;
;               if (n > 0) { y0 += __uint_as_float(yp[fb][i] << 16); y1 += __uint_as_float(yp[fb][i] & 0xffff0000u); }
;               yp[fb][i] = pack2(y0, y1);
	v_pk_fma_f32 v[64:65], v[66:67], v[64:65], v[70:71]
	v_div_scale_f32 v66, s[34:35], v49, v49, 1.0
	v_rcp_f32_e32 v67, v66
	v_cndmask_b32_e64 v64, v64, v68, s[0:1]
	v_cndmask_b32_e64 v65, v65, v69, s[0:1]
	v_cvt_pk_bf16_f32 v173, v64, v65
	v_fma_f32 v68, -v66, v67, 1.0
	v_fmac_f32_e32 v67, v68, v67
	v_div_scale_f32 v68, vcc, 1.0, v49, 1.0
	v_mul_f32_e32 v69, v68, v67
	v_fma_f32 v70, -v66, v69, v68
	v_fmac_f32_e32 v69, v70, v67
	v_fma_f32 v66, -v66, v69, v68
	v_div_fmas_f32 v66, v66, v67, v69
	v_div_fixup_f32 v49, v66, v49, 1.0
	v_div_scale_f32 v66, s[34:35], v48, v48, 1.0
	v_rcp_f32_e32 v67, v66
	v_lshlrev_b32_e32 v64, 16, v113
	v_and_b32_e32 v65, 0xffff0000, v113
	v_cvt_pk_bf16_f32 v3, v74, v75
	v_fma_f32 v68, -v66, v67, 1.0
	v_fmac_f32_e32 v67, v68, v67
	v_div_scale_f32 v68, vcc, 1.0, v48, 1.0
	v_mul_f32_e32 v69, v68, v67
	v_fma_f32 v70, -v66, v69, v68
	v_fmac_f32_e32 v69, v70, v67
	v_fma_f32 v66, -v66, v69, v68
	v_div_fmas_f32 v66, v66, v67, v69
	v_div_fixup_f32 v48, v66, v48, 1.0
	v_lshlrev_b32_e32 v68, 16, v174
	v_and_b32_e32 v69, 0xffff0000, v174
	v_pk_mul_f32 v[66:67], v[48:49], v[64:65]
	v_pk_fma_f32 v[48:49], v[48:49], v[64:65], v[68:69]
	v_div_scale_f32 v64, s[34:35], v51, v51, 1.0
	v_rcp_f32_e32 v65, v64
	v_cndmask_b32_e64 v48, v48, v66, s[0:1]
	v_cndmask_b32_e64 v49, v49, v67, s[0:1]
	v_cvt_pk_bf16_f32 v174, v48, v49
	v_fma_f32 v66, -v64, v65, 1.0
	v_fmac_f32_e32 v65, v66, v65
	v_div_scale_f32 v66, vcc, 1.0, v51, 1.0
	v_mul_f32_e32 v67, v66, v65
	v_fma_f32 v68, -v64, v67, v66
	v_fmac_f32_e32 v67, v68, v65
	v_fma_f32 v64, -v64, v67, v66
	v_div_fmas_f32 v64, v64, v65, v67
	v_div_fixup_f32 v51, v64, v51, 1.0
	v_div_scale_f32 v64, s[34:35], v50, v50, 1.0
	v_rcp_f32_e32 v65, v64
	v_lshlrev_b32_e32 v48, 16, v112
	v_and_b32_e32 v49, 0xffff0000, v112
	v_cvt_pk_bf16_f32 v2, v76, v77
	v_fma_f32 v66, -v64, v65, 1.0
	v_fmac_f32_e32 v65, v66, v65
	v_div_scale_f32 v66, vcc, 1.0, v50, 1.0
	v_mul_f32_e32 v67, v66, v65
	v_fma_f32 v68, -v64, v67, v66
	v_fmac_f32_e32 v67, v68, v65
	v_fma_f32 v64, -v64, v67, v66
	v_div_fmas_f32 v64, v64, v65, v67
	v_div_fixup_f32 v50, v64, v50, 1.0
	v_lshlrev_b32_e32 v66, 16, v175
	v_and_b32_e32 v67, 0xffff0000, v175
	v_pk_mul_f32 v[64:65], v[50:51], v[48:49]
	v_pk_fma_f32 v[48:49], v[50:51], v[48:49], v[66:67]
	v_mul_f32_e32 v50, v236, v52
	v_mul_f32_e32 v51, v236, v53
	v_exp_f32_e32 v50, v50
	v_exp_f32_e32 v51, v51
	v_cndmask_b32_e64 v48, v48, v64, s[0:1]
	v_cndmask_b32_e64 v49, v49, v65, s[0:1]
	v_cvt_pk_bf16_f32 v175, v48, v49
	v_pk_add_f32 v[50:51], v[50:51], 1.0 op_sel_hi:[1,0]
	v_lshlrev_b32_e32 v48, 16, v101
	v_div_scale_f32 v52, s[34:35], v51, v51, 1.0
	v_rcp_f32_e32 v53, v52
	v_and_b32_e32 v49, 0xffff0000, v101
	v_cvt_pk_bf16_f32 v0, v78, v79
	s_add_i32 s8, s8, 1
	v_fma_f32 v64, -v52, v53, 1.0
	v_fmac_f32_e32 v53, v64, v53
	v_div_scale_f32 v64, vcc, 1.0, v51, 1.0
	v_mul_f32_e32 v65, v64, v53
	v_fma_f32 v66, -v52, v65, v64
	v_fmac_f32_e32 v65, v66, v53
	v_fma_f32 v52, -v52, v65, v64
	v_div_fmas_f32 v52, v52, v53, v65
	v_div_fixup_f32 v51, v52, v51, 1.0
	v_div_scale_f32 v52, s[34:35], v50, v50, 1.0
	v_rcp_f32_e32 v53, v52
	s_cmp_eq_u32 s8, 3
	v_fma_f32 v64, -v52, v53, 1.0
	v_fmac_f32_e32 v53, v64, v53
	v_div_scale_f32 v64, vcc, 1.0, v50, 1.0
	v_mul_f32_e32 v65, v64, v53
	v_fma_f32 v66, -v52, v65, v64
	v_fmac_f32_e32 v65, v66, v53
	v_fma_f32 v52, -v52, v65, v64
	v_div_fmas_f32 v52, v52, v53, v65
	v_div_fixup_f32 v50, v52, v50, 1.0
	v_lshlrev_b32_e32 v64, 16, v176
	v_and_b32_e32 v65, 0xffff0000, v176
	v_pk_mul_f32 v[52:53], v[50:51], v[48:49]
	v_pk_fma_f32 v[48:49], v[50:51], v[48:49], v[64:65]
	v_mul_f32_e32 v50, v236, v54
	v_mul_f32_e32 v51, v236, v55
	v_exp_f32_e32 v50, v50
	v_exp_f32_e32 v51, v51
	v_cndmask_b32_e64 v48, v48, v52, s[0:1]
	v_cndmask_b32_e64 v49, v49, v53, s[0:1]
	v_cvt_pk_bf16_f32 v176, v48, v49
	v_pk_add_f32 v[50:51], v[50:51], 1.0 op_sel_hi:[1,0]
	v_lshlrev_b32_e32 v48, 16, v100
	v_div_scale_f32 v52, s[34:35], v51, v51, 1.0
	v_rcp_f32_e32 v53, v52
	v_and_b32_e32 v49, 0xffff0000, v100
	v_fma_f32 v54, -v52, v53, 1.0
	v_fmac_f32_e32 v53, v54, v53
	v_div_scale_f32 v54, vcc, 1.0, v51, 1.0
	v_mul_f32_e32 v55, v54, v53
	v_fma_f32 v64, -v52, v55, v54
	v_fmac_f32_e32 v55, v64, v53
	v_fma_f32 v52, -v52, v55, v54
	v_div_fmas_f32 v52, v52, v53, v55
	v_div_fixup_f32 v51, v52, v51, 1.0
	v_div_scale_f32 v52, s[34:35], v50, v50, 1.0
	v_rcp_f32_e32 v53, v52
	s_nop 0
	v_fma_f32 v54, -v52, v53, 1.0
	v_fmac_f32_e32 v53, v54, v53
	v_div_scale_f32 v54, vcc, 1.0, v50, 1.0
	v_mul_f32_e32 v55, v54, v53
	v_fma_f32 v64, -v52, v55, v54
	v_fmac_f32_e32 v55, v64, v53
	v_fma_f32 v52, -v52, v55, v54
	v_div_fmas_f32 v52, v52, v53, v55
	v_div_fixup_f32 v50, v52, v50, 1.0
	v_lshlrev_b32_e32 v54, 16, v177
	v_and_b32_e32 v55, 0xffff0000, v177
	v_pk_mul_f32 v[52:53], v[50:51], v[48:49]
	v_pk_fma_f32 v[48:49], v[50:51], v[48:49], v[54:55]
	v_mul_f32_e32 v50, v236, v56
	v_mul_f32_e32 v51, v236, v57
	v_exp_f32_e32 v50, v50
	v_exp_f32_e32 v51, v51
	v_cndmask_b32_e64 v48, v48, v52, s[0:1]
	v_cndmask_b32_e64 v49, v49, v53, s[0:1]
	v_cvt_pk_bf16_f32 v177, v48, v49
	v_pk_add_f32 v[50:51], v[50:51], 1.0 op_sel_hi:[1,0]
	v_lshlrev_b32_e32 v48, 16, v99
	v_div_scale_f32 v52, s[34:35], v51, v51, 1.0
	v_rcp_f32_e32 v53, v52
	v_and_b32_e32 v49, 0xffff0000, v99
	v_fma_f32 v54, -v52, v53, 1.0
	v_fmac_f32_e32 v53, v54, v53
	v_div_scale_f32 v54, vcc, 1.0, v51, 1.0
	v_mul_f32_e32 v55, v54, v53
	v_fma_f32 v56, -v52, v55, v54
	v_fmac_f32_e32 v55, v56, v53
	v_fma_f32 v52, -v52, v55, v54
	v_div_fmas_f32 v52, v52, v53, v55
	v_div_fixup_f32 v51, v52, v51, 1.0
	v_div_scale_f32 v52, s[34:35], v50, v50, 1.0
	v_rcp_f32_e32 v53, v52
	s_nop 0
; DI unsigned pack2(float a, float b) { f2_t v = {a, b}; bf2_t r = __builtin_convertvector(v, bf2_t); return __builtin_bit_cast(unsigned, r); }
; __global__ void __launch_bounds__(512) mega(Params p) {
;     ...
; #pragma unroll
;           for (int fb = 0; fb < 4; ++fb)
; #pragma unroll
;             for (int i = 0; i < 8; ++i) {
;               const float b0 = __uint_as_float(bp[fb][i] << 16), b1 = __uint_as_float(bp[fb][i] & 0xffff0000u);
;               const float g0 = 1.f / (1.f + __builtin_amdgcn_exp2f(nr1 * acc[fb][2 * i]));
;               const float g1 = 1.f / (1.f + __builtin_amdgcn_exp2f(nr1 * acc[fb][2 * i + 1]));
;               float y0 = g0 * b0, y1 = g1 * b1;
;               if (n > 0) { y0 += __uint_as_float(yp[fb][i] << 16); y1 += __uint_as_float(yp[fb][i] & 0xffff0000u); }
;               yp[fb][i] = pack2(y0, y1);
	v_fma_f32 v54, -v52, v53, 1.0
	v_fmac_f32_e32 v53, v54, v53
	v_div_scale_f32 v54, vcc, 1.0, v50, 1.0
	v_mul_f32_e32 v55, v54, v53
	v_fma_f32 v56, -v52, v55, v54
	v_fmac_f32_e32 v55, v56, v53
	v_fma_f32 v52, -v52, v55, v54
	v_div_fmas_f32 v52, v52, v53, v55
	v_div_fixup_f32 v50, v52, v50, 1.0
	v_lshlrev_b32_e32 v54, 16, v178
	v_and_b32_e32 v55, 0xffff0000, v178
	v_pk_mul_f32 v[52:53], v[50:51], v[48:49]
	v_pk_fma_f32 v[48:49], v[50:51], v[48:49], v[54:55]
	v_mul_f32_e32 v50, v236, v58
	v_mul_f32_e32 v51, v236, v59
	v_exp_f32_e32 v50, v50
	v_exp_f32_e32 v51, v51
	v_cndmask_b32_e64 v48, v48, v52, s[0:1]
	v_cndmask_b32_e64 v49, v49, v53, s[0:1]
	v_cvt_pk_bf16_f32 v178, v48, v49
	v_pk_add_f32 v[50:51], v[50:51], 1.0 op_sel_hi:[1,0]
	v_lshlrev_b32_e32 v48, 16, v98
	v_div_scale_f32 v52, s[34:35], v51, v51, 1.0
	v_rcp_f32_e32 v53, v52
	v_and_b32_e32 v49, 0xffff0000, v98
	v_fma_f32 v54, -v52, v53, 1.0
	v_fmac_f32_e32 v53, v54, v53
	v_div_scale_f32 v54, vcc, 1.0, v51, 1.0
	v_mul_f32_e32 v55, v54, v53
	v_fma_f32 v56, -v52, v55, v54
	v_fmac_f32_e32 v55, v56, v53
	v_fma_f32 v52, -v52, v55, v54
	v_div_fmas_f32 v52, v52, v53, v55
	v_div_fixup_f32 v51, v52, v51, 1.0
	v_div_scale_f32 v52, s[34:35], v50, v50, 1.0
	v_rcp_f32_e32 v53, v52
	s_nop 0
	v_fma_f32 v54, -v52, v53, 1.0
	v_fmac_f32_e32 v53, v54, v53
	v_div_scale_f32 v54, vcc, 1.0, v50, 1.0
	v_mul_f32_e32 v55, v54, v53
	v_fma_f32 v56, -v52, v55, v54
	v_fmac_f32_e32 v55, v56, v53
	v_fma_f32 v52, -v52, v55, v54
	v_div_fmas_f32 v52, v52, v53, v55
	v_div_fixup_f32 v50, v52, v50, 1.0
	v_lshlrev_b32_e32 v54, 16, v179
	v_and_b32_e32 v55, 0xffff0000, v179
	v_pk_mul_f32 v[52:53], v[50:51], v[48:49]
	v_pk_fma_f32 v[48:49], v[50:51], v[48:49], v[54:55]
	v_mul_f32_e32 v50, v236, v60
	v_mul_f32_e32 v51, v236, v61
	v_exp_f32_e32 v50, v50
	v_exp_f32_e32 v51, v51
	v_cndmask_b32_e64 v48, v48, v52, s[0:1]
	v_cndmask_b32_e64 v49, v49, v53, s[0:1]
	v_cvt_pk_bf16_f32 v179, v48, v49
	v_pk_add_f32 v[50:51], v[50:51], 1.0 op_sel_hi:[1,0]
	v_lshlrev_b32_e32 v48, 16, v97
	v_div_scale_f32 v52, s[34:35], v51, v51, 1.0
	v_rcp_f32_e32 v53, v52
	v_and_b32_e32 v49, 0xffff0000, v97
	v_fma_f32 v54, -v52, v53, 1.0
	v_fmac_f32_e32 v53, v54, v53
	v_div_scale_f32 v54, vcc, 1.0, v51, 1.0
	v_mul_f32_e32 v55, v54, v53
	v_fma_f32 v56, -v52, v55, v54
	v_fmac_f32_e32 v55, v56, v53
	v_fma_f32 v52, -v52, v55, v54
	v_div_fmas_f32 v52, v52, v53, v55
	v_div_fixup_f32 v51, v52, v51, 1.0
	v_div_scale_f32 v52, s[34:35], v50, v50, 1.0
	v_rcp_f32_e32 v53, v52
	s_nop 0
	v_fma_f32 v54, -v52, v53, 1.0
	v_fmac_f32_e32 v53, v54, v53
	v_div_scale_f32 v54, vcc, 1.0, v50, 1.0
	v_mul_f32_e32 v55, v54, v53
	v_fma_f32 v56, -v52, v55, v54
	v_fmac_f32_e32 v55, v56, v53
	v_fma_f32 v52, -v52, v55, v54
	v_div_fmas_f32 v52, v52, v53, v55
	v_div_fixup_f32 v50, v52, v50, 1.0
	v_lshlrev_b32_e32 v54, 16, v164
	v_and_b32_e32 v55, 0xffff0000, v164
	v_pk_mul_f32 v[52:53], v[50:51], v[48:49]
	v_pk_fma_f32 v[48:49], v[50:51], v[48:49], v[54:55]
	v_mul_f32_e32 v50, v236, v62
	v_mul_f32_e32 v51, v236, v63
	v_exp_f32_e32 v50, v50
	v_exp_f32_e32 v51, v51
	v_cndmask_b32_e64 v48, v48, v52, s[0:1]
	v_cndmask_b32_e64 v49, v49, v53, s[0:1]
	v_cvt_pk_bf16_f32 v164, v48, v49
	v_pk_add_f32 v[50:51], v[50:51], 1.0 op_sel_hi:[1,0]
	v_lshlrev_b32_e32 v48, 16, v96
	v_div_scale_f32 v52, s[34:35], v51, v51, 1.0
	v_rcp_f32_e32 v53, v52
	v_and_b32_e32 v49, 0xffff0000, v96
	v_fma_f32 v54, -v52, v53, 1.0
	v_fmac_f32_e32 v53, v54, v53
	v_div_scale_f32 v54, vcc, 1.0, v51, 1.0
	v_mul_f32_e32 v55, v54, v53
	v_fma_f32 v56, -v52, v55, v54
	v_fmac_f32_e32 v55, v56, v53
	v_fma_f32 v52, -v52, v55, v54
	v_div_fmas_f32 v52, v52, v53, v55
	v_div_fixup_f32 v51, v52, v51, 1.0
	v_div_scale_f32 v52, s[34:35], v50, v50, 1.0
	v_rcp_f32_e32 v53, v52
	s_nop 0
	v_fma_f32 v54, -v52, v53, 1.0
	v_fmac_f32_e32 v53, v54, v53
	v_div_scale_f32 v54, vcc, 1.0, v50, 1.0
	v_mul_f32_e32 v55, v54, v53
	v_fma_f32 v56, -v52, v55, v54
	v_fmac_f32_e32 v55, v56, v53
	v_fma_f32 v52, -v52, v55, v54
	v_div_fmas_f32 v52, v52, v53, v55
	v_div_fixup_f32 v50, v52, v50, 1.0
	v_lshlrev_b32_e32 v54, 16, v165
	v_and_b32_e32 v55, 0xffff0000, v165
	v_pk_mul_f32 v[52:53], v[50:51], v[48:49]
	v_pk_fma_f32 v[48:49], v[50:51], v[48:49], v[54:55]
	v_div_scale_f32 v50, s[34:35], v33, v33, 1.0
	v_rcp_f32_e32 v51, v50
	v_cndmask_b32_e64 v48, v48, v52, s[0:1]
	v_cndmask_b32_e64 v49, v49, v53, s[0:1]
	v_cvt_pk_bf16_f32 v165, v48, v49
	v_fma_f32 v52, -v50, v51, 1.0
	v_fmac_f32_e32 v51, v52, v51
	v_div_scale_f32 v52, vcc, 1.0, v33, 1.0
	v_mul_f32_e32 v53, v52, v51
	v_fma_f32 v54, -v50, v53, v52
	v_fmac_f32_e32 v53, v54, v51
	v_fma_f32 v50, -v50, v53, v52
	v_div_fmas_f32 v50, v50, v51, v53
	v_div_fixup_f32 v33, v50, v33, 1.0
	v_div_scale_f32 v50, s[34:35], v32, v32, 1.0
	v_rcp_f32_e32 v51, v50
	v_lshlrev_b32_e32 v48, 16, v80
	v_and_b32_e32 v49, 0xffff0000, v80
	v_fma_f32 v52, -v50, v51, 1.0
	v_fmac_f32_e32 v51, v52, v51
	v_div_scale_f32 v52, vcc, 1.0, v32, 1.0
	v_mul_f32_e32 v53, v52, v51
	v_fma_f32 v54, -v50, v53, v52
	v_fmac_f32_e32 v53, v54, v51
	v_fma_f32 v50, -v50, v53, v52
	v_div_fmas_f32 v50, v50, v51, v53
	v_div_fixup_f32 v32, v50, v32, 1.0
	v_lshlrev_b32_e32 v52, 16, v162
	v_and_b32_e32 v53, 0xffff0000, v162
	v_pk_mul_f32 v[50:51], v[32:33], v[48:49]
	v_pk_fma_f32 v[32:33], v[32:33], v[48:49], v[52:53]
	s_nop 0
	v_cndmask_b32_e64 v33, v33, v51, s[0:1]
	v_cndmask_b32_e64 v32, v32, v50, s[0:1]
	v_cvt_pk_bf16_f32 v162, v32, v33
	v_lshlrev_b32_e32 v32, 16, v15
	v_and_b32_e32 v33, 0xffff0000, v15
	v_mul_f32_e32 v15, v236, v34
	v_exp_f32_e32 v34, v15
	v_mul_f32_e32 v15, v236, v35
	v_exp_f32_e32 v35, v15
	s_nop 0
	v_pk_add_f32 v[34:35], v[34:35], 1.0 op_sel_hi:[1,0]
; DI unsigned pack2(float a, float b) { f2_t v = {a, b}; bf2_t r = __builtin_convertvector(v, bf2_t); return __builtin_bit_cast(unsigned, r); }
; __global__ void __launch_bounds__(512) mega(Params p) {
;     ...
; #pragma unroll
;           for (int fb = 0; fb < 4; ++fb)
; #pragma unroll
;             for (int i = 0; i < 8; ++i) {
;               const float b0 = __uint_as_float(bp[fb][i] << 16), b1 = __uint_as_float(bp[fb][i] & 0xffff0000u);
;               const float g0 = 1.f / (1.f + __builtin_amdgcn_exp2f(nr1 * acc[fb][2 * i]));
;               const float g1 = 1.f / (1.f + __builtin_amdgcn_exp2f(nr1 * acc[fb][2 * i + 1]));
;               float y0 = g0 * b0, y1 = g1 * b1;
;               if (n > 0) { y0 += __uint_as_float(yp[fb][i] << 16); y1 += __uint_as_float(yp[fb][i] & 0xffff0000u); }
;               yp[fb][i] = pack2(y0, y1);
	s_nop 0
	v_div_scale_f32 v15, s[34:35], v35, v35, 1.0
	v_rcp_f32_e32 v48, v15
	s_nop 0
	v_fma_f32 v49, -v15, v48, 1.0
	v_fmac_f32_e32 v48, v49, v48
	v_div_scale_f32 v49, vcc, 1.0, v35, 1.0
	v_mul_f32_e32 v50, v49, v48
	v_fma_f32 v51, -v15, v50, v49
	v_fmac_f32_e32 v50, v51, v48
	v_fma_f32 v15, -v15, v50, v49
	v_div_fmas_f32 v15, v15, v48, v50
	v_div_fixup_f32 v35, v15, v35, 1.0
	v_div_scale_f32 v15, s[34:35], v34, v34, 1.0
	v_rcp_f32_e32 v48, v15
	s_nop 0
	v_fma_f32 v49, -v15, v48, 1.0
	v_fmac_f32_e32 v48, v49, v48
	v_div_scale_f32 v49, vcc, 1.0, v34, 1.0
	v_mul_f32_e32 v50, v49, v48
	v_fma_f32 v51, -v15, v50, v49
	v_fmac_f32_e32 v50, v51, v48
	v_fma_f32 v15, -v15, v50, v49
	v_div_fmas_f32 v15, v15, v48, v50
	v_div_fixup_f32 v34, v15, v34, 1.0
	v_lshlrev_b32_e32 v50, 16, v163
	v_and_b32_e32 v51, 0xffff0000, v163
	v_pk_mul_f32 v[48:49], v[34:35], v[32:33]
	v_pk_fma_f32 v[32:33], v[34:35], v[32:33], v[50:51]
	s_nop 0
	v_cndmask_b32_e64 v15, v33, v49, s[0:1]
	v_cndmask_b32_e64 v32, v32, v48, s[0:1]
	v_cvt_pk_bf16_f32 v163, v32, v15
	v_lshlrev_b32_e32 v32, 16, v14
	v_and_b32_e32 v33, 0xffff0000, v14
	v_mul_f32_e32 v14, v236, v36
	v_mul_f32_e32 v15, v236, v37
	v_exp_f32_e32 v14, v14
	v_exp_f32_e32 v15, v15
	s_nop 0
	v_pk_add_f32 v[14:15], v[14:15], 1.0 op_sel_hi:[1,0]
	s_nop 0
	v_div_scale_f32 v34, s[34:35], v15, v15, 1.0
	v_rcp_f32_e32 v35, v34
	s_nop 0
	v_fma_f32 v36, -v34, v35, 1.0
	v_fmac_f32_e32 v35, v36, v35
	v_div_scale_f32 v36, vcc, 1.0, v15, 1.0
	v_mul_f32_e32 v37, v36, v35
	v_fma_f32 v48, -v34, v37, v36
	v_fmac_f32_e32 v37, v48, v35
	v_fma_f32 v34, -v34, v37, v36
	v_div_fmas_f32 v34, v34, v35, v37
	v_div_fixup_f32 v15, v34, v15, 1.0
	v_div_scale_f32 v34, s[34:35], v14, v14, 1.0
	v_rcp_f32_e32 v35, v34
	s_nop 0
	v_fma_f32 v36, -v34, v35, 1.0
	v_fmac_f32_e32 v35, v36, v35
	v_div_scale_f32 v36, vcc, 1.0, v14, 1.0
	v_mul_f32_e32 v37, v36, v35
	v_fma_f32 v48, -v34, v37, v36
	v_fmac_f32_e32 v37, v48, v35
	v_fma_f32 v34, -v34, v37, v36
	v_div_fmas_f32 v34, v34, v35, v37
	v_div_fixup_f32 v14, v34, v14, 1.0
	v_lshlrev_b32_e32 v36, 16, v160
	v_and_b32_e32 v37, 0xffff0000, v160
	v_pk_mul_f32 v[34:35], v[14:15], v[32:33]
	v_pk_fma_f32 v[14:15], v[14:15], v[32:33], v[36:37]
	s_nop 0
	v_cndmask_b32_e64 v15, v15, v35, s[0:1]
	v_cndmask_b32_e64 v14, v14, v34, s[0:1]
	v_cvt_pk_bf16_f32 v160, v14, v15
	v_lshlrev_b32_e32 v14, 16, v13
	v_and_b32_e32 v15, 0xffff0000, v13
	v_mul_f32_e32 v13, v236, v38
	v_exp_f32_e32 v32, v13
	v_mul_f32_e32 v13, v236, v39
	v_exp_f32_e32 v33, v13
	s_nop 0
	v_pk_add_f32 v[32:33], v[32:33], 1.0 op_sel_hi:[1,0]
	s_nop 0
	v_div_scale_f32 v13, s[34:35], v33, v33, 1.0
	v_rcp_f32_e32 v34, v13
	s_nop 0
	v_fma_f32 v35, -v13, v34, 1.0
	v_fmac_f32_e32 v34, v35, v34
	v_div_scale_f32 v35, vcc, 1.0, v33, 1.0
	v_mul_f32_e32 v36, v35, v34
	v_fma_f32 v37, -v13, v36, v35
	v_fmac_f32_e32 v36, v37, v34
	v_fma_f32 v13, -v13, v36, v35
	v_div_fmas_f32 v13, v13, v34, v36
	v_div_fixup_f32 v33, v13, v33, 1.0
	v_div_scale_f32 v13, s[34:35], v32, v32, 1.0
	v_rcp_f32_e32 v34, v13
	s_nop 0
	v_fma_f32 v35, -v13, v34, 1.0
	v_fmac_f32_e32 v34, v35, v34
	v_div_scale_f32 v35, vcc, 1.0, v32, 1.0
	v_mul_f32_e32 v36, v35, v34
	v_fma_f32 v37, -v13, v36, v35
	v_fmac_f32_e32 v36, v37, v34
	v_fma_f32 v13, -v13, v36, v35
	v_div_fmas_f32 v13, v13, v34, v36
	v_div_fixup_f32 v32, v13, v32, 1.0
	v_lshlrev_b32_e32 v36, 16, v161
	v_and_b32_e32 v37, 0xffff0000, v161
	v_pk_mul_f32 v[34:35], v[32:33], v[14:15]
	v_pk_fma_f32 v[14:15], v[32:33], v[14:15], v[36:37]
	s_nop 0
	v_cndmask_b32_e64 v13, v15, v35, s[0:1]
	v_cndmask_b32_e64 v14, v14, v34, s[0:1]
	v_cvt_pk_bf16_f32 v161, v14, v13
	v_lshlrev_b32_e32 v14, 16, v12
	v_and_b32_e32 v15, 0xffff0000, v12
	v_mul_f32_e32 v12, v236, v40
	v_mul_f32_e32 v13, v236, v41
	v_exp_f32_e32 v12, v12
	v_exp_f32_e32 v13, v13
	s_nop 0
	v_pk_add_f32 v[12:13], v[12:13], 1.0 op_sel_hi:[1,0]
	s_nop 0
	v_div_scale_f32 v32, s[34:35], v13, v13, 1.0
	v_rcp_f32_e32 v33, v32
	s_nop 0
	v_fma_f32 v34, -v32, v33, 1.0
	v_fmac_f32_e32 v33, v34, v33
	v_div_scale_f32 v34, vcc, 1.0, v13, 1.0
	v_mul_f32_e32 v35, v34, v33
	v_fma_f32 v36, -v32, v35, v34
	v_fmac_f32_e32 v35, v36, v33
	v_fma_f32 v32, -v32, v35, v34
	v_div_fmas_f32 v32, v32, v33, v35
	v_div_fixup_f32 v13, v32, v13, 1.0
	v_div_scale_f32 v32, s[34:35], v12, v12, 1.0
	v_rcp_f32_e32 v33, v32
	s_nop 0
	v_fma_f32 v34, -v32, v33, 1.0
	v_fmac_f32_e32 v33, v34, v33
	v_div_scale_f32 v34, vcc, 1.0, v12, 1.0
	v_mul_f32_e32 v35, v34, v33
	v_fma_f32 v36, -v32, v35, v34
	v_fmac_f32_e32 v35, v36, v33
	v_fma_f32 v32, -v32, v35, v34
	v_div_fmas_f32 v32, v32, v33, v35
	v_div_fixup_f32 v12, v32, v12, 1.0
	v_lshlrev_b32_e32 v34, 16, v158
	v_and_b32_e32 v35, 0xffff0000, v158
	v_pk_mul_f32 v[32:33], v[12:13], v[14:15]
	v_pk_fma_f32 v[12:13], v[12:13], v[14:15], v[34:35]
	s_nop 0
	v_cndmask_b32_e64 v13, v13, v33, s[0:1]
	v_cndmask_b32_e64 v12, v12, v32, s[0:1]
	v_cvt_pk_bf16_f32 v158, v12, v13
	v_lshlrev_b32_e32 v12, 16, v11
	v_and_b32_e32 v13, 0xffff0000, v11
	v_mul_f32_e32 v11, v236, v42
	v_exp_f32_e32 v14, v11
	v_mul_f32_e32 v11, v236, v43
	v_exp_f32_e32 v15, v11
	s_nop 0
	v_pk_add_f32 v[14:15], v[14:15], 1.0 op_sel_hi:[1,0]
	s_nop 0
	v_div_scale_f32 v11, s[34:35], v15, v15, 1.0
	v_rcp_f32_e32 v32, v11
	s_nop 0
	v_fma_f32 v33, -v11, v32, 1.0
	v_fmac_f32_e32 v32, v33, v32
	v_div_scale_f32 v33, vcc, 1.0, v15, 1.0
	v_mul_f32_e32 v34, v33, v32
	v_fma_f32 v35, -v11, v34, v33
	v_fmac_f32_e32 v34, v35, v32
	v_fma_f32 v11, -v11, v34, v33
	v_div_fmas_f32 v11, v11, v32, v34
	v_div_fixup_f32 v15, v11, v15, 1.0
	v_div_scale_f32 v11, s[34:35], v14, v14, 1.0
	v_rcp_f32_e32 v32, v11
	s_nop 0
	v_fma_f32 v33, -v11, v32, 1.0
; DI unsigned pack2(float a, float b) { f2_t v = {a, b}; bf2_t r = __builtin_convertvector(v, bf2_t); return __builtin_bit_cast(unsigned, r); }
; __global__ void __launch_bounds__(512) mega(Params p) {
;     ...
; #pragma unroll
;           for (int fb = 0; fb < 4; ++fb)
; #pragma unroll
;             for (int i = 0; i < 8; ++i) {
;               const float b0 = __uint_as_float(bp[fb][i] << 16), b1 = __uint_as_float(bp[fb][i] & 0xffff0000u);
;               const float g0 = 1.f / (1.f + __builtin_amdgcn_exp2f(nr1 * acc[fb][2 * i]));
;               const float g1 = 1.f / (1.f + __builtin_amdgcn_exp2f(nr1 * acc[fb][2 * i + 1]));
;               float y0 = g0 * b0, y1 = g1 * b1;
;               if (n > 0) { y0 += __uint_as_float(yp[fb][i] << 16); y1 += __uint_as_float(yp[fb][i] & 0xffff0000u); }
;               yp[fb][i] = pack2(y0, y1);
	v_fmac_f32_e32 v32, v33, v32
	v_div_scale_f32 v33, vcc, 1.0, v14, 1.0
	v_mul_f32_e32 v34, v33, v32
	v_fma_f32 v35, -v11, v34, v33
	v_fmac_f32_e32 v34, v35, v32
	v_fma_f32 v11, -v11, v34, v33
	v_div_fmas_f32 v11, v11, v32, v34
	v_div_fixup_f32 v14, v11, v14, 1.0
	v_lshlrev_b32_e32 v34, 16, v159
	v_and_b32_e32 v35, 0xffff0000, v159
	v_pk_mul_f32 v[32:33], v[14:15], v[12:13]
	v_pk_fma_f32 v[12:13], v[14:15], v[12:13], v[34:35]
	s_nop 0
	v_cndmask_b32_e64 v11, v13, v33, s[0:1]
	v_cndmask_b32_e64 v12, v12, v32, s[0:1]
	v_cvt_pk_bf16_f32 v159, v12, v11
	v_lshlrev_b32_e32 v12, 16, v10
	v_and_b32_e32 v13, 0xffff0000, v10
	v_mul_f32_e32 v10, v236, v44
	v_mul_f32_e32 v11, v236, v45
	v_exp_f32_e32 v10, v10
	v_exp_f32_e32 v11, v11
	s_nop 0
	v_pk_add_f32 v[10:11], v[10:11], 1.0 op_sel_hi:[1,0]
	s_nop 0
	v_div_scale_f32 v14, s[34:35], v11, v11, 1.0
	v_rcp_f32_e32 v15, v14
	s_nop 0
	v_fma_f32 v32, -v14, v15, 1.0
	v_fmac_f32_e32 v15, v32, v15
	v_div_scale_f32 v32, vcc, 1.0, v11, 1.0
	v_mul_f32_e32 v33, v32, v15
	v_fma_f32 v34, -v14, v33, v32
	v_fmac_f32_e32 v33, v34, v15
	v_fma_f32 v14, -v14, v33, v32
	v_div_fmas_f32 v14, v14, v15, v33
	v_div_fixup_f32 v11, v14, v11, 1.0
	v_div_scale_f32 v14, s[34:35], v10, v10, 1.0
	v_rcp_f32_e32 v15, v14
	s_nop 0
	v_fma_f32 v32, -v14, v15, 1.0
	v_fmac_f32_e32 v15, v32, v15
	v_div_scale_f32 v32, vcc, 1.0, v10, 1.0
	v_mul_f32_e32 v33, v32, v15
	v_fma_f32 v34, -v14, v33, v32
	v_fmac_f32_e32 v33, v34, v15
	v_fma_f32 v14, -v14, v33, v32
	v_div_fmas_f32 v14, v14, v15, v33
	v_div_fixup_f32 v10, v14, v10, 1.0
	v_lshlrev_b32_e32 v32, 16, v156
	v_and_b32_e32 v33, 0xffff0000, v156
	v_pk_mul_f32 v[14:15], v[10:11], v[12:13]
	v_pk_fma_f32 v[10:11], v[10:11], v[12:13], v[32:33]
	s_nop 0
	v_cndmask_b32_e64 v11, v11, v15, s[0:1]
	v_cndmask_b32_e64 v10, v10, v14, s[0:1]
	v_cvt_pk_bf16_f32 v156, v10, v11
	v_lshlrev_b32_e32 v10, 16, v9
	v_and_b32_e32 v11, 0xffff0000, v9
	v_mul_f32_e32 v9, v236, v46
	v_exp_f32_e32 v12, v9
	v_mul_f32_e32 v9, v236, v47
	v_exp_f32_e32 v13, v9
	s_nop 0
	v_pk_add_f32 v[12:13], v[12:13], 1.0 op_sel_hi:[1,0]
	s_nop 0
	v_div_scale_f32 v9, s[34:35], v13, v13, 1.0
	v_rcp_f32_e32 v14, v9
	s_nop 0
	v_fma_f32 v15, -v9, v14, 1.0
	v_fmac_f32_e32 v14, v15, v14
	v_div_scale_f32 v15, vcc, 1.0, v13, 1.0
	v_mul_f32_e32 v32, v15, v14
	v_fma_f32 v33, -v9, v32, v15
	v_fmac_f32_e32 v32, v33, v14
	v_fma_f32 v9, -v9, v32, v15
	v_div_fmas_f32 v9, v9, v14, v32
	v_div_fixup_f32 v13, v9, v13, 1.0
	v_div_scale_f32 v9, s[34:35], v12, v12, 1.0
	v_rcp_f32_e32 v14, v9
	s_nop 0
	v_fma_f32 v15, -v9, v14, 1.0
	v_fmac_f32_e32 v14, v15, v14
	v_div_scale_f32 v15, vcc, 1.0, v12, 1.0
	v_mul_f32_e32 v32, v15, v14
	v_fma_f32 v33, -v9, v32, v15
	v_fmac_f32_e32 v32, v33, v14
	v_fma_f32 v9, -v9, v32, v15
	v_div_fmas_f32 v9, v9, v14, v32
	v_div_fixup_f32 v12, v9, v12, 1.0
	v_lshlrev_b32_e32 v32, 16, v157
	v_and_b32_e32 v33, 0xffff0000, v157
	v_pk_mul_f32 v[14:15], v[12:13], v[10:11]
	v_pk_fma_f32 v[10:11], v[12:13], v[10:11], v[32:33]
	s_nop 0
	v_cndmask_b32_e64 v9, v11, v15, s[0:1]
	v_cndmask_b32_e64 v10, v10, v14, s[0:1]
	v_cvt_pk_bf16_f32 v157, v10, v9
	v_lshlrev_b32_e32 v10, 16, v8
	v_and_b32_e32 v11, 0xffff0000, v8
	v_mul_f32_e32 v8, v236, v16
	v_mul_f32_e32 v9, v236, v17
	v_exp_f32_e32 v8, v8
	v_exp_f32_e32 v9, v9
	s_nop 0
	v_pk_add_f32 v[8:9], v[8:9], 1.0 op_sel_hi:[1,0]
	s_nop 0
	v_div_scale_f32 v12, s[34:35], v9, v9, 1.0
	v_rcp_f32_e32 v13, v12
	s_nop 0
	v_fma_f32 v14, -v12, v13, 1.0
	v_fmac_f32_e32 v13, v14, v13
	v_div_scale_f32 v14, vcc, 1.0, v9, 1.0
	v_mul_f32_e32 v15, v14, v13
	v_fma_f32 v16, -v12, v15, v14
	v_fmac_f32_e32 v15, v16, v13
	v_fma_f32 v12, -v12, v15, v14
	v_div_fmas_f32 v12, v12, v13, v15
	v_div_fixup_f32 v9, v12, v9, 1.0
	v_div_scale_f32 v12, s[34:35], v8, v8, 1.0
	v_rcp_f32_e32 v13, v12
	s_nop 0
	v_fma_f32 v14, -v12, v13, 1.0
	v_fmac_f32_e32 v13, v14, v13
	v_div_scale_f32 v14, vcc, 1.0, v8, 1.0
	v_mul_f32_e32 v15, v14, v13
	v_fma_f32 v16, -v12, v15, v14
	v_fmac_f32_e32 v15, v16, v13
	v_fma_f32 v12, -v12, v15, v14
	v_div_fmas_f32 v12, v12, v13, v15
	v_div_fixup_f32 v8, v12, v8, 1.0
	v_lshlrev_b32_e32 v14, 16, v154
	v_and_b32_e32 v15, 0xffff0000, v154
	v_pk_mul_f32 v[12:13], v[8:9], v[10:11]
	v_pk_fma_f32 v[8:9], v[8:9], v[10:11], v[14:15]
	s_nop 0
	v_cndmask_b32_e64 v9, v9, v13, s[0:1]
	v_cndmask_b32_e64 v8, v8, v12, s[0:1]
	v_cvt_pk_bf16_f32 v154, v8, v9
	v_lshlrev_b32_e32 v8, 16, v7
	v_and_b32_e32 v9, 0xffff0000, v7
	v_mul_f32_e32 v7, v236, v18
	v_exp_f32_e32 v10, v7
	v_mul_f32_e32 v7, v236, v19
	v_exp_f32_e32 v11, v7
	s_nop 0
	v_pk_add_f32 v[10:11], v[10:11], 1.0 op_sel_hi:[1,0]
	s_nop 0
	v_div_scale_f32 v7, s[34:35], v11, v11, 1.0
	v_rcp_f32_e32 v12, v7
	s_nop 0
	v_fma_f32 v13, -v7, v12, 1.0
	v_fmac_f32_e32 v12, v13, v12
	v_div_scale_f32 v13, vcc, 1.0, v11, 1.0
	v_mul_f32_e32 v14, v13, v12
	v_fma_f32 v15, -v7, v14, v13
	v_fmac_f32_e32 v14, v15, v12
	v_fma_f32 v7, -v7, v14, v13
	v_div_fmas_f32 v7, v7, v12, v14
	v_div_fixup_f32 v11, v7, v11, 1.0
	v_div_scale_f32 v7, s[34:35], v10, v10, 1.0
	v_rcp_f32_e32 v12, v7
	s_nop 0
	v_fma_f32 v13, -v7, v12, 1.0
	v_fmac_f32_e32 v12, v13, v12
	v_div_scale_f32 v13, vcc, 1.0, v10, 1.0
	v_mul_f32_e32 v14, v13, v12
	v_fma_f32 v15, -v7, v14, v13
	v_fmac_f32_e32 v14, v15, v12
	v_fma_f32 v7, -v7, v14, v13
	v_div_fmas_f32 v7, v7, v12, v14
	v_div_fixup_f32 v10, v7, v10, 1.0
	v_lshlrev_b32_e32 v14, 16, v155
	v_and_b32_e32 v15, 0xffff0000, v155
	v_pk_mul_f32 v[12:13], v[10:11], v[8:9]
	v_pk_fma_f32 v[8:9], v[10:11], v[8:9], v[14:15]
	s_nop 0
	v_cndmask_b32_e64 v7, v9, v13, s[0:1]
	v_cndmask_b32_e64 v8, v8, v12, s[0:1]
	v_cvt_pk_bf16_f32 v155, v8, v7
	v_lshlrev_b32_e32 v8, 16, v6
; DI unsigned pack2(float a, float b) { f2_t v = {a, b}; bf2_t r = __builtin_convertvector(v, bf2_t); return __builtin_bit_cast(unsigned, r); }
; __global__ void __launch_bounds__(512) mega(Params p) {
;     ...
; #pragma unroll
;           for (int fb = 0; fb < 4; ++fb)
; #pragma unroll
;             for (int i = 0; i < 8; ++i) {
;               const float b0 = __uint_as_float(bp[fb][i] << 16), b1 = __uint_as_float(bp[fb][i] & 0xffff0000u);
;               const float g0 = 1.f / (1.f + __builtin_amdgcn_exp2f(nr1 * acc[fb][2 * i]));
;               const float g1 = 1.f / (1.f + __builtin_amdgcn_exp2f(nr1 * acc[fb][2 * i + 1]));
;               float y0 = g0 * b0, y1 = g1 * b1;
;               if (n > 0) { y0 += __uint_as_float(yp[fb][i] << 16); y1 += __uint_as_float(yp[fb][i] & 0xffff0000u); }
;               yp[fb][i] = pack2(y0, y1);
	v_and_b32_e32 v9, 0xffff0000, v6
	v_mul_f32_e32 v6, v236, v20
	v_mul_f32_e32 v7, v236, v21
	v_exp_f32_e32 v6, v6
	v_exp_f32_e32 v7, v7
	s_nop 0
	v_pk_add_f32 v[6:7], v[6:7], 1.0 op_sel_hi:[1,0]
	s_nop 0
	v_div_scale_f32 v10, s[34:35], v7, v7, 1.0
	v_rcp_f32_e32 v11, v10
	s_nop 0
	v_fma_f32 v12, -v10, v11, 1.0
	v_fmac_f32_e32 v11, v12, v11
	v_div_scale_f32 v12, vcc, 1.0, v7, 1.0
	v_mul_f32_e32 v13, v12, v11
	v_fma_f32 v14, -v10, v13, v12
	v_fmac_f32_e32 v13, v14, v11
	v_fma_f32 v10, -v10, v13, v12
	v_div_fmas_f32 v10, v10, v11, v13
	v_div_fixup_f32 v7, v10, v7, 1.0
	v_div_scale_f32 v10, s[34:35], v6, v6, 1.0
	v_rcp_f32_e32 v11, v10
	s_nop 0
	v_fma_f32 v12, -v10, v11, 1.0
	v_fmac_f32_e32 v11, v12, v11
	v_div_scale_f32 v12, vcc, 1.0, v6, 1.0
	v_mul_f32_e32 v13, v12, v11
	v_fma_f32 v14, -v10, v13, v12
	v_fmac_f32_e32 v13, v14, v11
	v_fma_f32 v10, -v10, v13, v12
	v_div_fmas_f32 v10, v10, v11, v13
	v_div_fixup_f32 v6, v10, v6, 1.0
	v_lshlrev_b32_e32 v12, 16, v152
	v_and_b32_e32 v13, 0xffff0000, v152
	v_pk_mul_f32 v[10:11], v[6:7], v[8:9]
	v_pk_fma_f32 v[6:7], v[6:7], v[8:9], v[12:13]
	s_nop 0
	v_cndmask_b32_e64 v7, v7, v11, s[0:1]
	v_cndmask_b32_e64 v6, v6, v10, s[0:1]
	v_cvt_pk_bf16_f32 v152, v6, v7
	v_lshlrev_b32_e32 v6, 16, v5
	v_and_b32_e32 v7, 0xffff0000, v5
	v_mul_f32_e32 v5, v236, v22
	v_exp_f32_e32 v8, v5
	v_mul_f32_e32 v5, v236, v23
	v_exp_f32_e32 v9, v5
	s_nop 0
	v_pk_add_f32 v[8:9], v[8:9], 1.0 op_sel_hi:[1,0]
	s_nop 0
	v_div_scale_f32 v5, s[34:35], v9, v9, 1.0
	v_rcp_f32_e32 v10, v5
	s_nop 0
	v_fma_f32 v11, -v5, v10, 1.0
	v_fmac_f32_e32 v10, v11, v10
	v_div_scale_f32 v11, vcc, 1.0, v9, 1.0
	v_mul_f32_e32 v12, v11, v10
	v_fma_f32 v13, -v5, v12, v11
	v_fmac_f32_e32 v12, v13, v10
	v_fma_f32 v5, -v5, v12, v11
	v_div_fmas_f32 v5, v5, v10, v12
	v_div_fixup_f32 v9, v5, v9, 1.0
	v_div_scale_f32 v5, s[34:35], v8, v8, 1.0
	v_rcp_f32_e32 v10, v5
	s_nop 0
	v_fma_f32 v11, -v5, v10, 1.0
	v_fmac_f32_e32 v10, v11, v10
	v_div_scale_f32 v11, vcc, 1.0, v8, 1.0
	v_mul_f32_e32 v12, v11, v10
	v_fma_f32 v13, -v5, v12, v11
	v_fmac_f32_e32 v12, v13, v10
	v_fma_f32 v5, -v5, v12, v11
	v_div_fmas_f32 v5, v5, v10, v12
	v_div_fixup_f32 v8, v5, v8, 1.0
	v_lshlrev_b32_e32 v12, 16, v153
	v_and_b32_e32 v13, 0xffff0000, v153
	v_pk_mul_f32 v[10:11], v[8:9], v[6:7]
	v_pk_fma_f32 v[6:7], v[8:9], v[6:7], v[12:13]
	s_nop 0
	v_cndmask_b32_e64 v5, v7, v11, s[0:1]
	v_cndmask_b32_e64 v6, v6, v10, s[0:1]
	v_cvt_pk_bf16_f32 v153, v6, v5
	v_lshlrev_b32_e32 v6, 16, v4
	v_and_b32_e32 v7, 0xffff0000, v4
	v_mul_f32_e32 v4, v236, v24
	v_mul_f32_e32 v5, v236, v25
	v_exp_f32_e32 v4, v4
	v_exp_f32_e32 v5, v5
	s_nop 0
	v_pk_add_f32 v[4:5], v[4:5], 1.0 op_sel_hi:[1,0]
	s_nop 0
	v_div_scale_f32 v8, s[34:35], v5, v5, 1.0
	v_rcp_f32_e32 v9, v8
	s_nop 0
	v_fma_f32 v10, -v8, v9, 1.0
	v_fmac_f32_e32 v9, v10, v9
	v_div_scale_f32 v10, vcc, 1.0, v5, 1.0
	v_mul_f32_e32 v11, v10, v9
	v_fma_f32 v12, -v8, v11, v10
	v_fmac_f32_e32 v11, v12, v9
	v_fma_f32 v8, -v8, v11, v10
	v_div_fmas_f32 v8, v8, v9, v11
	v_div_fixup_f32 v5, v8, v5, 1.0
	v_div_scale_f32 v8, s[34:35], v4, v4, 1.0
	v_rcp_f32_e32 v9, v8
	s_nop 0
	v_fma_f32 v10, -v8, v9, 1.0
	v_fmac_f32_e32 v9, v10, v9
	v_div_scale_f32 v10, vcc, 1.0, v4, 1.0
	v_mul_f32_e32 v11, v10, v9
	v_fma_f32 v12, -v8, v11, v10
	v_fmac_f32_e32 v11, v12, v9
	v_fma_f32 v8, -v8, v11, v10
	v_div_fmas_f32 v8, v8, v9, v11
	v_div_fixup_f32 v4, v8, v4, 1.0
	v_lshlrev_b32_e32 v10, 16, v150
	v_and_b32_e32 v11, 0xffff0000, v150
	v_pk_mul_f32 v[8:9], v[4:5], v[6:7]
	v_pk_fma_f32 v[4:5], v[4:5], v[6:7], v[10:11]
	s_nop 0
	v_cndmask_b32_e64 v5, v5, v9, s[0:1]
	v_cndmask_b32_e64 v4, v4, v8, s[0:1]
	v_cvt_pk_bf16_f32 v150, v4, v5
	v_lshlrev_b32_e32 v4, 16, v3
	v_and_b32_e32 v5, 0xffff0000, v3
	v_mul_f32_e32 v3, v236, v26
	v_exp_f32_e32 v6, v3
	v_mul_f32_e32 v3, v236, v27
	v_exp_f32_e32 v7, v3
	s_nop 0
	v_pk_add_f32 v[6:7], v[6:7], 1.0 op_sel_hi:[1,0]
	s_nop 0
	v_div_scale_f32 v3, s[34:35], v7, v7, 1.0
	v_rcp_f32_e32 v8, v3
	s_nop 0
	v_fma_f32 v9, -v3, v8, 1.0
	v_fmac_f32_e32 v8, v9, v8
	v_div_scale_f32 v9, vcc, 1.0, v7, 1.0
	v_mul_f32_e32 v10, v9, v8
	v_fma_f32 v11, -v3, v10, v9
	v_fmac_f32_e32 v10, v11, v8
	v_fma_f32 v3, -v3, v10, v9
	v_div_fmas_f32 v3, v3, v8, v10
	v_div_fixup_f32 v7, v3, v7, 1.0
	v_div_scale_f32 v3, s[34:35], v6, v6, 1.0
	v_rcp_f32_e32 v8, v3
	s_nop 0
	v_fma_f32 v9, -v3, v8, 1.0
	v_fmac_f32_e32 v8, v9, v8
	v_div_scale_f32 v9, vcc, 1.0, v6, 1.0
	v_mul_f32_e32 v10, v9, v8
; DI int get_tid() { int t = threadIdx.x; asm volatile("" : "+v"(t)); return t; }
; DI unsigned pack2(float a, float b) { f2_t v = {a, b}; bf2_t r = __builtin_convertvector(v, bf2_t); return __builtin_bit_cast(unsigned, r); }
; template <int ROWS>
; DI void epi_flush(char* lds, u16* __restrict__ dst, size_t ld) {
;   const int tid = get_tid();
;   const int r0 = tid >> 5, ch = tid & 31;
;   __syncthreads();
; #pragma unroll 4
;   for (int r = r0; r < ROWS; r += 16) {
;     const u32x4 v = *(const u32x4*)(lds + r * EROW + ch * 16);
;     *(u32x4*)(dst + (size_t)r * ld + ch * 8) = v;
;   }
; __global__ void __launch_bounds__(512) mega(Params p) {
;     ...
; #pragma unroll
;           for (int fb = 0; fb < 4; ++fb)
; #pragma unroll
;             for (int i = 0; i < 8; ++i) {
;               const float b0 = __uint_as_float(bp[fb][i] << 16), b1 = __uint_as_float(bp[fb][i] & 0xffff0000u);
;               const float g0 = 1.f / (1.f + __builtin_amdgcn_exp2f(nr1 * acc[fb][2 * i]));
;               const float g1 = 1.f / (1.f + __builtin_amdgcn_exp2f(nr1 * acc[fb][2 * i + 1]));
;               float y0 = g0 * b0, y1 = g1 * b1;
;               if (n > 0) { y0 += __uint_as_float(yp[fb][i] << 16); y1 += __uint_as_float(yp[fb][i] & 0xffff0000u); }
;               yp[fb][i] = pack2(y0, y1);
;             }
;         }
;         __syncthreads();
; #pragma unroll
;         for (int fb = 0; fb < 4; ++fb)
; #pragma unroll
;           for (int jq = 0; jq < 4; ++jq)
;             *(uint2*)(lds + (wt * 32 + l32) * EROW + (wf * 128 + fb * 32 + 8 * jq + 4 * hh) * 2) = make_uint2(yp[fb][2 * jq], yp[fb][2 * jq + 1]);
;         epi_flush<128>(lds, (u16*)(ws + R_Y) + (size_t)tt * 128 * 1024 + ft * 256, 1024);
	v_fma_f32 v11, -v3, v10, v9
	v_fmac_f32_e32 v10, v11, v8
	v_fma_f32 v3, -v3, v10, v9
	v_div_fmas_f32 v3, v3, v8, v10
	v_div_fixup_f32 v6, v3, v6, 1.0
	v_lshlrev_b32_e32 v10, 16, v151
	v_and_b32_e32 v11, 0xffff0000, v151
	v_pk_mul_f32 v[8:9], v[6:7], v[4:5]
	v_pk_fma_f32 v[4:5], v[6:7], v[4:5], v[10:11]
	s_nop 0
	v_cndmask_b32_e64 v3, v5, v9, s[0:1]
	v_cndmask_b32_e64 v4, v4, v8, s[0:1]
	v_cvt_pk_bf16_f32 v151, v4, v3
	v_lshlrev_b32_e32 v4, 16, v2
	v_and_b32_e32 v5, 0xffff0000, v2
	v_mul_f32_e32 v2, v236, v28
	v_mul_f32_e32 v3, v236, v29
	v_exp_f32_e32 v2, v2
	v_exp_f32_e32 v3, v3
	s_nop 0
	v_pk_add_f32 v[2:3], v[2:3], 1.0 op_sel_hi:[1,0]
	s_nop 0
	v_div_scale_f32 v6, s[34:35], v3, v3, 1.0
	v_rcp_f32_e32 v7, v6
	s_nop 0
	v_fma_f32 v8, -v6, v7, 1.0
	v_fmac_f32_e32 v7, v8, v7
	v_div_scale_f32 v8, vcc, 1.0, v3, 1.0
	v_mul_f32_e32 v9, v8, v7
	v_fma_f32 v10, -v6, v9, v8
	v_fmac_f32_e32 v9, v10, v7
	v_fma_f32 v6, -v6, v9, v8
	v_div_fmas_f32 v6, v6, v7, v9
	v_div_fixup_f32 v3, v6, v3, 1.0
	v_div_scale_f32 v6, s[34:35], v2, v2, 1.0
	v_rcp_f32_e32 v7, v6
	s_nop 0
	v_fma_f32 v8, -v6, v7, 1.0
	v_fmac_f32_e32 v7, v8, v7
	v_div_scale_f32 v8, vcc, 1.0, v2, 1.0
	v_mul_f32_e32 v9, v8, v7
	v_fma_f32 v10, -v6, v9, v8
	v_fmac_f32_e32 v9, v10, v7
	v_fma_f32 v6, -v6, v9, v8
	v_div_fmas_f32 v6, v6, v7, v9
	v_div_fixup_f32 v2, v6, v2, 1.0
	v_lshlrev_b32_e32 v8, 16, v148
	v_and_b32_e32 v9, 0xffff0000, v148
	v_pk_mul_f32 v[6:7], v[2:3], v[4:5]
	v_pk_fma_f32 v[2:3], v[2:3], v[4:5], v[8:9]
	s_nop 0
	v_cndmask_b32_e64 v3, v3, v7, s[0:1]
	v_cndmask_b32_e64 v2, v2, v6, s[0:1]
	v_cvt_pk_bf16_f32 v148, v2, v3
	v_lshlrev_b32_e32 v2, 16, v0
	v_and_b32_e32 v3, 0xffff0000, v0
	v_mul_f32_e32 v0, v236, v30
	v_exp_f32_e32 v4, v0
	v_mul_f32_e32 v0, v236, v31
	v_exp_f32_e32 v5, v0
	s_nop 0
	v_pk_add_f32 v[4:5], v[4:5], 1.0 op_sel_hi:[1,0]
	s_nop 0
	v_div_scale_f32 v0, s[34:35], v5, v5, 1.0
	v_rcp_f32_e32 v6, v0
	s_nop 0
	v_fma_f32 v7, -v0, v6, 1.0
	v_fmac_f32_e32 v6, v7, v6
	v_div_scale_f32 v7, vcc, 1.0, v5, 1.0
	v_mul_f32_e32 v8, v7, v6
	v_fma_f32 v9, -v0, v8, v7
	v_fmac_f32_e32 v8, v9, v6
	v_fma_f32 v0, -v0, v8, v7
	v_div_fmas_f32 v0, v0, v6, v8
	v_div_fixup_f32 v5, v0, v5, 1.0
	v_div_scale_f32 v0, s[34:35], v4, v4, 1.0
	v_rcp_f32_e32 v6, v0
	s_nop 0
	v_fma_f32 v7, -v0, v6, 1.0
	v_fmac_f32_e32 v6, v7, v6
	v_div_scale_f32 v7, vcc, 1.0, v4, 1.0
	v_mul_f32_e32 v8, v7, v6
	v_fma_f32 v9, -v0, v8, v7
	v_fmac_f32_e32 v8, v9, v6
	v_fma_f32 v0, -v0, v8, v7
	v_div_fmas_f32 v0, v0, v6, v8
	v_div_fixup_f32 v4, v0, v4, 1.0
	v_lshlrev_b32_e32 v8, 16, v149
	v_and_b32_e32 v9, 0xffff0000, v149
	v_pk_mul_f32 v[6:7], v[4:5], v[2:3]
	v_pk_fma_f32 v[2:3], v[4:5], v[2:3], v[8:9]
	s_nop 0
	v_cndmask_b32_e64 v0, v3, v7, s[0:1]
	v_cndmask_b32_e64 v2, v2, v6, s[0:1]
	v_cvt_pk_bf16_f32 v149, v2, v0
	s_cbranch_scc0 .LBB0_25
	v_mov_b32_e32 v6, v145
	s_waitcnt vmcnt(0)
	s_barrier
	ds_write2_b64 v235, v[166:167], v[168:169] offset1:2
	ds_write2_b64 v235, v[170:171], v[172:173] offset0:4 offset1:6
	ds_write2_b64 v235, v[174:175], v[176:177] offset0:8 offset1:10
	ds_write2_b64 v235, v[178:179], v[164:165] offset0:12 offset1:14
	ds_write2_b64 v235, v[162:163], v[160:161] offset0:16 offset1:18
	ds_write2_b64 v235, v[158:159], v[156:157] offset0:20 offset1:22
	ds_write2_b64 v235, v[154:155], v[152:153] offset0:24 offset1:26
	ds_write2_b64 v235, v[150:151], v[148:149] offset0:28 offset1:30
	s_waitcnt lgkmcnt(0)
	v_ashrrev_i32_e32 v2, 5, v6
	v_cmp_gt_i32_e32 vcc, s70, v2
	s_barrier
	s_and_saveexec_b64 s[0:1], vcc
	s_cbranch_execz .LBB0_23
	v_max_i32_e32 v0, 0x70, v2
	v_sub_u32_e32 v0, v0, v2
	v_add_u32_e32 v0, 15, v0
	v_and_b32_e32 v4, 31, v6
	v_and_b32_e32 v3, 48, v0
	s_and_b32 s33, s52, 0xe0
	v_lshlrev_b32_e32 v12, 4, v4
	v_cmp_ne_u32_e32 vcc, 48, v3
	s_and_saveexec_b64 s[8:9], vcc
	s_cbranch_execz .LBB0_55
	v_lshrrev_b32_e32 v3, 4, v0
	s_add_i32 s34, s33, s57
	v_add_u32_e32 v3, 1, v3
	s_add_i32 s34, s34, s58
	v_and_b32_e32 v7, 3, v3
	s_ashr_i32 s35, s34, 31
	v_ashrrev_i32_e32 v3, 31, v2
	s_lshl_b64 s[34:35], s[34:35], 18
	v_lshlrev_b64 v[8:9], 11, v[2:3]
	v_lshl_add_u64 v[8:9], s[34:35], 0, v[8:9]
	s_lshl_b64 s[34:35], s[54:55], 1
	s_add_u32 s34, s10, s34
	v_lshl_or_b32 v8, v4, 4, v8
	s_addc_u32 s35, s11, s35
	v_lshl_add_u64 v[4:5], s[34:35], 0, v[8:9]
	s_movk_i32 s34, 0x210
	v_mul_lo_u32 v3, v2, s34
	v_add3_u32 v3, v3, v12, 0
	v_sub_u32_e32 v7, 0, v7
	s_mov_b64 s[34:35], 0
	s_mov_b64 s[64:65], 0x8000

; DI unsigned pack2(float a, float b) { f2_t v = {a, b}; bf2_t r = __builtin_convertvector(v, bf2_t); return __builtin_bit_cast(unsigned, r); }
; DI f32x16 mfma(bf16x8 a, bf16x8 b, f32x16 c) { return __builtin_amdgcn_mfma_f32_32x32x16_bf16(a, b, c, 0, 0, 0); }
; template <int DQK, int DV, bool BIAS>
; DI void attn_tile(const char* cur, const bf16x8* qf, f32x16* o, float& m, float& lsum, int kt, int l32, int hh,
;                   const int* __restrict__ posb, int qpos, int qmin, const int* __restrict__ kpmax, const float* lut) {
;     ...
;       const float sh = m - cb;
;       float rs = 0.f;
; #pragma unroll
;       for (int i = 0; i < 16; ++i) { s0[i] = __builtin_amdgcn_exp2f(s0[i] - sh); rs += s0[i]; }
; #pragma unroll
;       for (int i = 0; i < 16; ++i) { s1[i] = __builtin_amdgcn_exp2f(s1[i] - sh); rs += s1[i]; }
;       lsum += rs;
;       bf16x8 pf[4];
; #pragma unroll
;       for (int ks = 0; ks < 4; ++ks) {
;         const f32x16& sv = (ks < 2) ? s0 : s1;
;         const int b0 = (ks & 1) * 8;
;         uint4 u;
;         u.x = pack2(sv[b0 + 0], sv[b0 + 1]); u.y = pack2(sv[b0 + 2], sv[b0 + 3]);
;         u.z = pack2(sv[b0 + 4], sv[b0 + 5]); u.w = pack2(sv[b0 + 6], sv[b0 + 7]);
;         pf[ks] = __builtin_bit_cast(bf16x8, u);
;       }
; #pragma unroll
;       for (int vb = 0; vb < DV / 32; ++vb)
; #pragma unroll
;         for (int ks = 0; ks < 4; ++ks) {
;           const bf16x8 a = *(const bf16x8*)(cur + KB + (vb * 32 + l32) * VROW + ks * 32 + hh * 16);
;           o[vb] = mfma(a, pf[ks], o[vb]);
;         }
.LBB0_76:
	v_sub_f32_e32 v50, v50, v130
	v_exp_f32_e32 v50, v50
	v_sub_f32_e32 v51, v51, v130
	v_exp_f32_e32 v51, v51
	v_sub_f32_e32 v52, v52, v130
	v_exp_f32_e32 v52, v52
	v_sub_f32_e32 v53, v53, v130
	v_exp_f32_e32 v53, v53
	v_sub_f32_e32 v54, v54, v130
	v_add_f32_e32 v131, 0, v50
	v_exp_f32_e32 v54, v54
	v_sub_f32_e32 v55, v55, v130
	v_add_f32_e32 v131, v51, v131
	v_exp_f32_e32 v55, v55
	v_sub_f32_e32 v56, v56, v130
	v_add_f32_e32 v131, v52, v131
	v_exp_f32_e32 v56, v56
	v_sub_f32_e32 v57, v57, v130
	v_add_f32_e32 v131, v53, v131
	v_exp_f32_e32 v57, v57
	v_sub_f32_e32 v58, v58, v130
	v_add_f32_e32 v131, v54, v131
	v_exp_f32_e32 v58, v58
	v_sub_f32_e32 v59, v59, v130
	v_add_f32_e32 v131, v55, v131
	v_exp_f32_e32 v59, v59
	v_sub_f32_e32 v60, v60, v130
	v_add_f32_e32 v131, v56, v131
	v_exp_f32_e32 v60, v60
	v_sub_f32_e32 v61, v61, v130
	v_add_f32_e32 v131, v57, v131
	v_exp_f32_e32 v61, v61
	v_sub_f32_e32 v62, v62, v130
	v_add_f32_e32 v131, v58, v131
	v_exp_f32_e32 v62, v62
	v_sub_f32_e32 v63, v63, v130
	v_add_f32_e32 v131, v59, v131
	v_exp_f32_e32 v63, v63
	v_sub_f32_e32 v64, v64, v130
	v_add_f32_e32 v131, v60, v131
	v_exp_f32_e32 v64, v64
	v_sub_f32_e32 v65, v65, v130
	v_add_f32_e32 v131, v61, v131
	v_exp_f32_e32 v65, v65
	v_sub_f32_e32 v34, v34, v130
	v_add_f32_e32 v131, v62, v131
	v_exp_f32_e32 v34, v34
	v_sub_f32_e32 v35, v35, v130
	v_add_f32_e32 v131, v63, v131
	v_exp_f32_e32 v35, v35
	v_sub_f32_e32 v36, v36, v130
	v_add_f32_e32 v131, v64, v131
	v_exp_f32_e32 v36, v36
	v_sub_f32_e32 v37, v37, v130
	v_add_f32_e32 v131, v65, v131
	v_exp_f32_e32 v37, v37
	v_sub_f32_e32 v38, v38, v130
	v_add_f32_e32 v131, v34, v131
	v_exp_f32_e32 v132, v38
	v_add_f32_e32 v131, v35, v131
	v_add_f32_e32 v131, v36, v131
	v_add_f32_e32 v131, v37, v131
	v_sub_f32_e32 v39, v39, v130
	v_add_f32_e32 v38, v132, v131
	v_exp_f32_e32 v131, v39
	v_sub_f32_e32 v39, v40, v130
	v_exp_f32_e32 v133, v39
	v_sub_f32_e32 v39, v41, v130
	v_exp_f32_e32 v41, v39
	v_sub_f32_e32 v39, v42, v130
	v_exp_f32_e32 v134, v39
	v_sub_f32_e32 v39, v43, v130
	v_exp_f32_e32 v135, v39
	v_sub_f32_e32 v39, v44, v130
	v_exp_f32_e32 v136, v39
	v_sub_f32_e32 v39, v45, v130
	v_exp_f32_e32 v137, v39
	v_sub_f32_e32 v39, v46, v130
	v_exp_f32_e32 v138, v39
	v_sub_f32_e32 v39, v47, v130
	v_exp_f32_e32 v139, v39
	v_sub_f32_e32 v39, v48, v130
	v_cvt_pk_bf16_f32 v42, v58, v59
	v_exp_f32_e32 v140, v39
	v_sub_f32_e32 v39, v49, v130
	v_cvt_pk_bf16_f32 v46, v50, v51
	v_cvt_pk_bf16_f32 v47, v52, v53
	v_cvt_pk_bf16_f32 v48, v54, v55
	v_cvt_pk_bf16_f32 v49, v56, v57
	s_waitcnt lgkmcnt(0)
	s_nop 1
	v_mfma_f32_32x32x16_bf16 v[18:33], v[148:151], v[46:49], v[18:33]
	v_mfma_f32_32x32x16_bf16 v[2:17], v[164:167], v[46:49], v[2:17]
	v_add_f32_e32 v38, v131, v38
	v_add_f32_e32 v38, v133, v38
	v_add_f32_e32 v38, v41, v38
	v_add_f32_e32 v38, v134, v38
	v_cvt_pk_bf16_f32 v43, v60, v61
	v_cvt_pk_bf16_f32 v44, v62, v63
	v_cvt_pk_bf16_f32 v45, v64, v65
	v_add_f32_e32 v38, v135, v38
	s_nop 0
	v_mfma_f32_32x32x16_bf16 v[18:33], v[152:155], v[42:45], v[18:33]
	v_mfma_f32_32x32x16_bf16 v[2:17], v[168:171], v[42:45], v[2:17]
	v_add_f32_e32 v38, v136, v38
	v_add_f32_e32 v38, v137, v38
	v_exp_f32_e32 v141, v39
	v_add_f32_e32 v38, v138, v38
	v_add_f32_e32 v38, v139, v38
	v_add_f32_e32 v38, v140, v38
	v_add_f32_e32 v38, v141, v38
	v_add_f32_e32 v129, v129, v38
	v_cvt_pk_bf16_f32 v38, v34, v35
	v_cvt_pk_bf16_f32 v39, v36, v37
	v_cvt_pk_bf16_f32 v40, v132, v131
	v_cvt_pk_bf16_f32 v41, v133, v41
	v_cvt_pk_bf16_f32 v34, v134, v135
	v_cvt_pk_bf16_f32 v35, v136, v137
	s_nop 0
	v_mfma_f32_32x32x16_bf16 v[18:33], v[156:159], v[38:41], v[18:33]
	v_mfma_f32_32x32x16_bf16 v[2:17], v[172:175], v[38:41], v[2:17]
	v_cvt_pk_bf16_f32 v36, v138, v139
	v_cvt_pk_bf16_f32 v37, v140, v141
	s_nop 1
	v_mfma_f32_32x32x16_bf16 v[18:33], v[160:163], v[34:37], v[18:33]
	v_mfma_f32_32x32x16_bf16 v[2:17], v[176:179], v[34:37], v[2:17]

; DI float xmax32(float v) { const auto r = __builtin_amdgcn_permlane32_swap(__float_as_uint(v), __float_as_uint(v), false, false); return fmaxf(__uint_as_float(r[0]), __uint_as_float(r[1])); }
; DI f32x16 mfma(bf16x8 a, bf16x8 b, f32x16 c) { return __builtin_amdgcn_mfma_f32_32x32x16_bf16(a, b, c, 0, 0, 0); }
; template <int DQK, int DV, bool BIAS>
; DI void attn_tile(const char* cur, const bf16x8* qf, f32x16* o, float& m, float& lsum, int kt, int l32, int hh,
;                   const int* __restrict__ posb, int qpos, int qmin, const int* __restrict__ kpmax, const float* lut) {
;     ...
;       for (int st = 0; st < DQK / 16; ++st) {
;         const bf16x8 a0 = *(const bf16x8*)(cur + l32 * KROW + st * 32 + hh * 16);
;         const bf16x8 a1 = *(const bf16x8*)(cur + (32 + l32) * KROW + st * 32 + hh * 16);
;         s0 = mfma(a0, qf[st], s0);
;         s1 = mfma(a1, qf[st], s1);
;       }
;       float cb = 0.f;
;       if (BIAS) {
;         const int kmx = kpmax[kt];
;         if (kmx - qmin <= -128) {
;           cb = lut[0];
;         } else {
; #pragma unroll
;           for (int j = 0; j < 4; ++j) {
;             const int4 k0 = *(const int4*)(posb + kt * 64 + 8 * j + 4 * hh);
;             const int4 k1 = *(const int4*)(posb + kt * 64 + 32 + 8 * j + 4 * hh);
;             const int ka[4] = {k0.x, k0.y, k0.z, k0.w}, kb[4] = {k1.x, k1.y, k1.z, k1.w};
; #pragma unroll
;             for (int r = 0; r < 4; ++r) {
;               s0[4 * j + r] += lut[min(max(ka[r] - qpos, -128), 128) + 128];
;               s1[4 * j + r] += lut[min(max(kb[r] - qpos, -128), 128) + 128];
;             }
;           }
;         }
;       }
;       float mx = s0[0];
; #pragma unroll
;       for (int i = 1; i < 16; ++i) mx = fmaxf(mx, s0[i]);
; #pragma unroll
;       for (int i = 0; i < 16; ++i) mx = fmaxf(mx, s1[i]);
;       mx = xmax32(mx) + cb;
;       if (__any(mx > m + 8.f)) {
;         const float mnew = fmaxf(m, mx);
;         const float alpha = __builtin_amdgcn_exp2f(m - mnew);
;         m = mnew;
;         lsum *= alpha;
; #pragma unroll
;         for (int vb = 0; vb < DV / 32; ++vb)
; #pragma unroll
;           for (int i = 0; i < 16; ++i) o[vb][i] *= alpha;
;       }
.LBB0_78:
	s_or_b32 s8, s59, s36
	v_cmp_lt_i32_e32 vcc, s8, v115
	s_and_saveexec_b64 s[52:53], vcc
	s_cbranch_execz .LBB0_77
	s_mul_i32 s8, s59, 0x5800
	s_add_i32 s8, s47, s8
	v_add3_u32 v131, s8, v126, v127
	v_add3_u32 v142, s8, v127, v128
	ds_read_b128 v[34:37], v131
	ds_read_b128 v[38:41], v131 offset:32
	ds_read_b128 v[42:45], v131 offset:64
	ds_read_b128 v[46:49], v131 offset:96
	ds_read_b128 v[132:135], v131 offset:128
	ds_read_b128 v[136:139], v131 offset:160
	ds_read_b128 v[234:237], v131 offset:6656
	ds_read_b128 v[238:241], v131 offset:6688
	ds_read_b128 v[242:245], v131 offset:6720
	s_waitcnt lgkmcnt(8)
	v_mfma_f32_32x32x16_bf16 v[50:65], v[34:37], v[82:85], 0
	ds_read_b128 v[246:249], v131 offset:6752
	ds_read_b128 v[250:253], v131 offset:6784
	ds_read_b128 v[190:193], v131 offset:6816
	s_waitcnt lgkmcnt(10)
	v_mfma_f32_32x32x16_bf16 v[50:65], v[38:41], v[66:69], v[50:65]
	s_waitcnt lgkmcnt(9)
	v_mfma_f32_32x32x16_bf16 v[50:65], v[42:45], v[70:73], v[50:65]
	s_waitcnt lgkmcnt(8)
	v_mfma_f32_32x32x16_bf16 v[50:65], v[46:49], v[74:77], v[50:65]
	s_waitcnt lgkmcnt(7)
	v_mfma_f32_32x32x16_bf16 v[50:65], v[132:135], v[78:81], v[50:65]
	s_waitcnt lgkmcnt(6)
	v_mfma_f32_32x32x16_bf16 v[50:65], v[136:139], v[86:89], v[50:65]
	ds_read_b128 v[148:151], v142 offset:13312
	ds_read_b128 v[152:155], v142 offset:13344
	ds_read_b128 v[156:159], v142 offset:13376
	ds_read_b128 v[160:163], v142 offset:13408
	ds_read_b128 v[164:167], v142 offset:17920
	ds_read_b128 v[168:171], v142 offset:17952
	ds_read_b128 v[172:175], v142 offset:17984
	ds_read_b128 v[176:179], v142 offset:18016
	s_waitcnt lgkmcnt(13)
	v_mfma_f32_32x32x16_bf16 v[34:49], v[234:237], v[82:85], 0
	s_waitcnt lgkmcnt(12)
	v_mfma_f32_32x32x16_bf16 v[34:49], v[238:241], v[66:69], v[34:49]
	s_waitcnt lgkmcnt(11)
	v_mfma_f32_32x32x16_bf16 v[34:49], v[242:245], v[70:73], v[34:49]
	s_waitcnt lgkmcnt(10)
	v_mfma_f32_32x32x16_bf16 v[34:49], v[246:249], v[74:77], v[34:49]
	v_max_f32_e32 v140, v50, v50
	v_max_f32_e32 v131, v51, v51
	v_max_f32_e32 v131, v140, v131
	v_max3_f32 v131, v131, v52, v53
	s_waitcnt lgkmcnt(9)
	v_mfma_f32_32x32x16_bf16 v[34:49], v[250:253], v[78:81], v[34:49]
	v_max3_f32 v131, v131, v54, v55
	v_max3_f32 v131, v131, v56, v57
	v_max3_f32 v131, v131, v58, v59
	v_max3_f32 v131, v131, v60, v61
	s_waitcnt lgkmcnt(8)
	v_mfma_f32_32x32x16_bf16 v[34:49], v[190:193], v[86:89], v[34:49]
	v_max3_f32 v131, v131, v62, v63
	v_max3_f32 v131, v131, v64, v65
	s_nop 9
	v_max3_f32 v131, v131, v34, v35
	v_max3_f32 v131, v131, v36, v37
	v_max3_f32 v131, v131, v38, v39
	v_max3_f32 v131, v131, v40, v41
	v_max3_f32 v131, v131, v42, v43
	v_max3_f32 v131, v131, v44, v45
	v_max3_f32 v131, v131, v46, v47
	v_max3_f32 v131, v131, v48, v49
	v_mov_b32_e32 v132, v131
	s_nop 1
	v_permlane32_swap_b32_e32 v131, v132
	v_max_f32_e32 v132, v132, v132
	v_max_f32_e32 v131, v131, v131
	v_max_f32_e32 v131, v131, v132
	v_add_f32_e32 v132, 0x41000000, v130
	v_cmp_gt_f32_e32 vcc, v131, v132
	s_cbranch_vccz .LBB0_76
	v_add_f32_e32 v131, 0, v131
	v_max_f32_e32 v132, v130, v130
	v_max_f32_e32 v131, v132, v131
	v_sub_f32_e32 v130, v130, v131
	v_exp_f32_e32 v130, v130
	s_nop 0
	v_mul_f32_e32 v129, v129, v130
	v_pk_mul_f32 v[16:17], v[16:17], v[130:131] op_sel_hi:[1,0]
	v_pk_mul_f32 v[14:15], v[14:15], v[130:131] op_sel_hi:[1,0]
	v_pk_mul_f32 v[12:13], v[12:13], v[130:131] op_sel_hi:[1,0]
	v_pk_mul_f32 v[10:11], v[10:11], v[130:131] op_sel_hi:[1,0]
	v_pk_mul_f32 v[8:9], v[8:9], v[130:131] op_sel_hi:[1,0]
	v_pk_mul_f32 v[6:7], v[6:7], v[130:131] op_sel_hi:[1,0]
	v_pk_mul_f32 v[4:5], v[4:5], v[130:131] op_sel_hi:[1,0]
	v_pk_mul_f32 v[2:3], v[2:3], v[130:131] op_sel_hi:[1,0]
	v_pk_mul_f32 v[32:33], v[32:33], v[130:131] op_sel_hi:[1,0]
	v_pk_mul_f32 v[30:31], v[30:31], v[130:131] op_sel_hi:[1,0]
	v_pk_mul_f32 v[28:29], v[28:29], v[130:131] op_sel_hi:[1,0]
	v_pk_mul_f32 v[26:27], v[26:27], v[130:131] op_sel_hi:[1,0]
	v_pk_mul_f32 v[24:25], v[24:25], v[130:131] op_sel_hi:[1,0]
	v_pk_mul_f32 v[22:23], v[22:23], v[130:131] op_sel_hi:[1,0]
	v_pk_mul_f32 v[20:21], v[20:21], v[130:131] op_sel_hi:[1,0]
	v_pk_mul_f32 v[18:19], v[18:19], v[130:131] op_sel_hi:[1,0]
	v_mov_b32_e32 v130, v131
	s_branch .LBB0_76
